# k-inner chains, snake accumulator order, alternate chains issue k1 before k0 so every adjacent MFMA pair shares an operand or the accumulator; no mid setprio flip
# baseline (speedup 1.0000x reference)
; #define PG8_STAGE(bufoff, gbase, voff) do { _Pragma("unroll") for (int _i = 0; _i < 2; ++_i) \
;         __builtin_amdgcn_global_load_lds((const unsigned*)((const char*)(gbase) + (voff)[_i]), (PG8_LAS unsigned*)(lds + (bufoff) + ldsw + _i * 8192), 16, 0, 0); } while (0)
; #define PG8_LDA(dst, b, h) do { _Pragma("unroll") for (int m = 0; m < 4; ++m) _Pragma("unroll") for (int k = 0; k < 2; ++k) dst[m][k] = *(const PG8_LAS bf16x8*)(lds + PG8_SA(b, h) + aoff + m * 2048 + k * 1024); } while (0)
; #define PG8_MMA(ai, bj, At, Bt) do { __builtin_amdgcn_s_setprio(3); _Pragma("unroll") for (int m = 0; m < 4; ++m) _Pragma("unroll") for (int n = 0; n < 2; ++n) _Pragma("unroll") for (int k = 0; k < 2; ++k) \
;         acc[ai][bj][m][n] = __builtin_amdgcn_mfma_f32_16x16x32_bf16(Bt[n][k], At[m][k], acc[ai][bj][m][n], 0, 0, 0); __builtin_amdgcn_s_setprio(0); } while (0)
; #define PG8_WAIT_V(n) asm volatile("s_waitcnt vmcnt(" #n ")" ::: "memory")
; #define PG8_WAIT_L(n) asm volatile("s_waitcnt lgkmcnt(" #n ")" ::: "memory")
; #define PG8_BAR __builtin_amdgcn_s_barrier()
; #define PG8_SCHED __builtin_amdgcn_sched_barrier(0)
; template <class Epi, class Sched, bool ALIGN_EPI = false, bool SP2 = false>
; __device__ __forceinline__ void gemm_phase(PG8_LAS unsigned char* lds, const Gemm g, const Sched& S, const Epi& E) {
;     ...
;             PG8_WAIT_V(8); PG8_WAIT_L(0); PG8_BAR; PG8_MMA(0, 0, At, B0); PG8_MMA(0, 1, At, B1); PG8_BAR; PG8_SCHED;
;             PG8_LDA(At, 0, 1); PG8_STAGE(PG8_SB(0, 0), b2, voffB); PG8_STAGE(PG8_SB(0, 1), b2 + hstepB, voffB); PG8_STAGE(PG8_SA(0, 0), a2, voffA);
.Lengw1_e:
	s_waitcnt lgkmcnt(0)
	s_barrier
	s_setprio 3
	s_waitcnt lgkmcnt(0)
	v_mfma_f32_16x16x32_bf16 v[126:129], v[130:133], v[192:195], v[126:129]
	v_mfma_f32_16x16x32_bf16 v[126:129], v[134:137], v[196:199], v[126:129]
	v_mfma_f32_16x16x32_bf16 v[118:121], v[172:175], v[196:199], v[118:121]
	v_mfma_f32_16x16x32_bf16 v[118:121], v[156:159], v[192:195], v[118:121]
	v_mfma_f32_16x16x32_bf16 v[102:105], v[156:159], v[200:203], v[102:105]
	v_mfma_f32_16x16x32_bf16 v[102:105], v[172:175], v[204:207], v[102:105]
	v_mfma_f32_16x16x32_bf16 v[110:113], v[134:137], v[204:207], v[110:113]
	v_mfma_f32_16x16x32_bf16 v[110:113], v[130:133], v[200:203], v[110:113]
	v_mfma_f32_16x16x32_bf16 v[94:97], v[130:133], v[208:211], v[94:97]
	v_mfma_f32_16x16x32_bf16 v[94:97], v[134:137], v[212:215], v[94:97]
	v_mfma_f32_16x16x32_bf16 v[86:89], v[172:175], v[212:215], v[86:89]
	v_mfma_f32_16x16x32_bf16 v[86:89], v[156:159], v[208:211], v[86:89]
	v_mfma_f32_16x16x32_bf16 v[70:73], v[156:159], v[216:219], v[70:73]
	v_mfma_f32_16x16x32_bf16 v[70:73], v[172:175], v[220:223], v[70:73]
	v_mfma_f32_16x16x32_bf16 v[78:81], v[134:137], v[220:223], v[78:81]
	v_mfma_f32_16x16x32_bf16 v[78:81], v[130:133], v[216:219], v[78:81]
	v_mfma_f32_16x16x32_bf16 v[122:125], v[176:179], v[192:195], v[122:125]
	v_mfma_f32_16x16x32_bf16 v[122:125], v[180:183], v[196:199], v[122:125]
	v_mfma_f32_16x16x32_bf16 v[114:117], v[188:191], v[196:199], v[114:117]
	v_mfma_f32_16x16x32_bf16 v[114:117], v[184:187], v[192:195], v[114:117]
	v_mfma_f32_16x16x32_bf16 v[98:101], v[184:187], v[200:203], v[98:101]
	v_mfma_f32_16x16x32_bf16 v[98:101], v[188:191], v[204:207], v[98:101]
	v_mfma_f32_16x16x32_bf16 v[106:109], v[180:183], v[204:207], v[106:109]
	v_mfma_f32_16x16x32_bf16 v[106:109], v[176:179], v[200:203], v[106:109]
	v_mfma_f32_16x16x32_bf16 v[90:93], v[176:179], v[208:211], v[90:93]
	v_mfma_f32_16x16x32_bf16 v[90:93], v[180:183], v[212:215], v[90:93]
	v_mfma_f32_16x16x32_bf16 v[82:85], v[188:191], v[212:215], v[82:85]
	v_mfma_f32_16x16x32_bf16 v[82:85], v[184:187], v[208:211], v[82:85]
	v_mfma_f32_16x16x32_bf16 v[66:69], v[184:187], v[216:219], v[66:69]
	v_mfma_f32_16x16x32_bf16 v[66:69], v[188:191], v[220:223], v[66:69]
	v_mfma_f32_16x16x32_bf16 v[74:77], v[180:183], v[220:223], v[74:77]
	v_mfma_f32_16x16x32_bf16 v[74:77], v[176:179], v[216:219], v[74:77]
	s_setprio 0
	s_barrier
	s_add_i32 s56, s83, s66
	v_lshl_add_u64 v[160:161], s[8:9], 0, v[140:141]
	s_mov_b32 m0, s56
	ds_read_b128 v[192:195], v169 offset:16384
	ds_read_b128 v[196:199], v169 offset:17408
	ds_read_b128 v[200:203], v169 offset:18432
	ds_read_b128 v[204:207], v169 offset:19456
	ds_read_b128 v[208:211], v169 offset:20480
	ds_read_b128 v[212:215], v169 offset:21504
	ds_read_b128 v[216:219], v169 offset:22528
	ds_read_b128 v[220:223], v169 offset:23552
	global_load_lds_dwordx4 v[160:161], off
	s_add_i32 m0, s56, 0x2000
	s_add_u32 s56, s8, 0x100000
	v_lshl_add_u64 v[224:225], s[8:9], 0, v[144:145]
	s_addc_u32 s57, s9, 0
	s_add_i32 s58, s89, s66
	global_load_lds_dwordx4 v[224:225], off
	v_lshl_add_u64 v[226:227], s[56:57], 0, v[140:141]
	s_mov_b32 m0, s58
	v_lshl_add_u64 v[228:229], s[36:37], 0, v[142:143]
	global_load_lds_dwordx4 v[226:227], off
	v_lshl_add_u64 v[226:227], s[56:57], 0, v[144:145]
	s_add_i32 m0, s58, 0x2000
	s_nop 0
	global_load_lds_dwordx4 v[226:227], off
	v_lshl_add_u64 v[226:227], s[36:37], 0, v[138:139]
	s_mov_b32 m0, s55
	s_nop 0
	global_load_lds_dwordx4 v[226:227], off
	s_mov_b32 m0, s67
	s_nop 0
	global_load_lds_dwordx4 v[228:229], off
	s_cmp_eq_u32 s97, 0
	s_cbranch_scc1 .Lengw2_a
	s_cmp_eq_u32 s97, 2
	s_cbranch_scc1 .Lengw2_b
	s_cmp_eq_u32 s97, 4
	s_cbranch_scc1 .Lengw2_c
	s_waitcnt vmcnt(16)
	s_branch .Lengw2_e

; #define PG8_STAGE(bufoff, gbase, voff) do { _Pragma("unroll") for (int _i = 0; _i < 2; ++_i) \
;         __builtin_amdgcn_global_load_lds((const unsigned*)((const char*)(gbase) + (voff)[_i]), (PG8_LAS unsigned*)(lds + (bufoff) + ldsw + _i * 8192), 16, 0, 0); } while (0)
; #define PG8_LDA(dst, b, h) do { _Pragma("unroll") for (int m = 0; m < 4; ++m) _Pragma("unroll") for (int k = 0; k < 2; ++k) dst[m][k] = *(const PG8_LAS bf16x8*)(lds + PG8_SA(b, h) + aoff + m * 2048 + k * 1024); } while (0)
; #define PG8_LDB(dst, b, h) do { _Pragma("unroll") for (int n = 0; n < 2; ++n) _Pragma("unroll") for (int k = 0; k < 2; ++k) dst[n][k] = *(const PG8_LAS bf16x8*)(lds + PG8_SB(b, h) + boff + n * 2048 + k * 1024); } while (0)
; #define PG8_MMA(ai, bj, At, Bt) do { __builtin_amdgcn_s_setprio(3); _Pragma("unroll") for (int m = 0; m < 4; ++m) _Pragma("unroll") for (int n = 0; n < 2; ++n) _Pragma("unroll") for (int k = 0; k < 2; ++k) \
;         acc[ai][bj][m][n] = __builtin_amdgcn_mfma_f32_16x16x32_bf16(Bt[n][k], At[m][k], acc[ai][bj][m][n], 0, 0, 0); __builtin_amdgcn_s_setprio(0); } while (0)
; #define PG8_WAIT_V(n) asm volatile("s_waitcnt vmcnt(" #n ")" ::: "memory")
; #define PG8_WAIT_L(n) asm volatile("s_waitcnt lgkmcnt(" #n ")" ::: "memory")
; #define PG8_BAR __builtin_amdgcn_s_barrier()
; #define PG8_SCHED __builtin_amdgcn_sched_barrier(0)
; template <class Epi, class Sched, bool ALIGN_EPI = false, bool SP2 = false>
; __device__ __forceinline__ void gemm_phase(PG8_LAS unsigned char* lds, const Gemm g, const Sched& S, const Epi& E) {
;     ...
;             PG8_WAIT_V(8); PG8_WAIT_L(0); PG8_BAR; PG8_MMA(1, 0, At, B0); PG8_MMA(1, 1, At, B1); PG8_BAR; PG8_SCHED;
;             PG8_LDB(B0, 1, 0); PG8_LDB(B1, 1, 1); PG8_SCHED; PG8_LDA(At, 1, 0); PG8_STAGE(PG8_SA(0, 1), a2 + hstepA, voffA);
.Lengw2_e:
	s_waitcnt lgkmcnt(0)
	s_barrier
	s_setprio 3
	s_waitcnt lgkmcnt(0)
	v_mfma_f32_16x16x32_bf16 v[62:65], v[130:133], v[192:195], v[62:65]
	v_mfma_f32_16x16x32_bf16 v[62:65], v[134:137], v[196:199], v[62:65]
	v_mfma_f32_16x16x32_bf16 v[54:57], v[172:175], v[196:199], v[54:57]
	v_mfma_f32_16x16x32_bf16 v[54:57], v[156:159], v[192:195], v[54:57]
	v_mfma_f32_16x16x32_bf16 v[38:41], v[156:159], v[200:203], v[38:41]
	v_mfma_f32_16x16x32_bf16 v[38:41], v[172:175], v[204:207], v[38:41]
	v_mfma_f32_16x16x32_bf16 v[46:49], v[134:137], v[204:207], v[46:49]
	v_mfma_f32_16x16x32_bf16 v[46:49], v[130:133], v[200:203], v[46:49]
	v_mfma_f32_16x16x32_bf16 v[30:33], v[130:133], v[208:211], v[30:33]
	v_mfma_f32_16x16x32_bf16 v[30:33], v[134:137], v[212:215], v[30:33]
	v_mfma_f32_16x16x32_bf16 v[22:25], v[172:175], v[212:215], v[22:25]
	v_mfma_f32_16x16x32_bf16 v[22:25], v[156:159], v[208:211], v[22:25]
	v_mfma_f32_16x16x32_bf16 v[6:9], v[156:159], v[216:219], v[6:9]
	v_mfma_f32_16x16x32_bf16 v[6:9], v[172:175], v[220:223], v[6:9]
	v_mfma_f32_16x16x32_bf16 v[14:17], v[134:137], v[220:223], v[14:17]
	v_mfma_f32_16x16x32_bf16 v[14:17], v[130:133], v[216:219], v[14:17]
	v_mfma_f32_16x16x32_bf16 v[58:61], v[176:179], v[192:195], v[58:61]
	v_mfma_f32_16x16x32_bf16 v[58:61], v[180:183], v[196:199], v[58:61]
	v_mfma_f32_16x16x32_bf16 v[50:53], v[188:191], v[196:199], v[50:53]
	v_mfma_f32_16x16x32_bf16 v[50:53], v[184:187], v[192:195], v[50:53]
	v_mfma_f32_16x16x32_bf16 v[34:37], v[184:187], v[200:203], v[34:37]
	v_mfma_f32_16x16x32_bf16 v[34:37], v[188:191], v[204:207], v[34:37]
	v_mfma_f32_16x16x32_bf16 v[42:45], v[180:183], v[204:207], v[42:45]
	v_mfma_f32_16x16x32_bf16 v[42:45], v[176:179], v[200:203], v[42:45]
	v_mfma_f32_16x16x32_bf16 v[26:29], v[176:179], v[208:211], v[26:29]
	v_mfma_f32_16x16x32_bf16 v[26:29], v[180:183], v[212:215], v[26:29]
	v_mfma_f32_16x16x32_bf16 v[18:21], v[188:191], v[212:215], v[18:21]
	v_mfma_f32_16x16x32_bf16 v[18:21], v[184:187], v[208:211], v[18:21]
	v_mfma_f32_16x16x32_bf16 v[2:5], v[184:187], v[216:219], v[2:5]
	v_mfma_f32_16x16x32_bf16 v[2:5], v[188:191], v[220:223], v[2:5]
	v_mfma_f32_16x16x32_bf16 v[10:13], v[180:183], v[220:223], v[10:13]
	v_mfma_f32_16x16x32_bf16 v[10:13], v[176:179], v[216:219], v[10:13]
	s_setprio 0
	s_barrier
	s_add_i32 s56, 0, 0x18000
	v_add_u32_e32 v146, s56, v164
	s_add_i32 s57, 0, 0x1c000
	ds_read_b128 v[130:133], v146
	ds_read_b128 v[134:137], v146 offset:1024
	ds_read_b128 v[156:159], v146 offset:2048
	ds_read_b128 v[172:175], v146 offset:3072
	v_add_u32_e32 v146, s57, v164
	ds_read_b128 v[176:179], v146
	ds_read_b128 v[180:183], v146 offset:1024
	ds_read_b128 v[184:187], v146 offset:2048
	ds_read_b128 v[188:191], v146 offset:3072
	s_add_u32 s36, s36, 0x100000
	s_addc_u32 s37, s37, 0
	s_mov_b32 m0, s72
	v_lshl_add_u64 v[230:231], s[36:37], 0, v[138:139]
	ds_read_b128 v[192:195], v169 offset:32768
	ds_read_b128 v[196:199], v169 offset:33792
	ds_read_b128 v[200:203], v169 offset:34816
	ds_read_b128 v[204:207], v169 offset:35840
	ds_read_b128 v[208:211], v169 offset:36864
	ds_read_b128 v[212:215], v169 offset:37888
	ds_read_b128 v[216:219], v169 offset:38912
	ds_read_b128 v[220:223], v169 offset:39936
	global_load_lds_dwordx4 v[230:231], off
	v_lshl_add_u64 v[230:231], s[36:37], 0, v[142:143]
	s_mov_b32 m0, s73
	s_nop 0
	global_load_lds_dwordx4 v[230:231], off
	s_cmp_eq_u32 s97, 4
	s_cbranch_scc1 .Lengw3_c
	s_cmp_eq_u32 s97, 8
	s_cbranch_scc1 .Lengw3_d
	s_waitcnt vmcnt(8)
	s_branch .Lengw3_e

; #define PG8_STAGE(bufoff, gbase, voff) do { _Pragma("unroll") for (int _i = 0; _i < 2; ++_i) \
;         __builtin_amdgcn_global_load_lds((const unsigned*)((const char*)(gbase) + (voff)[_i]), (PG8_LAS unsigned*)(lds + (bufoff) + ldsw + _i * 8192), 16, 0, 0); } while (0)
; #define PG8_LDA(dst, b, h) do { _Pragma("unroll") for (int m = 0; m < 4; ++m) _Pragma("unroll") for (int k = 0; k < 2; ++k) dst[m][k] = *(const PG8_LAS bf16x8*)(lds + PG8_SA(b, h) + aoff + m * 2048 + k * 1024); } while (0)
; #define PG8_MMA(ai, bj, At, Bt) do { __builtin_amdgcn_s_setprio(3); _Pragma("unroll") for (int m = 0; m < 4; ++m) _Pragma("unroll") for (int n = 0; n < 2; ++n) _Pragma("unroll") for (int k = 0; k < 2; ++k) \
;         acc[ai][bj][m][n] = __builtin_amdgcn_mfma_f32_16x16x32_bf16(Bt[n][k], At[m][k], acc[ai][bj][m][n], 0, 0, 0); __builtin_amdgcn_s_setprio(0); } while (0)
; #define PG8_WAIT_V(n) asm volatile("s_waitcnt vmcnt(" #n ")" ::: "memory")
; #define PG8_WAIT_L(n) asm volatile("s_waitcnt lgkmcnt(" #n ")" ::: "memory")
; #define PG8_BAR __builtin_amdgcn_s_barrier()
; #define PG8_SCHED __builtin_amdgcn_sched_barrier(0)
; template <class Epi, class Sched, bool ALIGN_EPI = false, bool SP2 = false>
; __device__ __forceinline__ void gemm_phase(PG8_LAS unsigned char* lds, const Gemm g, const Sched& S, const Epi& E) {
;     ...
;             PG8_WAIT_V(8); PG8_WAIT_L(0); PG8_BAR; PG8_MMA(0, 0, At, B0); PG8_MMA(0, 1, At, B1); PG8_BAR; PG8_SCHED;
;             PG8_LDA(At, 1, 1); PG8_STAGE(PG8_SB(1, 0), b3, voffB); PG8_STAGE(PG8_SB(1, 1), b3 + hstepB, voffB); PG8_STAGE(PG8_SA(1, 0), a3, voffA);
;             PG8_WAIT_V(8); PG8_WAIT_L(0); PG8_BAR; PG8_MMA(1, 0, At, B0); PG8_MMA(1, 1, At, B1); PG8_BAR; PG8_SCHED;
;     __device__ __forceinline__ void operator()(const f32x4 (&acc)[2][2][4][2], const Unit& u, int wr, int wc, int fr, int fq) const {
;         const int row0 = u.pm * BM + wr * 64 + fr; const int cls = u.pn >> 3;
;         if (u.pn >= 40) {
.Lengw3_e:
	s_waitcnt lgkmcnt(0)
	s_barrier
	s_setprio 3
	s_waitcnt lgkmcnt(0)
	v_mfma_f32_16x16x32_bf16 v[126:129], v[130:133], v[192:195], v[126:129]
	v_mfma_f32_16x16x32_bf16 v[126:129], v[134:137], v[196:199], v[126:129]
	v_mfma_f32_16x16x32_bf16 v[118:121], v[172:175], v[196:199], v[118:121]
	v_mfma_f32_16x16x32_bf16 v[118:121], v[156:159], v[192:195], v[118:121]
	v_mfma_f32_16x16x32_bf16 v[102:105], v[156:159], v[200:203], v[102:105]
	v_mfma_f32_16x16x32_bf16 v[102:105], v[172:175], v[204:207], v[102:105]
	v_mfma_f32_16x16x32_bf16 v[110:113], v[134:137], v[204:207], v[110:113]
	v_mfma_f32_16x16x32_bf16 v[110:113], v[130:133], v[200:203], v[110:113]
	v_mfma_f32_16x16x32_bf16 v[94:97], v[130:133], v[208:211], v[94:97]
	v_mfma_f32_16x16x32_bf16 v[94:97], v[134:137], v[212:215], v[94:97]
	v_mfma_f32_16x16x32_bf16 v[86:89], v[172:175], v[212:215], v[86:89]
	v_mfma_f32_16x16x32_bf16 v[86:89], v[156:159], v[208:211], v[86:89]
	v_mfma_f32_16x16x32_bf16 v[70:73], v[156:159], v[216:219], v[70:73]
	v_mfma_f32_16x16x32_bf16 v[70:73], v[172:175], v[220:223], v[70:73]
	v_mfma_f32_16x16x32_bf16 v[78:81], v[134:137], v[220:223], v[78:81]
	v_mfma_f32_16x16x32_bf16 v[78:81], v[130:133], v[216:219], v[78:81]
	v_mfma_f32_16x16x32_bf16 v[122:125], v[176:179], v[192:195], v[122:125]
	v_mfma_f32_16x16x32_bf16 v[122:125], v[180:183], v[196:199], v[122:125]
	v_mfma_f32_16x16x32_bf16 v[114:117], v[188:191], v[196:199], v[114:117]
	v_mfma_f32_16x16x32_bf16 v[114:117], v[184:187], v[192:195], v[114:117]
	v_mfma_f32_16x16x32_bf16 v[98:101], v[184:187], v[200:203], v[98:101]
	v_mfma_f32_16x16x32_bf16 v[98:101], v[188:191], v[204:207], v[98:101]
	v_mfma_f32_16x16x32_bf16 v[106:109], v[180:183], v[204:207], v[106:109]
	v_mfma_f32_16x16x32_bf16 v[106:109], v[176:179], v[200:203], v[106:109]
	v_mfma_f32_16x16x32_bf16 v[90:93], v[176:179], v[208:211], v[90:93]
	v_mfma_f32_16x16x32_bf16 v[90:93], v[180:183], v[212:215], v[90:93]
	v_mfma_f32_16x16x32_bf16 v[82:85], v[188:191], v[212:215], v[82:85]
	v_mfma_f32_16x16x32_bf16 v[82:85], v[184:187], v[208:211], v[82:85]
	v_mfma_f32_16x16x32_bf16 v[66:69], v[184:187], v[216:219], v[66:69]
	v_mfma_f32_16x16x32_bf16 v[66:69], v[188:191], v[220:223], v[66:69]
	v_mfma_f32_16x16x32_bf16 v[74:77], v[180:183], v[220:223], v[74:77]
	v_mfma_f32_16x16x32_bf16 v[74:77], v[176:179], v[216:219], v[74:77]
	s_setprio 0
	s_barrier
	s_add_i32 s36, s56, s66
	v_lshl_add_u64 v[160:161], v[160:161], 0, s[18:19]
	s_mov_b32 m0, s36
	ds_read_b128 v[192:195], v169 offset:49152
	ds_read_b128 v[196:199], v169 offset:50176
	ds_read_b128 v[200:203], v169 offset:51200
	ds_read_b128 v[204:207], v169 offset:52224
	ds_read_b128 v[208:211], v169 offset:53248
	ds_read_b128 v[212:215], v169 offset:54272
	ds_read_b128 v[216:219], v169 offset:55296
	ds_read_b128 v[220:223], v169 offset:56320
	global_load_lds_dwordx4 v[160:161], off
	s_add_i32 m0, s36, 0x2000
	s_add_u32 s8, s8, 0x100080
	v_lshl_add_u64 v[160:161], v[224:225], 0, s[18:19]
	s_addc_u32 s9, s9, 0
	s_add_i32 s36, s57, s66
	global_load_lds_dwordx4 v[160:161], off
	v_lshl_add_u64 v[160:161], s[8:9], 0, v[140:141]
	s_mov_b32 m0, s36
	s_nop 0
	global_load_lds_dwordx4 v[160:161], off
	v_lshl_add_u64 v[160:161], s[8:9], 0, v[144:145]
	s_add_i32 m0, s36, 0x2000
	s_nop 0
	global_load_lds_dwordx4 v[160:161], off
	v_lshl_add_u64 v[160:161], v[226:227], 0, s[18:19]
	s_mov_b32 m0, s75
	s_nop 0
	global_load_lds_dwordx4 v[160:161], off
	v_lshl_add_u64 v[160:161], v[228:229], 0, s[18:19]
	s_mov_b32 m0, s76
	s_nop 0
	global_load_lds_dwordx4 v[160:161], off
	s_waitcnt vmcnt(8)
	s_waitcnt lgkmcnt(0)
	s_barrier
	s_setprio 3
	s_waitcnt lgkmcnt(0)
	v_mfma_f32_16x16x32_bf16 v[62:65], v[130:133], v[192:195], v[62:65]
	v_mfma_f32_16x16x32_bf16 v[62:65], v[134:137], v[196:199], v[62:65]
	v_mfma_f32_16x16x32_bf16 v[54:57], v[172:175], v[196:199], v[54:57]
	v_mfma_f32_16x16x32_bf16 v[54:57], v[156:159], v[192:195], v[54:57]
	v_mfma_f32_16x16x32_bf16 v[38:41], v[156:159], v[200:203], v[38:41]
	v_mfma_f32_16x16x32_bf16 v[38:41], v[172:175], v[204:207], v[38:41]
	v_mfma_f32_16x16x32_bf16 v[46:49], v[134:137], v[204:207], v[46:49]
	v_mfma_f32_16x16x32_bf16 v[46:49], v[130:133], v[200:203], v[46:49]
	v_mfma_f32_16x16x32_bf16 v[30:33], v[130:133], v[208:211], v[30:33]
	v_mfma_f32_16x16x32_bf16 v[30:33], v[134:137], v[212:215], v[30:33]
	v_mfma_f32_16x16x32_bf16 v[22:25], v[172:175], v[212:215], v[22:25]
	v_mfma_f32_16x16x32_bf16 v[22:25], v[156:159], v[208:211], v[22:25]
	v_mfma_f32_16x16x32_bf16 v[6:9], v[156:159], v[216:219], v[6:9]
	v_mfma_f32_16x16x32_bf16 v[6:9], v[172:175], v[220:223], v[6:9]
	v_mfma_f32_16x16x32_bf16 v[14:17], v[134:137], v[220:223], v[14:17]
	v_mfma_f32_16x16x32_bf16 v[14:17], v[130:133], v[216:219], v[14:17]
	v_mfma_f32_16x16x32_bf16 v[58:61], v[176:179], v[192:195], v[58:61]
	v_mfma_f32_16x16x32_bf16 v[58:61], v[180:183], v[196:199], v[58:61]
	v_mfma_f32_16x16x32_bf16 v[50:53], v[188:191], v[196:199], v[50:53]
	v_mfma_f32_16x16x32_bf16 v[50:53], v[184:187], v[192:195], v[50:53]
	v_mfma_f32_16x16x32_bf16 v[34:37], v[184:187], v[200:203], v[34:37]
	v_mfma_f32_16x16x32_bf16 v[34:37], v[188:191], v[204:207], v[34:37]
	v_mfma_f32_16x16x32_bf16 v[42:45], v[180:183], v[204:207], v[42:45]
	v_mfma_f32_16x16x32_bf16 v[42:45], v[176:179], v[200:203], v[42:45]
	v_mfma_f32_16x16x32_bf16 v[26:29], v[176:179], v[208:211], v[26:29]
	v_mfma_f32_16x16x32_bf16 v[26:29], v[180:183], v[212:215], v[26:29]
	v_mfma_f32_16x16x32_bf16 v[18:21], v[188:191], v[212:215], v[18:21]
	v_mfma_f32_16x16x32_bf16 v[18:21], v[184:187], v[208:211], v[18:21]
	v_mfma_f32_16x16x32_bf16 v[2:5], v[184:187], v[216:219], v[2:5]
	v_mfma_f32_16x16x32_bf16 v[2:5], v[188:191], v[220:223], v[2:5]
	v_mfma_f32_16x16x32_bf16 v[10:13], v[180:183], v[220:223], v[10:13]
	v_mfma_f32_16x16x32_bf16 v[10:13], v[176:179], v[216:219], v[10:13]
	s_setprio 0
	s_barrier
	s_add_i32 s45, s45, 2
	s_add_u32 s6, s6, 0x100
	s_addc_u32 s7, s7, 0
	s_add_u32 s33, s33, 0x100
	s_addc_u32 s44, s44, 0
	s_cmp_gt_u32 s45, 61
	s_cbranch_scc0 .LBB0_143
	s_and_b64 vcc, exec, s[20:21]
	s_cbranch_vccz .LBB0_148
	s_barrier
	v_lshl_add_u32 v156, s0, 8, v163
	s_cmp_lt_i32 s54, 40
	s_mov_b64 s[0:1], -1
	s_cbranch_scc1 .LBB0_149

; #define PG8_STAGE(bufoff, gbase, voff) do { _Pragma("unroll") for (int _i = 0; _i < 2; ++_i) \
;         __builtin_amdgcn_global_load_lds((const unsigned*)((const char*)(gbase) + (voff)[_i]), (PG8_LAS unsigned*)(lds + (bufoff) + ldsw + _i * 8192), 16, 0, 0); } while (0)
; #define PG8_LDA(dst, b, h) do { _Pragma("unroll") for (int m = 0; m < 4; ++m) _Pragma("unroll") for (int k = 0; k < 2; ++k) dst[m][k] = *(const PG8_LAS bf16x8*)(lds + PG8_SA(b, h) + aoff + m * 2048 + k * 1024); } while (0)
; #define PG8_LDB(dst, b, h) do { _Pragma("unroll") for (int n = 0; n < 2; ++n) _Pragma("unroll") for (int k = 0; k < 2; ++k) dst[n][k] = *(const PG8_LAS bf16x8*)(lds + PG8_SB(b, h) + boff + n * 2048 + k * 1024); } while (0)
; #define PG8_MMA(ai, bj, At, Bt) do { __builtin_amdgcn_s_setprio(3); _Pragma("unroll") for (int m = 0; m < 4; ++m) _Pragma("unroll") for (int n = 0; n < 2; ++n) _Pragma("unroll") for (int k = 0; k < 2; ++k) \
;         acc[ai][bj][m][n] = __builtin_amdgcn_mfma_f32_16x16x32_bf16(Bt[n][k], At[m][k], acc[ai][bj][m][n], 0, 0, 0); __builtin_amdgcn_s_setprio(0); } while (0)
; #define PG8_WAIT_V(n) asm volatile("s_waitcnt vmcnt(" #n ")" ::: "memory")
; #define PG8_WAIT_L(n) asm volatile("s_waitcnt lgkmcnt(" #n ")" ::: "memory")
; #define PG8_BAR __builtin_amdgcn_s_barrier()
; #define PG8_SCHED __builtin_amdgcn_sched_barrier(0)
; template <class Epi, class Sched, bool ALIGN_EPI = false, bool SP2 = false>
; __device__ __forceinline__ void gemm_phase(PG8_LAS unsigned char* lds, const Gemm g, const Sched& S, const Epi& E) {
;     ...
;             PG8_LDB(B0, 0, 0); PG8_LDB(B1, 0, 1); PG8_SCHED; PG8_LDA(At, 0, 0); PG8_STAGE(PG8_SA(1, 1), a1 + hstepA, voffA);
;             PG8_WAIT_V(8); PG8_WAIT_L(0); PG8_BAR; PG8_MMA(0, 0, At, B0); PG8_MMA(0, 1, At, B1); PG8_BAR; PG8_SCHED;
;             PG8_LDA(At, 0, 1); PG8_STAGE(PG8_SB(0, 0), b2, voffB); PG8_STAGE(PG8_SB(0, 1), b2 + hstepB, voffB); PG8_STAGE(PG8_SA(0, 0), a2, voffA);
.LBB0_478:
	ds_read_b128 v[130:133], v170
	ds_read_b128 v[134:137], v170 offset:1024
	ds_read_b128 v[138:141], v170 offset:2048
	ds_read_b128 v[142:145], v170 offset:3072
	ds_read_b128 v[164:167], v171
	ds_read_b128 v[174:177], v171 offset:1024
	ds_read_b128 v[178:181], v171 offset:2048
	ds_read_b128 v[182:185], v171 offset:3072
	s_add_u32 s36, s6, 0xfff80080
	s_addc_u32 s37, s7, -1
	s_cmp_eq_u32 s79, 4
	s_cselect_b32 s59, s27, s37
	s_cselect_b32 s58, s26, s36
	s_cselect_b32 s37, s23, s78
	s_cselect_b32 s36, s25, s77
	v_lshl_add_u64 v[218:219], s[6:7], 0, v[154:155]
	s_add_i32 m0, s31, 0xc000
	ds_read_b128 v[186:189], v172
	ds_read_b128 v[190:193], v172 offset:1024
	ds_read_b128 v[194:197], v172 offset:2048
	ds_read_b128 v[198:201], v172 offset:3072
	ds_read_b128 v[202:205], v172 offset:4096
	ds_read_b128 v[206:209], v172 offset:5120
	ds_read_b128 v[210:213], v172 offset:6144
	ds_read_b128 v[214:217], v172 offset:7168
	global_load_lds_dwordx4 v[218:219], off
	v_lshl_add_u64 v[218:219], s[6:7], 0, v[156:157]
	s_add_i32 m0, s31, 0xe000
	s_nop 0
	global_load_lds_dwordx4 v[218:219], off
	s_waitcnt vmcnt(8)
	s_waitcnt lgkmcnt(0)
	s_barrier
	s_setprio 3
	s_waitcnt lgkmcnt(0)
	v_mfma_f32_16x16x32_bf16 v[126:129], v[130:133], v[186:189], v[126:129]
	v_mfma_f32_16x16x32_bf16 v[126:129], v[134:137], v[190:193], v[126:129]
	v_mfma_f32_16x16x32_bf16 v[122:125], v[142:145], v[190:193], v[122:125]
	v_mfma_f32_16x16x32_bf16 v[122:125], v[138:141], v[186:189], v[122:125]
	v_mfma_f32_16x16x32_bf16 v[114:117], v[138:141], v[194:197], v[114:117]
	v_mfma_f32_16x16x32_bf16 v[114:117], v[142:145], v[198:201], v[114:117]
	v_mfma_f32_16x16x32_bf16 v[118:121], v[134:137], v[198:201], v[118:121]
	v_mfma_f32_16x16x32_bf16 v[118:121], v[130:133], v[194:197], v[118:121]
	v_mfma_f32_16x16x32_bf16 v[110:113], v[130:133], v[202:205], v[110:113]
	v_mfma_f32_16x16x32_bf16 v[110:113], v[134:137], v[206:209], v[110:113]
	v_mfma_f32_16x16x32_bf16 v[102:105], v[142:145], v[206:209], v[102:105]
	v_mfma_f32_16x16x32_bf16 v[102:105], v[138:141], v[202:205], v[102:105]
	v_mfma_f32_16x16x32_bf16 v[74:77], v[138:141], v[210:213], v[74:77]
	v_mfma_f32_16x16x32_bf16 v[74:77], v[142:145], v[214:217], v[74:77]
	v_mfma_f32_16x16x32_bf16 v[78:81], v[134:137], v[214:217], v[78:81]
	v_mfma_f32_16x16x32_bf16 v[78:81], v[130:133], v[210:213], v[78:81]
	v_mfma_f32_16x16x32_bf16 v[106:109], v[164:167], v[186:189], v[106:109]
	v_mfma_f32_16x16x32_bf16 v[106:109], v[174:177], v[190:193], v[106:109]
	v_mfma_f32_16x16x32_bf16 v[98:101], v[182:185], v[190:193], v[98:101]
	v_mfma_f32_16x16x32_bf16 v[98:101], v[178:181], v[186:189], v[98:101]
	v_mfma_f32_16x16x32_bf16 v[90:93], v[178:181], v[194:197], v[90:93]
	v_mfma_f32_16x16x32_bf16 v[90:93], v[182:185], v[198:201], v[90:93]
	v_mfma_f32_16x16x32_bf16 v[94:97], v[174:177], v[198:201], v[94:97]
	v_mfma_f32_16x16x32_bf16 v[94:97], v[164:167], v[194:197], v[94:97]
	v_mfma_f32_16x16x32_bf16 v[86:89], v[164:167], v[202:205], v[86:89]
	v_mfma_f32_16x16x32_bf16 v[86:89], v[174:177], v[206:209], v[86:89]
	v_mfma_f32_16x16x32_bf16 v[82:85], v[182:185], v[206:209], v[82:85]
	v_mfma_f32_16x16x32_bf16 v[82:85], v[178:181], v[202:205], v[82:85]
	v_mfma_f32_16x16x32_bf16 v[66:69], v[178:181], v[210:213], v[66:69]
	v_mfma_f32_16x16x32_bf16 v[66:69], v[182:185], v[214:217], v[66:69]
	v_mfma_f32_16x16x32_bf16 v[70:73], v[174:177], v[214:217], v[70:73]
	v_mfma_f32_16x16x32_bf16 v[70:73], v[164:167], v[210:213], v[70:73]
	s_setprio 0
	s_barrier
	s_add_i32 s83, s72, s44
	v_lshl_add_u64 v[218:219], s[36:37], 0, v[148:149]
	s_mov_b32 m0, s83
	ds_read_b128 v[186:189], v172 offset:16384
	ds_read_b128 v[190:193], v172 offset:17408
	ds_read_b128 v[194:197], v172 offset:18432
	ds_read_b128 v[198:201], v172 offset:19456
	ds_read_b128 v[202:205], v172 offset:20480
	ds_read_b128 v[206:209], v172 offset:21504
	ds_read_b128 v[210:213], v172 offset:22528
	ds_read_b128 v[214:217], v172 offset:23552
	global_load_lds_dwordx4 v[218:219], off
	s_add_i32 m0, s83, 0x2000
	s_add_u32 s84, s36, 0x20000
	v_lshl_add_u64 v[220:221], s[36:37], 0, v[152:153]
	s_addc_u32 s85, s37, 0
	s_add_i32 s83, s73, s44
	global_load_lds_dwordx4 v[220:221], off
	v_lshl_add_u64 v[222:223], s[84:85], 0, v[148:149]
	s_mov_b32 m0, s83
	v_lshl_add_u64 v[224:225], s[58:59], 0, v[150:151]
	global_load_lds_dwordx4 v[222:223], off
	v_lshl_add_u64 v[222:223], s[84:85], 0, v[152:153]
	s_add_i32 m0, s83, 0x2000
	s_nop 0
	global_load_lds_dwordx4 v[222:223], off
	v_lshl_add_u64 v[222:223], s[58:59], 0, v[146:147]
	s_mov_b32 m0, s31
	s_nop 0
	global_load_lds_dwordx4 v[222:223], off
	s_mov_b32 m0, s45
	s_nop 0
	global_load_lds_dwordx4 v[224:225], off
	s_waitcnt vmcnt(8)
	s_waitcnt lgkmcnt(0)
	s_barrier
; #define PG8_STAGE(bufoff, gbase, voff) do { _Pragma("unroll") for (int _i = 0; _i < 2; ++_i) \
;         __builtin_amdgcn_global_load_lds((const unsigned*)((const char*)(gbase) + (voff)[_i]), (PG8_LAS unsigned*)(lds + (bufoff) + ldsw + _i * 8192), 16, 0, 0); } while (0)
; #define PG8_LDA(dst, b, h) do { _Pragma("unroll") for (int m = 0; m < 4; ++m) _Pragma("unroll") for (int k = 0; k < 2; ++k) dst[m][k] = *(const PG8_LAS bf16x8*)(lds + PG8_SA(b, h) + aoff + m * 2048 + k * 1024); } while (0)
; #define PG8_LDB(dst, b, h) do { _Pragma("unroll") for (int n = 0; n < 2; ++n) _Pragma("unroll") for (int k = 0; k < 2; ++k) dst[n][k] = *(const PG8_LAS bf16x8*)(lds + PG8_SB(b, h) + boff + n * 2048 + k * 1024); } while (0)
; #define PG8_MMA(ai, bj, At, Bt) do { __builtin_amdgcn_s_setprio(3); _Pragma("unroll") for (int m = 0; m < 4; ++m) _Pragma("unroll") for (int n = 0; n < 2; ++n) _Pragma("unroll") for (int k = 0; k < 2; ++k) \
;         acc[ai][bj][m][n] = __builtin_amdgcn_mfma_f32_16x16x32_bf16(Bt[n][k], At[m][k], acc[ai][bj][m][n], 0, 0, 0); __builtin_amdgcn_s_setprio(0); } while (0)
; #define PG8_WAIT_V(n) asm volatile("s_waitcnt vmcnt(" #n ")" ::: "memory")
; #define PG8_WAIT_L(n) asm volatile("s_waitcnt lgkmcnt(" #n ")" ::: "memory")
; #define PG8_BAR __builtin_amdgcn_s_barrier()
; #define PG8_SCHED __builtin_amdgcn_sched_barrier(0)
; template <class Epi, class Sched, bool ALIGN_EPI = false, bool SP2 = false>
; __device__ __forceinline__ void gemm_phase(PG8_LAS unsigned char* lds, const Gemm g, const Sched& S, const Epi& E) {
;     ...
;             PG8_WAIT_V(8); PG8_WAIT_L(0); PG8_BAR; PG8_MMA(1, 0, At, B0); PG8_MMA(1, 1, At, B1); PG8_BAR; PG8_SCHED;
;             PG8_LDB(B0, 1, 0); PG8_LDB(B1, 1, 1); PG8_SCHED; PG8_LDA(At, 1, 0); PG8_STAGE(PG8_SA(0, 1), a2 + hstepA, voffA);
;             PG8_WAIT_V(8); PG8_WAIT_L(0); PG8_BAR; PG8_MMA(0, 0, At, B0); PG8_MMA(0, 1, At, B1); PG8_BAR; PG8_SCHED;
	s_setprio 3
	s_waitcnt lgkmcnt(0)
	v_mfma_f32_16x16x32_bf16 v[62:65], v[130:133], v[186:189], v[62:65]
	v_mfma_f32_16x16x32_bf16 v[62:65], v[134:137], v[190:193], v[62:65]
	v_mfma_f32_16x16x32_bf16 v[58:61], v[142:145], v[190:193], v[58:61]
	v_mfma_f32_16x16x32_bf16 v[58:61], v[138:141], v[186:189], v[58:61]
	v_mfma_f32_16x16x32_bf16 v[46:49], v[138:141], v[194:197], v[46:49]
	v_mfma_f32_16x16x32_bf16 v[46:49], v[142:145], v[198:201], v[46:49]
	v_mfma_f32_16x16x32_bf16 v[54:57], v[134:137], v[198:201], v[54:57]
	v_mfma_f32_16x16x32_bf16 v[54:57], v[130:133], v[194:197], v[54:57]
	v_mfma_f32_16x16x32_bf16 v[38:41], v[130:133], v[202:205], v[38:41]
	v_mfma_f32_16x16x32_bf16 v[38:41], v[134:137], v[206:209], v[38:41]
	v_mfma_f32_16x16x32_bf16 v[30:33], v[142:145], v[206:209], v[30:33]
	v_mfma_f32_16x16x32_bf16 v[30:33], v[138:141], v[202:205], v[30:33]
	v_mfma_f32_16x16x32_bf16 v[14:17], v[138:141], v[210:213], v[14:17]
	v_mfma_f32_16x16x32_bf16 v[14:17], v[142:145], v[214:217], v[14:17]
	v_mfma_f32_16x16x32_bf16 v[22:25], v[134:137], v[214:217], v[22:25]
	v_mfma_f32_16x16x32_bf16 v[22:25], v[130:133], v[210:213], v[22:25]
	v_mfma_f32_16x16x32_bf16 v[50:53], v[164:167], v[186:189], v[50:53]
	v_mfma_f32_16x16x32_bf16 v[50:53], v[174:177], v[190:193], v[50:53]
	v_mfma_f32_16x16x32_bf16 v[42:45], v[182:185], v[190:193], v[42:45]
	v_mfma_f32_16x16x32_bf16 v[42:45], v[178:181], v[186:189], v[42:45]
	v_mfma_f32_16x16x32_bf16 v[26:29], v[178:181], v[194:197], v[26:29]
	v_mfma_f32_16x16x32_bf16 v[26:29], v[182:185], v[198:201], v[26:29]
	v_mfma_f32_16x16x32_bf16 v[34:37], v[174:177], v[198:201], v[34:37]
	v_mfma_f32_16x16x32_bf16 v[34:37], v[164:167], v[194:197], v[34:37]
	v_mfma_f32_16x16x32_bf16 v[18:21], v[164:167], v[202:205], v[18:21]
	v_mfma_f32_16x16x32_bf16 v[18:21], v[174:177], v[206:209], v[18:21]
	v_mfma_f32_16x16x32_bf16 v[10:13], v[182:185], v[206:209], v[10:13]
	v_mfma_f32_16x16x32_bf16 v[10:13], v[178:181], v[202:205], v[10:13]
	v_mfma_f32_16x16x32_bf16 v[2:5], v[178:181], v[210:213], v[2:5]
	v_mfma_f32_16x16x32_bf16 v[2:5], v[182:185], v[214:217], v[2:5]
	v_mfma_f32_16x16x32_bf16 v[6:9], v[174:177], v[214:217], v[6:9]
	v_mfma_f32_16x16x32_bf16 v[6:9], v[164:167], v[210:213], v[6:9]
	s_setprio 0
	s_barrier
	s_add_i32 s83, 0, 0x18000
	s_add_i32 s84, 0, 0x1c000
	v_add_u32_e32 v142, s83, v168
	v_add_u32_e32 v173, s84, v168
	ds_read_b128 v[130:133], v142
	ds_read_b128 v[134:137], v142 offset:1024
	ds_read_b128 v[138:141], v142 offset:2048
	ds_read_b128 v[142:145], v142 offset:3072
	ds_read_b128 v[164:167], v173
	ds_read_b128 v[174:177], v173 offset:1024
	ds_read_b128 v[178:181], v173 offset:2048
	ds_read_b128 v[182:185], v173 offset:3072
	s_add_u32 s58, s58, 0x80000
	s_addc_u32 s59, s59, 0
	s_mov_b32 m0, s54
	v_lshl_add_u64 v[226:227], s[58:59], 0, v[146:147]
	ds_read_b128 v[186:189], v172 offset:32768
	ds_read_b128 v[190:193], v172 offset:33792
	ds_read_b128 v[194:197], v172 offset:34816
	ds_read_b128 v[198:201], v172 offset:35840
	ds_read_b128 v[202:205], v172 offset:36864
	ds_read_b128 v[206:209], v172 offset:37888
	ds_read_b128 v[210:213], v172 offset:38912
	ds_read_b128 v[214:217], v172 offset:39936
	global_load_lds_dwordx4 v[226:227], off
	v_lshl_add_u64 v[226:227], s[58:59], 0, v[150:151]
	s_mov_b32 m0, s55
	s_nop 0
	global_load_lds_dwordx4 v[226:227], off
	s_waitcnt vmcnt(8)
	s_waitcnt lgkmcnt(0)
	s_barrier
	s_setprio 3
	s_waitcnt lgkmcnt(0)
	v_mfma_f32_16x16x32_bf16 v[126:129], v[130:133], v[186:189], v[126:129]
	v_mfma_f32_16x16x32_bf16 v[126:129], v[134:137], v[190:193], v[126:129]
	v_mfma_f32_16x16x32_bf16 v[122:125], v[142:145], v[190:193], v[122:125]
	v_mfma_f32_16x16x32_bf16 v[122:125], v[138:141], v[186:189], v[122:125]
	v_mfma_f32_16x16x32_bf16 v[114:117], v[138:141], v[194:197], v[114:117]
	v_mfma_f32_16x16x32_bf16 v[114:117], v[142:145], v[198:201], v[114:117]
	v_mfma_f32_16x16x32_bf16 v[118:121], v[134:137], v[198:201], v[118:121]
	v_mfma_f32_16x16x32_bf16 v[118:121], v[130:133], v[194:197], v[118:121]
	v_mfma_f32_16x16x32_bf16 v[110:113], v[130:133], v[202:205], v[110:113]
	v_mfma_f32_16x16x32_bf16 v[110:113], v[134:137], v[206:209], v[110:113]
	v_mfma_f32_16x16x32_bf16 v[102:105], v[142:145], v[206:209], v[102:105]
	v_mfma_f32_16x16x32_bf16 v[102:105], v[138:141], v[202:205], v[102:105]
	v_mfma_f32_16x16x32_bf16 v[74:77], v[138:141], v[210:213], v[74:77]
	v_mfma_f32_16x16x32_bf16 v[74:77], v[142:145], v[214:217], v[74:77]
	v_mfma_f32_16x16x32_bf16 v[78:81], v[134:137], v[214:217], v[78:81]
	v_mfma_f32_16x16x32_bf16 v[78:81], v[130:133], v[210:213], v[78:81]
	v_mfma_f32_16x16x32_bf16 v[106:109], v[164:167], v[186:189], v[106:109]
	v_mfma_f32_16x16x32_bf16 v[106:109], v[174:177], v[190:193], v[106:109]
	v_mfma_f32_16x16x32_bf16 v[98:101], v[182:185], v[190:193], v[98:101]
	v_mfma_f32_16x16x32_bf16 v[98:101], v[178:181], v[186:189], v[98:101]
	v_mfma_f32_16x16x32_bf16 v[90:93], v[178:181], v[194:197], v[90:93]
	v_mfma_f32_16x16x32_bf16 v[90:93], v[182:185], v[198:201], v[90:93]
	v_mfma_f32_16x16x32_bf16 v[94:97], v[174:177], v[198:201], v[94:97]
	v_mfma_f32_16x16x32_bf16 v[94:97], v[164:167], v[194:197], v[94:97]
	v_mfma_f32_16x16x32_bf16 v[86:89], v[164:167], v[202:205], v[86:89]
	v_mfma_f32_16x16x32_bf16 v[86:89], v[174:177], v[206:209], v[86:89]
	v_mfma_f32_16x16x32_bf16 v[82:85], v[182:185], v[206:209], v[82:85]
	v_mfma_f32_16x16x32_bf16 v[82:85], v[178:181], v[202:205], v[82:85]
	v_mfma_f32_16x16x32_bf16 v[66:69], v[178:181], v[210:213], v[66:69]
	v_mfma_f32_16x16x32_bf16 v[66:69], v[182:185], v[214:217], v[66:69]
	v_mfma_f32_16x16x32_bf16 v[70:73], v[174:177], v[214:217], v[70:73]
	v_mfma_f32_16x16x32_bf16 v[70:73], v[164:167], v[210:213], v[70:73]
	s_setprio 0
	s_barrier
; #define PG8_STAGE(bufoff, gbase, voff) do { _Pragma("unroll") for (int _i = 0; _i < 2; ++_i) \
;         __builtin_amdgcn_global_load_lds((const unsigned*)((const char*)(gbase) + (voff)[_i]), (PG8_LAS unsigned*)(lds + (bufoff) + ldsw + _i * 8192), 16, 0, 0); } while (0)
; #define PG8_LDA(dst, b, h) do { _Pragma("unroll") for (int m = 0; m < 4; ++m) _Pragma("unroll") for (int k = 0; k < 2; ++k) dst[m][k] = *(const PG8_LAS bf16x8*)(lds + PG8_SA(b, h) + aoff + m * 2048 + k * 1024); } while (0)
; #define PG8_MMA(ai, bj, At, Bt) do { __builtin_amdgcn_s_setprio(3); _Pragma("unroll") for (int m = 0; m < 4; ++m) _Pragma("unroll") for (int n = 0; n < 2; ++n) _Pragma("unroll") for (int k = 0; k < 2; ++k) \
;         acc[ai][bj][m][n] = __builtin_amdgcn_mfma_f32_16x16x32_bf16(Bt[n][k], At[m][k], acc[ai][bj][m][n], 0, 0, 0); __builtin_amdgcn_s_setprio(0); } while (0)
; #define PG8_WAIT_V(n) asm volatile("s_waitcnt vmcnt(" #n ")" ::: "memory")
; #define PG8_WAIT_L(n) asm volatile("s_waitcnt lgkmcnt(" #n ")" ::: "memory")
; #define PG8_BAR __builtin_amdgcn_s_barrier()
; #define PG8_SCHED __builtin_amdgcn_sched_barrier(0)
; template <class Epi, class Sched, bool ALIGN_EPI = false, bool SP2 = false>
; __device__ __forceinline__ void gemm_phase(PG8_LAS unsigned char* lds, const Gemm g, const Sched& S, const Epi& E) {
;     ...
;             PG8_LDA(At, 1, 1); PG8_STAGE(PG8_SB(1, 0), b3, voffB); PG8_STAGE(PG8_SB(1, 1), b3 + hstepB, voffB); PG8_STAGE(PG8_SA(1, 0), a3, voffA);
;             PG8_WAIT_V(8); PG8_WAIT_L(0); PG8_BAR; PG8_MMA(1, 0, At, B0); PG8_MMA(1, 1, At, B1); PG8_BAR; PG8_SCHED;
;     ...
;         if constexpr (ALIGN_EPI) { if (wr == 0) PG8_BAR; }
	s_add_i32 s58, s83, s44
	v_lshl_add_u64 v[218:219], v[218:219], 0, s[18:19]
	s_mov_b32 m0, s58
	ds_read_b128 v[186:189], v172 offset:49152
	ds_read_b128 v[190:193], v172 offset:50176
	ds_read_b128 v[194:197], v172 offset:51200
	ds_read_b128 v[198:201], v172 offset:52224
	ds_read_b128 v[202:205], v172 offset:53248
	ds_read_b128 v[206:209], v172 offset:54272
	ds_read_b128 v[210:213], v172 offset:55296
	ds_read_b128 v[214:217], v172 offset:56320
	global_load_lds_dwordx4 v[218:219], off
	s_add_i32 m0, s58, 0x2000
	s_add_u32 s36, s36, 0x20080
	v_lshl_add_u64 v[218:219], v[220:221], 0, s[18:19]
	s_addc_u32 s37, s37, 0
	s_add_i32 s58, s84, s44
	global_load_lds_dwordx4 v[218:219], off
	v_lshl_add_u64 v[218:219], s[36:37], 0, v[148:149]
	s_mov_b32 m0, s58
	s_nop 0
	global_load_lds_dwordx4 v[218:219], off
	v_lshl_add_u64 v[218:219], s[36:37], 0, v[152:153]
	s_add_i32 m0, s58, 0x2000
	s_nop 0
	global_load_lds_dwordx4 v[218:219], off
	v_lshl_add_u64 v[218:219], v[222:223], 0, s[18:19]
	s_mov_b32 m0, s63
	s_nop 0
	global_load_lds_dwordx4 v[218:219], off
	v_lshl_add_u64 v[218:219], v[224:225], 0, s[18:19]
	s_mov_b32 m0, s66
	s_nop 0
	global_load_lds_dwordx4 v[218:219], off
	s_waitcnt vmcnt(8)
	s_waitcnt lgkmcnt(0)
	s_barrier
	s_setprio 3
	s_waitcnt lgkmcnt(0)
	v_mfma_f32_16x16x32_bf16 v[62:65], v[130:133], v[186:189], v[62:65]
	v_mfma_f32_16x16x32_bf16 v[62:65], v[134:137], v[190:193], v[62:65]
	v_mfma_f32_16x16x32_bf16 v[58:61], v[142:145], v[190:193], v[58:61]
	v_mfma_f32_16x16x32_bf16 v[58:61], v[138:141], v[186:189], v[58:61]
	v_mfma_f32_16x16x32_bf16 v[46:49], v[138:141], v[194:197], v[46:49]
	v_mfma_f32_16x16x32_bf16 v[46:49], v[142:145], v[198:201], v[46:49]
	v_mfma_f32_16x16x32_bf16 v[54:57], v[134:137], v[198:201], v[54:57]
	v_mfma_f32_16x16x32_bf16 v[54:57], v[130:133], v[194:197], v[54:57]
	v_mfma_f32_16x16x32_bf16 v[38:41], v[130:133], v[202:205], v[38:41]
	v_mfma_f32_16x16x32_bf16 v[38:41], v[134:137], v[206:209], v[38:41]
	v_mfma_f32_16x16x32_bf16 v[30:33], v[142:145], v[206:209], v[30:33]
	v_mfma_f32_16x16x32_bf16 v[30:33], v[138:141], v[202:205], v[30:33]
	v_mfma_f32_16x16x32_bf16 v[14:17], v[138:141], v[210:213], v[14:17]
	v_mfma_f32_16x16x32_bf16 v[14:17], v[142:145], v[214:217], v[14:17]
	v_mfma_f32_16x16x32_bf16 v[22:25], v[134:137], v[214:217], v[22:25]
	v_mfma_f32_16x16x32_bf16 v[22:25], v[130:133], v[210:213], v[22:25]
	v_mfma_f32_16x16x32_bf16 v[50:53], v[164:167], v[186:189], v[50:53]
	v_mfma_f32_16x16x32_bf16 v[50:53], v[174:177], v[190:193], v[50:53]
	v_mfma_f32_16x16x32_bf16 v[42:45], v[182:185], v[190:193], v[42:45]
	v_mfma_f32_16x16x32_bf16 v[42:45], v[178:181], v[186:189], v[42:45]
	v_mfma_f32_16x16x32_bf16 v[26:29], v[178:181], v[194:197], v[26:29]
	v_mfma_f32_16x16x32_bf16 v[26:29], v[182:185], v[198:201], v[26:29]
	v_mfma_f32_16x16x32_bf16 v[34:37], v[174:177], v[198:201], v[34:37]
	v_mfma_f32_16x16x32_bf16 v[34:37], v[164:167], v[194:197], v[34:37]
	v_mfma_f32_16x16x32_bf16 v[18:21], v[164:167], v[202:205], v[18:21]
	v_mfma_f32_16x16x32_bf16 v[18:21], v[174:177], v[206:209], v[18:21]
	v_mfma_f32_16x16x32_bf16 v[10:13], v[182:185], v[206:209], v[10:13]
	v_mfma_f32_16x16x32_bf16 v[10:13], v[178:181], v[202:205], v[10:13]
	v_mfma_f32_16x16x32_bf16 v[2:5], v[178:181], v[210:213], v[2:5]
	v_mfma_f32_16x16x32_bf16 v[2:5], v[182:185], v[214:217], v[2:5]
	v_mfma_f32_16x16x32_bf16 v[6:9], v[174:177], v[214:217], v[6:9]
	v_mfma_f32_16x16x32_bf16 v[6:9], v[164:167], v[210:213], v[6:9]
	s_setprio 0
	s_barrier
	s_add_i32 s79, s79, 2
	s_add_u32 s6, s6, 0x100
	s_addc_u32 s7, s7, 0
	s_add_u32 s77, s77, 0x100
	s_addc_u32 s78, s78, 0
	s_cmp_gt_u32 s79, 5
	s_cbranch_scc0 .LBB0_478
	s_and_b64 vcc, exec, s[20:21]
	s_cbranch_vccz .LBB0_481
	s_barrier

; #define PG8_STAGE(bufoff, gbase, voff) do { _Pragma("unroll") for (int _i = 0; _i < 2; ++_i) \
;         __builtin_amdgcn_global_load_lds((const unsigned*)((const char*)(gbase) + (voff)[_i]), (PG8_LAS unsigned*)(lds + (bufoff) + ldsw + _i * 8192), 16, 0, 0); } while (0)
; #define PG8_LDA(dst, b, h) do { _Pragma("unroll") for (int m = 0; m < 4; ++m) _Pragma("unroll") for (int k = 0; k < 2; ++k) dst[m][k] = *(const PG8_LAS bf16x8*)(lds + PG8_SA(b, h) + aoff + m * 2048 + k * 1024); } while (0)
; #define PG8_LDB(dst, b, h) do { _Pragma("unroll") for (int n = 0; n < 2; ++n) _Pragma("unroll") for (int k = 0; k < 2; ++k) dst[n][k] = *(const PG8_LAS bf16x8*)(lds + PG8_SB(b, h) + boff + n * 2048 + k * 1024); } while (0)
; #define PG8_MMA(ai, bj, At, Bt) do { __builtin_amdgcn_s_setprio(3); _Pragma("unroll") for (int m = 0; m < 4; ++m) _Pragma("unroll") for (int n = 0; n < 2; ++n) _Pragma("unroll") for (int k = 0; k < 2; ++k) \
;         acc[ai][bj][m][n] = __builtin_amdgcn_mfma_f32_16x16x32_bf16(Bt[n][k], At[m][k], acc[ai][bj][m][n], 0, 0, 0); __builtin_amdgcn_s_setprio(0); } while (0)
; #define PG8_WAIT_V(n) asm volatile("s_waitcnt vmcnt(" #n ")" ::: "memory")
; #define PG8_WAIT_L(n) asm volatile("s_waitcnt lgkmcnt(" #n ")" ::: "memory")
; #define PG8_BAR __builtin_amdgcn_s_barrier()
; #define PG8_SCHED __builtin_amdgcn_sched_barrier(0)
; template <class Epi, class Sched, bool ALIGN_EPI = false, bool SP2 = false>
; __device__ __forceinline__ void gemm_phase(PG8_LAS unsigned char* lds, const Gemm g, const Sched& S, const Epi& E) {
;     ...
;             PG8_LDB(B0, 0, 0); PG8_LDB(B1, 0, 1); PG8_SCHED; PG8_LDA(At, 0, 0); PG8_STAGE(PG8_SA(1, 1), a1 + hstepA, voffA);
;             PG8_WAIT_V(8); PG8_WAIT_L(0); PG8_BAR; PG8_MMA(0, 0, At, B0); PG8_MMA(0, 1, At, B1); PG8_BAR; PG8_SCHED;
;             PG8_LDA(At, 0, 1); PG8_STAGE(PG8_SB(0, 0), b2, voffB); PG8_STAGE(PG8_SB(0, 1), b2 + hstepB, voffB); PG8_STAGE(PG8_SA(0, 0), a2, voffA);
.LBB0_727:
	v_add_u32_e32 v160, s66, v157
	ds_read_b128 v[130:133], v160
	ds_read_b128 v[164:167], v160 offset:1024
	ds_read_b128 v[168:171], v160 offset:2048
	ds_read_b128 v[172:175], v160 offset:3072
	v_add_u32_e32 v160, s67, v157
	s_add_u32 s0, s28, s30
	ds_read_b128 v[176:179], v160
	ds_read_b128 v[180:183], v160 offset:1024
	ds_read_b128 v[184:187], v160 offset:2048
	ds_read_b128 v[188:191], v160 offset:3072
	s_addc_u32 s1, s29, s31
	s_add_u32 s0, s0, 0x100
	s_addc_u32 s1, s1, 0
	s_add_u32 s84, s79, s30
	s_addc_u32 s85, s81, s31
	s_cmpk_eq_i32 s30, 0x1f00
	s_cselect_b32 s37, s23, s1
	s_cselect_b32 s36, s72, s0
	s_cselect_b32 s1, s75, s85
	s_cselect_b32 s0, s76, s84
	v_lshl_add_u64 v[160:161], v[150:151], 0, s[30:31]
	s_add_i32 m0, s44, 0xc000
	ds_read_b128 v[192:195], v159
	ds_read_b128 v[196:199], v159 offset:1024
	ds_read_b128 v[200:203], v159 offset:2048
	ds_read_b128 v[204:207], v159 offset:3072
	ds_read_b128 v[208:211], v159 offset:4096
	ds_read_b128 v[212:215], v159 offset:5120
	ds_read_b128 v[216:219], v159 offset:6144
	ds_read_b128 v[220:223], v159 offset:7168
	global_load_lds_dwordx4 v[160:161], off
	v_lshl_add_u64 v[160:161], v[152:153], 0, s[30:31]
	s_add_i32 m0, s44, 0xe000
	s_nop 0
	global_load_lds_dwordx4 v[160:161], off
	s_waitcnt vmcnt(8)
	s_waitcnt lgkmcnt(0)
	s_barrier
	s_setprio 3
	s_waitcnt lgkmcnt(0)
	v_mfma_f32_16x16x32_bf16 v[126:129], v[130:133], v[192:195], v[126:129]
	v_mfma_f32_16x16x32_bf16 v[126:129], v[164:167], v[196:199], v[126:129]
	v_mfma_f32_16x16x32_bf16 v[122:125], v[172:175], v[196:199], v[122:125]
	v_mfma_f32_16x16x32_bf16 v[122:125], v[168:171], v[192:195], v[122:125]
	v_mfma_f32_16x16x32_bf16 v[106:109], v[168:171], v[200:203], v[106:109]
	v_mfma_f32_16x16x32_bf16 v[106:109], v[172:175], v[204:207], v[106:109]
	v_mfma_f32_16x16x32_bf16 v[110:113], v[164:167], v[204:207], v[110:113]
	v_mfma_f32_16x16x32_bf16 v[110:113], v[130:133], v[200:203], v[110:113]
	v_mfma_f32_16x16x32_bf16 v[94:97], v[130:133], v[208:211], v[94:97]
	v_mfma_f32_16x16x32_bf16 v[94:97], v[164:167], v[212:215], v[94:97]
	v_mfma_f32_16x16x32_bf16 v[90:93], v[172:175], v[212:215], v[90:93]
	v_mfma_f32_16x16x32_bf16 v[90:93], v[168:171], v[208:211], v[90:93]
	v_mfma_f32_16x16x32_bf16 v[74:77], v[168:171], v[216:219], v[74:77]
	v_mfma_f32_16x16x32_bf16 v[74:77], v[172:175], v[220:223], v[74:77]
	v_mfma_f32_16x16x32_bf16 v[78:81], v[164:167], v[220:223], v[78:81]
	v_mfma_f32_16x16x32_bf16 v[78:81], v[130:133], v[216:219], v[78:81]
	v_mfma_f32_16x16x32_bf16 v[118:121], v[176:179], v[192:195], v[118:121]
	v_mfma_f32_16x16x32_bf16 v[118:121], v[180:183], v[196:199], v[118:121]
	v_mfma_f32_16x16x32_bf16 v[114:117], v[188:191], v[196:199], v[114:117]
	v_mfma_f32_16x16x32_bf16 v[114:117], v[184:187], v[192:195], v[114:117]
	v_mfma_f32_16x16x32_bf16 v[98:101], v[184:187], v[200:203], v[98:101]
	v_mfma_f32_16x16x32_bf16 v[98:101], v[188:191], v[204:207], v[98:101]
	v_mfma_f32_16x16x32_bf16 v[102:105], v[180:183], v[204:207], v[102:105]
	v_mfma_f32_16x16x32_bf16 v[102:105], v[176:179], v[200:203], v[102:105]
	v_mfma_f32_16x16x32_bf16 v[86:89], v[176:179], v[208:211], v[86:89]
	v_mfma_f32_16x16x32_bf16 v[86:89], v[180:183], v[212:215], v[86:89]
	v_mfma_f32_16x16x32_bf16 v[82:85], v[188:191], v[212:215], v[82:85]
	v_mfma_f32_16x16x32_bf16 v[82:85], v[184:187], v[208:211], v[82:85]
	v_mfma_f32_16x16x32_bf16 v[66:69], v[184:187], v[216:219], v[66:69]
	v_mfma_f32_16x16x32_bf16 v[66:69], v[188:191], v[220:223], v[66:69]
	v_mfma_f32_16x16x32_bf16 v[70:73], v[180:183], v[220:223], v[70:73]
	v_mfma_f32_16x16x32_bf16 v[70:73], v[176:179], v[216:219], v[70:73]
	s_setprio 0
	s_barrier
	s_add_i32 s84, s66, s33
	v_lshl_add_u64 v[160:161], s[0:1], 0, v[136:137]
	s_mov_b32 m0, s84
	ds_read_b128 v[192:195], v159 offset:16384
	ds_read_b128 v[196:199], v159 offset:17408
	ds_read_b128 v[200:203], v159 offset:18432
	ds_read_b128 v[204:207], v159 offset:19456
	ds_read_b128 v[208:211], v159 offset:20480
	ds_read_b128 v[212:215], v159 offset:21504
	ds_read_b128 v[216:219], v159 offset:22528
	ds_read_b128 v[220:223], v159 offset:23552
	global_load_lds_dwordx4 v[160:161], off
	s_add_i32 m0, s84, 0x2000
	s_add_u32 s84, s0, 0x100000
	v_lshl_add_u64 v[224:225], s[0:1], 0, v[140:141]
	s_addc_u32 s85, s1, 0
	s_add_i32 s86, s67, s33
	global_load_lds_dwordx4 v[224:225], off
	v_lshl_add_u64 v[226:227], s[84:85], 0, v[136:137]
	s_mov_b32 m0, s86
	v_lshl_add_u64 v[228:229], s[36:37], 0, v[138:139]
	global_load_lds_dwordx4 v[226:227], off
	v_lshl_add_u64 v[226:227], s[84:85], 0, v[140:141]
	s_add_i32 m0, s86, 0x2000
	s_nop 0
	global_load_lds_dwordx4 v[226:227], off
	v_lshl_add_u64 v[226:227], s[36:37], 0, v[134:135]
	s_mov_b32 m0, s44
	s_nop 0
	global_load_lds_dwordx4 v[226:227], off
	s_mov_b32 m0, s45
	s_nop 0
	global_load_lds_dwordx4 v[228:229], off
	s_waitcnt vmcnt(8)
	s_waitcnt lgkmcnt(0)
	s_barrier
; #define PG8_STAGE(bufoff, gbase, voff) do { _Pragma("unroll") for (int _i = 0; _i < 2; ++_i) \
;         __builtin_amdgcn_global_load_lds((const unsigned*)((const char*)(gbase) + (voff)[_i]), (PG8_LAS unsigned*)(lds + (bufoff) + ldsw + _i * 8192), 16, 0, 0); } while (0)
; #define PG8_LDA(dst, b, h) do { _Pragma("unroll") for (int m = 0; m < 4; ++m) _Pragma("unroll") for (int k = 0; k < 2; ++k) dst[m][k] = *(const PG8_LAS bf16x8*)(lds + PG8_SA(b, h) + aoff + m * 2048 + k * 1024); } while (0)
; #define PG8_LDB(dst, b, h) do { _Pragma("unroll") for (int n = 0; n < 2; ++n) _Pragma("unroll") for (int k = 0; k < 2; ++k) dst[n][k] = *(const PG8_LAS bf16x8*)(lds + PG8_SB(b, h) + boff + n * 2048 + k * 1024); } while (0)
; #define PG8_MMA(ai, bj, At, Bt) do { __builtin_amdgcn_s_setprio(3); _Pragma("unroll") for (int m = 0; m < 4; ++m) _Pragma("unroll") for (int n = 0; n < 2; ++n) _Pragma("unroll") for (int k = 0; k < 2; ++k) \
;         acc[ai][bj][m][n] = __builtin_amdgcn_mfma_f32_16x16x32_bf16(Bt[n][k], At[m][k], acc[ai][bj][m][n], 0, 0, 0); __builtin_amdgcn_s_setprio(0); } while (0)
; #define PG8_WAIT_V(n) asm volatile("s_waitcnt vmcnt(" #n ")" ::: "memory")
; #define PG8_WAIT_L(n) asm volatile("s_waitcnt lgkmcnt(" #n ")" ::: "memory")
; #define PG8_BAR __builtin_amdgcn_s_barrier()
; #define PG8_SCHED __builtin_amdgcn_sched_barrier(0)
; template <class Epi, class Sched, bool ALIGN_EPI = false, bool SP2 = false>
; __device__ __forceinline__ void gemm_phase(PG8_LAS unsigned char* lds, const Gemm g, const Sched& S, const Epi& E) {
;     ...
;             PG8_WAIT_V(8); PG8_WAIT_L(0); PG8_BAR; PG8_MMA(1, 0, At, B0); PG8_MMA(1, 1, At, B1); PG8_BAR; PG8_SCHED;
;             PG8_LDB(B0, 1, 0); PG8_LDB(B1, 1, 1); PG8_SCHED; PG8_LDA(At, 1, 0); PG8_STAGE(PG8_SA(0, 1), a2 + hstepA, voffA);
;             PG8_WAIT_V(8); PG8_WAIT_L(0); PG8_BAR; PG8_MMA(0, 0, At, B0); PG8_MMA(0, 1, At, B1); PG8_BAR; PG8_SCHED;
	s_setprio 3
	s_waitcnt lgkmcnt(0)
	v_mfma_f32_16x16x32_bf16 v[62:65], v[130:133], v[192:195], v[62:65]
	v_mfma_f32_16x16x32_bf16 v[62:65], v[164:167], v[196:199], v[62:65]
	v_mfma_f32_16x16x32_bf16 v[58:61], v[172:175], v[196:199], v[58:61]
	v_mfma_f32_16x16x32_bf16 v[58:61], v[168:171], v[192:195], v[58:61]
	v_mfma_f32_16x16x32_bf16 v[42:45], v[168:171], v[200:203], v[42:45]
	v_mfma_f32_16x16x32_bf16 v[42:45], v[172:175], v[204:207], v[42:45]
	v_mfma_f32_16x16x32_bf16 v[46:49], v[164:167], v[204:207], v[46:49]
	v_mfma_f32_16x16x32_bf16 v[46:49], v[130:133], v[200:203], v[46:49]
	v_mfma_f32_16x16x32_bf16 v[30:33], v[130:133], v[208:211], v[30:33]
	v_mfma_f32_16x16x32_bf16 v[30:33], v[164:167], v[212:215], v[30:33]
	v_mfma_f32_16x16x32_bf16 v[26:29], v[172:175], v[212:215], v[26:29]
	v_mfma_f32_16x16x32_bf16 v[26:29], v[168:171], v[208:211], v[26:29]
	v_mfma_f32_16x16x32_bf16 v[10:13], v[168:171], v[216:219], v[10:13]
	v_mfma_f32_16x16x32_bf16 v[10:13], v[172:175], v[220:223], v[10:13]
	v_mfma_f32_16x16x32_bf16 v[14:17], v[164:167], v[220:223], v[14:17]
	v_mfma_f32_16x16x32_bf16 v[14:17], v[130:133], v[216:219], v[14:17]
	v_mfma_f32_16x16x32_bf16 v[54:57], v[176:179], v[192:195], v[54:57]
	v_mfma_f32_16x16x32_bf16 v[54:57], v[180:183], v[196:199], v[54:57]
	v_mfma_f32_16x16x32_bf16 v[50:53], v[188:191], v[196:199], v[50:53]
	v_mfma_f32_16x16x32_bf16 v[50:53], v[184:187], v[192:195], v[50:53]
	v_mfma_f32_16x16x32_bf16 v[34:37], v[184:187], v[200:203], v[34:37]
	v_mfma_f32_16x16x32_bf16 v[34:37], v[188:191], v[204:207], v[34:37]
	v_mfma_f32_16x16x32_bf16 v[38:41], v[180:183], v[204:207], v[38:41]
	v_mfma_f32_16x16x32_bf16 v[38:41], v[176:179], v[200:203], v[38:41]
	v_mfma_f32_16x16x32_bf16 v[22:25], v[176:179], v[208:211], v[22:25]
	v_mfma_f32_16x16x32_bf16 v[22:25], v[180:183], v[212:215], v[22:25]
	v_mfma_f32_16x16x32_bf16 v[18:21], v[188:191], v[212:215], v[18:21]
	v_mfma_f32_16x16x32_bf16 v[18:21], v[184:187], v[208:211], v[18:21]
	v_mfma_f32_16x16x32_bf16 v[2:5], v[184:187], v[216:219], v[2:5]
	v_mfma_f32_16x16x32_bf16 v[2:5], v[188:191], v[220:223], v[2:5]
	v_mfma_f32_16x16x32_bf16 v[6:9], v[180:183], v[220:223], v[6:9]
	v_mfma_f32_16x16x32_bf16 v[6:9], v[176:179], v[216:219], v[6:9]
	s_setprio 0
	s_barrier
	s_add_i32 s84, 0, 0x18000
	v_add_u32_e32 v163, s84, v157
	s_add_i32 s85, 0, 0x1c000
	ds_read_b128 v[130:133], v163
	ds_read_b128 v[164:167], v163 offset:1024
	ds_read_b128 v[168:171], v163 offset:2048
	ds_read_b128 v[172:175], v163 offset:3072
	v_add_u32_e32 v163, s85, v157
	ds_read_b128 v[176:179], v163
	ds_read_b128 v[180:183], v163 offset:1024
	ds_read_b128 v[184:187], v163 offset:2048
	ds_read_b128 v[188:191], v163 offset:3072
	s_add_u32 s36, s36, 0x100000
	s_addc_u32 s37, s37, 0
	s_mov_b32 m0, s54
	v_lshl_add_u64 v[230:231], s[36:37], 0, v[134:135]
	ds_read_b128 v[192:195], v159 offset:32768
	ds_read_b128 v[196:199], v159 offset:33792
	ds_read_b128 v[200:203], v159 offset:34816
	ds_read_b128 v[204:207], v159 offset:35840
	ds_read_b128 v[208:211], v159 offset:36864
	ds_read_b128 v[212:215], v159 offset:37888
	ds_read_b128 v[216:219], v159 offset:38912
	ds_read_b128 v[220:223], v159 offset:39936
	global_load_lds_dwordx4 v[230:231], off
	v_lshl_add_u64 v[230:231], s[36:37], 0, v[138:139]
	s_mov_b32 m0, s55
	s_nop 0
	global_load_lds_dwordx4 v[230:231], off
	s_waitcnt vmcnt(8)
	s_waitcnt lgkmcnt(0)
	s_barrier
	s_setprio 3
	s_waitcnt lgkmcnt(0)
	v_mfma_f32_16x16x32_bf16 v[126:129], v[130:133], v[192:195], v[126:129]
	v_mfma_f32_16x16x32_bf16 v[126:129], v[164:167], v[196:199], v[126:129]
	v_mfma_f32_16x16x32_bf16 v[122:125], v[172:175], v[196:199], v[122:125]
	v_mfma_f32_16x16x32_bf16 v[122:125], v[168:171], v[192:195], v[122:125]
	v_mfma_f32_16x16x32_bf16 v[106:109], v[168:171], v[200:203], v[106:109]
	v_mfma_f32_16x16x32_bf16 v[106:109], v[172:175], v[204:207], v[106:109]
	v_mfma_f32_16x16x32_bf16 v[110:113], v[164:167], v[204:207], v[110:113]
	v_mfma_f32_16x16x32_bf16 v[110:113], v[130:133], v[200:203], v[110:113]
	v_mfma_f32_16x16x32_bf16 v[94:97], v[130:133], v[208:211], v[94:97]
	v_mfma_f32_16x16x32_bf16 v[94:97], v[164:167], v[212:215], v[94:97]
	v_mfma_f32_16x16x32_bf16 v[90:93], v[172:175], v[212:215], v[90:93]
	v_mfma_f32_16x16x32_bf16 v[90:93], v[168:171], v[208:211], v[90:93]
	v_mfma_f32_16x16x32_bf16 v[74:77], v[168:171], v[216:219], v[74:77]
	v_mfma_f32_16x16x32_bf16 v[74:77], v[172:175], v[220:223], v[74:77]
	v_mfma_f32_16x16x32_bf16 v[78:81], v[164:167], v[220:223], v[78:81]
	v_mfma_f32_16x16x32_bf16 v[78:81], v[130:133], v[216:219], v[78:81]
	v_mfma_f32_16x16x32_bf16 v[118:121], v[176:179], v[192:195], v[118:121]
	v_mfma_f32_16x16x32_bf16 v[118:121], v[180:183], v[196:199], v[118:121]
	v_mfma_f32_16x16x32_bf16 v[114:117], v[188:191], v[196:199], v[114:117]
	v_mfma_f32_16x16x32_bf16 v[114:117], v[184:187], v[192:195], v[114:117]
	v_mfma_f32_16x16x32_bf16 v[98:101], v[184:187], v[200:203], v[98:101]
	v_mfma_f32_16x16x32_bf16 v[98:101], v[188:191], v[204:207], v[98:101]
	v_mfma_f32_16x16x32_bf16 v[102:105], v[180:183], v[204:207], v[102:105]
	v_mfma_f32_16x16x32_bf16 v[102:105], v[176:179], v[200:203], v[102:105]
	v_mfma_f32_16x16x32_bf16 v[86:89], v[176:179], v[208:211], v[86:89]
	v_mfma_f32_16x16x32_bf16 v[86:89], v[180:183], v[212:215], v[86:89]
	v_mfma_f32_16x16x32_bf16 v[82:85], v[188:191], v[212:215], v[82:85]
	v_mfma_f32_16x16x32_bf16 v[82:85], v[184:187], v[208:211], v[82:85]
	v_mfma_f32_16x16x32_bf16 v[66:69], v[184:187], v[216:219], v[66:69]
	v_mfma_f32_16x16x32_bf16 v[66:69], v[188:191], v[220:223], v[66:69]
	v_mfma_f32_16x16x32_bf16 v[70:73], v[180:183], v[220:223], v[70:73]
	v_mfma_f32_16x16x32_bf16 v[70:73], v[176:179], v[216:219], v[70:73]
	s_setprio 0
	s_barrier
; #define PG8_STAGE(bufoff, gbase, voff) do { _Pragma("unroll") for (int _i = 0; _i < 2; ++_i) \
;         __builtin_amdgcn_global_load_lds((const unsigned*)((const char*)(gbase) + (voff)[_i]), (PG8_LAS unsigned*)(lds + (bufoff) + ldsw + _i * 8192), 16, 0, 0); } while (0)
; #define PG8_LDA(dst, b, h) do { _Pragma("unroll") for (int m = 0; m < 4; ++m) _Pragma("unroll") for (int k = 0; k < 2; ++k) dst[m][k] = *(const PG8_LAS bf16x8*)(lds + PG8_SA(b, h) + aoff + m * 2048 + k * 1024); } while (0)
; #define PG8_MMA(ai, bj, At, Bt) do { __builtin_amdgcn_s_setprio(3); _Pragma("unroll") for (int m = 0; m < 4; ++m) _Pragma("unroll") for (int n = 0; n < 2; ++n) _Pragma("unroll") for (int k = 0; k < 2; ++k) \
;         acc[ai][bj][m][n] = __builtin_amdgcn_mfma_f32_16x16x32_bf16(Bt[n][k], At[m][k], acc[ai][bj][m][n], 0, 0, 0); __builtin_amdgcn_s_setprio(0); } while (0)
; #define PG8_WAIT_V(n) asm volatile("s_waitcnt vmcnt(" #n ")" ::: "memory")
; #define PG8_WAIT_L(n) asm volatile("s_waitcnt lgkmcnt(" #n ")" ::: "memory")
; #define PG8_BAR __builtin_amdgcn_s_barrier()
; #define PG8_SCHED __builtin_amdgcn_sched_barrier(0)
; template <class Epi, class Sched, bool ALIGN_EPI = false, bool SP2 = false>
; __device__ __forceinline__ void gemm_phase(PG8_LAS unsigned char* lds, const Gemm g, const Sched& S, const Epi& E) {
;     ...
;             PG8_LDA(At, 1, 1); PG8_STAGE(PG8_SB(1, 0), b3, voffB); PG8_STAGE(PG8_SB(1, 1), b3 + hstepB, voffB); PG8_STAGE(PG8_SA(1, 0), a3, voffA);
;             PG8_WAIT_V(8); PG8_WAIT_L(0); PG8_BAR; PG8_MMA(1, 0, At, B0); PG8_MMA(1, 1, At, B1); PG8_BAR; PG8_SCHED;
	s_add_i32 s36, s84, s33
	v_lshl_add_u64 v[160:161], v[160:161], 0, s[10:11]
	s_mov_b32 m0, s36
	ds_read_b128 v[192:195], v159 offset:49152
	ds_read_b128 v[196:199], v159 offset:50176
	ds_read_b128 v[200:203], v159 offset:51200
	ds_read_b128 v[204:207], v159 offset:52224
	ds_read_b128 v[208:211], v159 offset:53248
	ds_read_b128 v[212:215], v159 offset:54272
	ds_read_b128 v[216:219], v159 offset:55296
	ds_read_b128 v[220:223], v159 offset:56320
	global_load_lds_dwordx4 v[160:161], off
	s_add_i32 m0, s36, 0x2000
	s_add_u32 s0, s0, 0x100080
	v_lshl_add_u64 v[160:161], v[224:225], 0, s[10:11]
	s_addc_u32 s1, s1, 0
	s_add_i32 s36, s85, s33
	global_load_lds_dwordx4 v[160:161], off
	v_lshl_add_u64 v[160:161], s[0:1], 0, v[136:137]
	s_mov_b32 m0, s36
	s_nop 0
	global_load_lds_dwordx4 v[160:161], off
	v_lshl_add_u64 v[160:161], s[0:1], 0, v[140:141]
	s_add_i32 m0, s36, 0x2000
	s_nop 0
	global_load_lds_dwordx4 v[160:161], off
	v_lshl_add_u64 v[160:161], v[226:227], 0, s[10:11]
	s_mov_b32 m0, s61
	s_nop 0
	global_load_lds_dwordx4 v[160:161], off
	v_lshl_add_u64 v[160:161], v[228:229], 0, s[10:11]
	s_mov_b32 m0, s62
	s_nop 0
	global_load_lds_dwordx4 v[160:161], off
	s_waitcnt vmcnt(8)
	s_waitcnt lgkmcnt(0)
	s_barrier
	s_setprio 3
	s_waitcnt lgkmcnt(0)
	v_mfma_f32_16x16x32_bf16 v[62:65], v[130:133], v[192:195], v[62:65]
	v_mfma_f32_16x16x32_bf16 v[62:65], v[164:167], v[196:199], v[62:65]
	v_mfma_f32_16x16x32_bf16 v[58:61], v[172:175], v[196:199], v[58:61]
	v_mfma_f32_16x16x32_bf16 v[58:61], v[168:171], v[192:195], v[58:61]
	v_mfma_f32_16x16x32_bf16 v[42:45], v[168:171], v[200:203], v[42:45]
	v_mfma_f32_16x16x32_bf16 v[42:45], v[172:175], v[204:207], v[42:45]
	v_mfma_f32_16x16x32_bf16 v[46:49], v[164:167], v[204:207], v[46:49]
	v_mfma_f32_16x16x32_bf16 v[46:49], v[130:133], v[200:203], v[46:49]
	v_mfma_f32_16x16x32_bf16 v[30:33], v[130:133], v[208:211], v[30:33]
	v_mfma_f32_16x16x32_bf16 v[30:33], v[164:167], v[212:215], v[30:33]
	v_mfma_f32_16x16x32_bf16 v[26:29], v[172:175], v[212:215], v[26:29]
	v_mfma_f32_16x16x32_bf16 v[26:29], v[168:171], v[208:211], v[26:29]
	v_mfma_f32_16x16x32_bf16 v[10:13], v[168:171], v[216:219], v[10:13]
	v_mfma_f32_16x16x32_bf16 v[10:13], v[172:175], v[220:223], v[10:13]
	v_mfma_f32_16x16x32_bf16 v[14:17], v[164:167], v[220:223], v[14:17]
	v_mfma_f32_16x16x32_bf16 v[14:17], v[130:133], v[216:219], v[14:17]
	v_mfma_f32_16x16x32_bf16 v[54:57], v[176:179], v[192:195], v[54:57]
	v_mfma_f32_16x16x32_bf16 v[54:57], v[180:183], v[196:199], v[54:57]
	v_mfma_f32_16x16x32_bf16 v[50:53], v[188:191], v[196:199], v[50:53]
	v_mfma_f32_16x16x32_bf16 v[50:53], v[184:187], v[192:195], v[50:53]
	v_mfma_f32_16x16x32_bf16 v[34:37], v[184:187], v[200:203], v[34:37]
	v_mfma_f32_16x16x32_bf16 v[34:37], v[188:191], v[204:207], v[34:37]
	v_mfma_f32_16x16x32_bf16 v[38:41], v[180:183], v[204:207], v[38:41]
	v_mfma_f32_16x16x32_bf16 v[38:41], v[176:179], v[200:203], v[38:41]
	v_mfma_f32_16x16x32_bf16 v[22:25], v[176:179], v[208:211], v[22:25]
	v_mfma_f32_16x16x32_bf16 v[22:25], v[180:183], v[212:215], v[22:25]
	v_mfma_f32_16x16x32_bf16 v[18:21], v[188:191], v[212:215], v[18:21]
	v_mfma_f32_16x16x32_bf16 v[18:21], v[184:187], v[208:211], v[18:21]
	v_mfma_f32_16x16x32_bf16 v[2:5], v[184:187], v[216:219], v[2:5]
	v_mfma_f32_16x16x32_bf16 v[2:5], v[188:191], v[220:223], v[2:5]
	v_mfma_f32_16x16x32_bf16 v[6:9], v[180:183], v[220:223], v[6:9]
	v_mfma_f32_16x16x32_bf16 v[6:9], v[176:179], v[216:219], v[6:9]
	s_setprio 0
	s_barrier
	s_add_i32 s83, s83, 2
	s_add_u32 s30, s30, 0x100
	s_addc_u32 s31, s31, 0
	s_cmp_gt_u32 s83, 61
	s_cbranch_scc1 .LBB0_730

; #define PG8_STAGE(bufoff, gbase, voff) do { _Pragma("unroll") for (int _i = 0; _i < 2; ++_i) \
;         __builtin_amdgcn_global_load_lds((const unsigned*)((const char*)(gbase) + (voff)[_i]), (PG8_LAS unsigned*)(lds + (bufoff) + ldsw + _i * 8192), 16, 0, 0); } while (0)
; #define PG8_LDA(dst, b, h) do { _Pragma("unroll") for (int m = 0; m < 4; ++m) _Pragma("unroll") for (int k = 0; k < 2; ++k) dst[m][k] = *(const PG8_LAS bf16x8*)(lds + PG8_SA(b, h) + aoff + m * 2048 + k * 1024); } while (0)
; #define PG8_LDB(dst, b, h) do { _Pragma("unroll") for (int n = 0; n < 2; ++n) _Pragma("unroll") for (int k = 0; k < 2; ++k) dst[n][k] = *(const PG8_LAS bf16x8*)(lds + PG8_SB(b, h) + boff + n * 2048 + k * 1024); } while (0)
; #define PG8_MMA(ai, bj, At, Bt) do { __builtin_amdgcn_s_setprio(3); _Pragma("unroll") for (int m = 0; m < 4; ++m) _Pragma("unroll") for (int n = 0; n < 2; ++n) _Pragma("unroll") for (int k = 0; k < 2; ++k) \
;         acc[ai][bj][m][n] = __builtin_amdgcn_mfma_f32_16x16x32_bf16(Bt[n][k], At[m][k], acc[ai][bj][m][n], 0, 0, 0); __builtin_amdgcn_s_setprio(0); } while (0)
; #define PG8_WAIT_V(n) asm volatile("s_waitcnt vmcnt(" #n ")" ::: "memory")
; #define PG8_WAIT_L(n) asm volatile("s_waitcnt lgkmcnt(" #n ")" ::: "memory")
; #define PG8_BAR __builtin_amdgcn_s_barrier()
; #define PG8_SCHED __builtin_amdgcn_sched_barrier(0)
; template <class Epi, class Sched, bool ALIGN_EPI = false, bool SP2 = false>
; __device__ __forceinline__ void gemm_phase(PG8_LAS unsigned char* lds, const Gemm g, const Sched& S, const Epi& E) {
;     ...
;             PG8_LDB(B0, 0, 0); PG8_LDB(B1, 0, 1); PG8_SCHED; PG8_LDA(At, 0, 0); PG8_STAGE(PG8_SA(1, 1), a1 + hstepA, voffA);
;             PG8_WAIT_V(8); PG8_WAIT_L(0); PG8_BAR; PG8_MMA(0, 0, At, B0); PG8_MMA(0, 1, At, B1); PG8_BAR; PG8_SCHED;
;             PG8_LDA(At, 0, 1); PG8_STAGE(PG8_SB(0, 0), b2, voffB); PG8_STAGE(PG8_SB(0, 1), b2 + hstepB, voffB); PG8_STAGE(PG8_SA(0, 0), a2, voffA);
.LBB0_808:
	v_add_u32_e32 v3, s65, v186
	ds_read_b128 v[134:137], v3
	ds_read_b128 v[138:141], v3 offset:1024
	ds_read_b128 v[142:145], v3 offset:2048
	ds_read_b128 v[146:149], v3 offset:3072
	v_add_u32_e32 v3, s66, v186
	s_add_u32 s36, s28, s30
	ds_read_b128 v[150:153], v3
	ds_read_b128 v[154:157], v3 offset:1024
	ds_read_b128 v[158:161], v3 offset:2048
	ds_read_b128 v[190:193], v3 offset:3072
	s_addc_u32 s37, s29, s31
	s_add_u32 s36, s36, 0x100
	s_addc_u32 s37, s37, 0
	s_add_u32 s86, s83, s30
	s_addc_u32 s87, s84, s31
	s_cmpk_eq_i32 s30, 0x1f00
	s_cselect_b32 s41, s23, s37
	s_cselect_b32 s40, s75, s36
	s_cselect_b32 s37, s77, s87
	s_cselect_b32 s36, s78, s86
	v_lshl_add_u64 v[4:5], v[180:181], 0, s[30:31]
	s_add_i32 m0, s42, 0xc000
	ds_read_b128 v[194:197], v188
	ds_read_b128 v[198:201], v188 offset:1024
	ds_read_b128 v[202:205], v188 offset:2048
	ds_read_b128 v[206:209], v188 offset:3072
	ds_read_b128 v[210:213], v188 offset:4096
	ds_read_b128 v[214:217], v188 offset:5120
	ds_read_b128 v[218:221], v188 offset:6144
	ds_read_b128 v[222:225], v188 offset:7168
	global_load_lds_dwordx4 v[4:5], off
	v_lshl_add_u64 v[4:5], v[182:183], 0, s[30:31]
	s_add_i32 m0, s42, 0xe000
	s_nop 0
	global_load_lds_dwordx4 v[4:5], off
	s_waitcnt vmcnt(8)
	s_waitcnt lgkmcnt(0)
	s_barrier
	s_setprio 3
	s_waitcnt lgkmcnt(0)
	v_mfma_f32_16x16x32_bf16 v[130:133], v[134:137], v[194:197], v[130:133]
	v_mfma_f32_16x16x32_bf16 v[130:133], v[138:141], v[198:201], v[130:133]
	v_mfma_f32_16x16x32_bf16 v[126:129], v[146:149], v[198:201], v[126:129]
	v_mfma_f32_16x16x32_bf16 v[126:129], v[142:145], v[194:197], v[126:129]
	v_mfma_f32_16x16x32_bf16 v[110:113], v[142:145], v[202:205], v[110:113]
	v_mfma_f32_16x16x32_bf16 v[110:113], v[146:149], v[206:209], v[110:113]
	v_mfma_f32_16x16x32_bf16 v[114:117], v[138:141], v[206:209], v[114:117]
	v_mfma_f32_16x16x32_bf16 v[114:117], v[134:137], v[202:205], v[114:117]
	v_mfma_f32_16x16x32_bf16 v[98:101], v[134:137], v[210:213], v[98:101]
	v_mfma_f32_16x16x32_bf16 v[98:101], v[138:141], v[214:217], v[98:101]
	v_mfma_f32_16x16x32_bf16 v[94:97], v[146:149], v[214:217], v[94:97]
	v_mfma_f32_16x16x32_bf16 v[94:97], v[142:145], v[210:213], v[94:97]
	v_mfma_f32_16x16x32_bf16 v[78:81], v[142:145], v[218:221], v[78:81]
	v_mfma_f32_16x16x32_bf16 v[78:81], v[146:149], v[222:225], v[78:81]
	v_mfma_f32_16x16x32_bf16 v[82:85], v[138:141], v[222:225], v[82:85]
	v_mfma_f32_16x16x32_bf16 v[82:85], v[134:137], v[218:221], v[82:85]
	v_mfma_f32_16x16x32_bf16 v[122:125], v[150:153], v[194:197], v[122:125]
	v_mfma_f32_16x16x32_bf16 v[122:125], v[154:157], v[198:201], v[122:125]
	v_mfma_f32_16x16x32_bf16 v[118:121], v[190:193], v[198:201], v[118:121]
	v_mfma_f32_16x16x32_bf16 v[118:121], v[158:161], v[194:197], v[118:121]
	v_mfma_f32_16x16x32_bf16 v[102:105], v[158:161], v[202:205], v[102:105]
	v_mfma_f32_16x16x32_bf16 v[102:105], v[190:193], v[206:209], v[102:105]
	v_mfma_f32_16x16x32_bf16 v[106:109], v[154:157], v[206:209], v[106:109]
	v_mfma_f32_16x16x32_bf16 v[106:109], v[150:153], v[202:205], v[106:109]
	v_mfma_f32_16x16x32_bf16 v[90:93], v[150:153], v[210:213], v[90:93]
	v_mfma_f32_16x16x32_bf16 v[90:93], v[154:157], v[214:217], v[90:93]
	v_mfma_f32_16x16x32_bf16 v[86:89], v[190:193], v[214:217], v[86:89]
	v_mfma_f32_16x16x32_bf16 v[86:89], v[158:161], v[210:213], v[86:89]
	v_mfma_f32_16x16x32_bf16 v[70:73], v[158:161], v[218:221], v[70:73]
	v_mfma_f32_16x16x32_bf16 v[70:73], v[190:193], v[222:225], v[70:73]
	v_mfma_f32_16x16x32_bf16 v[74:77], v[154:157], v[222:225], v[74:77]
	v_mfma_f32_16x16x32_bf16 v[74:77], v[150:153], v[218:221], v[74:77]
	s_setprio 0
	s_barrier
	s_add_i32 s86, s65, s33
	v_lshl_add_u64 v[226:227], s[36:37], 0, v[166:167]
	s_mov_b32 m0, s86
	ds_read_b128 v[194:197], v188 offset:16384
	ds_read_b128 v[198:201], v188 offset:17408
	ds_read_b128 v[202:205], v188 offset:18432
	ds_read_b128 v[206:209], v188 offset:19456
	ds_read_b128 v[210:213], v188 offset:20480
	ds_read_b128 v[214:217], v188 offset:21504
	ds_read_b128 v[218:221], v188 offset:22528
	ds_read_b128 v[222:225], v188 offset:23552
	global_load_lds_dwordx4 v[226:227], off
	s_add_i32 m0, s86, 0x2000
	s_add_u32 s86, s36, 0x100000
	v_lshl_add_u64 v[228:229], s[36:37], 0, v[170:171]
	s_addc_u32 s87, s37, 0
	s_add_i32 s88, s66, s33
	global_load_lds_dwordx4 v[228:229], off
	v_lshl_add_u64 v[4:5], s[86:87], 0, v[166:167]
	s_mov_b32 m0, s88
	v_lshl_add_u64 v[230:231], s[40:41], 0, v[164:165]
	global_load_lds_dwordx4 v[4:5], off
	v_lshl_add_u64 v[4:5], s[86:87], 0, v[170:171]
	s_add_i32 m0, s88, 0x2000
	v_lshl_add_u64 v[232:233], s[40:41], 0, v[168:169]
	global_load_lds_dwordx4 v[4:5], off
	s_mov_b32 m0, s42
	s_nop 0
	global_load_lds_dwordx4 v[230:231], off
	s_mov_b32 m0, s43
	s_nop 0
	global_load_lds_dwordx4 v[232:233], off
	s_waitcnt vmcnt(8)
	s_waitcnt lgkmcnt(0)
	s_barrier
; #define PG8_STAGE(bufoff, gbase, voff) do { _Pragma("unroll") for (int _i = 0; _i < 2; ++_i) \
;         __builtin_amdgcn_global_load_lds((const unsigned*)((const char*)(gbase) + (voff)[_i]), (PG8_LAS unsigned*)(lds + (bufoff) + ldsw + _i * 8192), 16, 0, 0); } while (0)
; #define PG8_LDA(dst, b, h) do { _Pragma("unroll") for (int m = 0; m < 4; ++m) _Pragma("unroll") for (int k = 0; k < 2; ++k) dst[m][k] = *(const PG8_LAS bf16x8*)(lds + PG8_SA(b, h) + aoff + m * 2048 + k * 1024); } while (0)
; #define PG8_LDB(dst, b, h) do { _Pragma("unroll") for (int n = 0; n < 2; ++n) _Pragma("unroll") for (int k = 0; k < 2; ++k) dst[n][k] = *(const PG8_LAS bf16x8*)(lds + PG8_SB(b, h) + boff + n * 2048 + k * 1024); } while (0)
; #define PG8_MMA(ai, bj, At, Bt) do { __builtin_amdgcn_s_setprio(3); _Pragma("unroll") for (int m = 0; m < 4; ++m) _Pragma("unroll") for (int n = 0; n < 2; ++n) _Pragma("unroll") for (int k = 0; k < 2; ++k) \
;         acc[ai][bj][m][n] = __builtin_amdgcn_mfma_f32_16x16x32_bf16(Bt[n][k], At[m][k], acc[ai][bj][m][n], 0, 0, 0); __builtin_amdgcn_s_setprio(0); } while (0)
; #define PG8_WAIT_V(n) asm volatile("s_waitcnt vmcnt(" #n ")" ::: "memory")
; #define PG8_WAIT_L(n) asm volatile("s_waitcnt lgkmcnt(" #n ")" ::: "memory")
; #define PG8_BAR __builtin_amdgcn_s_barrier()
; #define PG8_SCHED __builtin_amdgcn_sched_barrier(0)
; template <class Epi, class Sched, bool ALIGN_EPI = false, bool SP2 = false>
; __device__ __forceinline__ void gemm_phase(PG8_LAS unsigned char* lds, const Gemm g, const Sched& S, const Epi& E) {
;     ...
;             PG8_WAIT_V(8); PG8_WAIT_L(0); PG8_BAR; PG8_MMA(1, 0, At, B0); PG8_MMA(1, 1, At, B1); PG8_BAR; PG8_SCHED;
;             PG8_LDB(B0, 1, 0); PG8_LDB(B1, 1, 1); PG8_SCHED; PG8_LDA(At, 1, 0); PG8_STAGE(PG8_SA(0, 1), a2 + hstepA, voffA);
;             PG8_WAIT_V(8); PG8_WAIT_L(0); PG8_BAR; PG8_MMA(0, 0, At, B0); PG8_MMA(0, 1, At, B1); PG8_BAR; PG8_SCHED;
	s_setprio 3
	s_waitcnt lgkmcnt(0)
	v_mfma_f32_16x16x32_bf16 v[66:69], v[134:137], v[194:197], v[66:69]
	v_mfma_f32_16x16x32_bf16 v[66:69], v[138:141], v[198:201], v[66:69]
	v_mfma_f32_16x16x32_bf16 v[62:65], v[146:149], v[198:201], v[62:65]
	v_mfma_f32_16x16x32_bf16 v[62:65], v[142:145], v[194:197], v[62:65]
	v_mfma_f32_16x16x32_bf16 v[46:49], v[142:145], v[202:205], v[46:49]
	v_mfma_f32_16x16x32_bf16 v[46:49], v[146:149], v[206:209], v[46:49]
	v_mfma_f32_16x16x32_bf16 v[50:53], v[138:141], v[206:209], v[50:53]
	v_mfma_f32_16x16x32_bf16 v[50:53], v[134:137], v[202:205], v[50:53]
	v_mfma_f32_16x16x32_bf16 v[34:37], v[134:137], v[210:213], v[34:37]
	v_mfma_f32_16x16x32_bf16 v[34:37], v[138:141], v[214:217], v[34:37]
	v_mfma_f32_16x16x32_bf16 v[30:33], v[146:149], v[214:217], v[30:33]
	v_mfma_f32_16x16x32_bf16 v[30:33], v[142:145], v[210:213], v[30:33]
	v_mfma_f32_16x16x32_bf16 v[14:17], v[142:145], v[218:221], v[14:17]
	v_mfma_f32_16x16x32_bf16 v[14:17], v[146:149], v[222:225], v[14:17]
	v_mfma_f32_16x16x32_bf16 v[18:21], v[138:141], v[222:225], v[18:21]
	v_mfma_f32_16x16x32_bf16 v[18:21], v[134:137], v[218:221], v[18:21]
	v_mfma_f32_16x16x32_bf16 v[58:61], v[150:153], v[194:197], v[58:61]
	v_mfma_f32_16x16x32_bf16 v[58:61], v[154:157], v[198:201], v[58:61]
	v_mfma_f32_16x16x32_bf16 v[54:57], v[190:193], v[198:201], v[54:57]
	v_mfma_f32_16x16x32_bf16 v[54:57], v[158:161], v[194:197], v[54:57]
	v_mfma_f32_16x16x32_bf16 v[38:41], v[158:161], v[202:205], v[38:41]
	v_mfma_f32_16x16x32_bf16 v[38:41], v[190:193], v[206:209], v[38:41]
	v_mfma_f32_16x16x32_bf16 v[42:45], v[154:157], v[206:209], v[42:45]
	v_mfma_f32_16x16x32_bf16 v[42:45], v[150:153], v[202:205], v[42:45]
	v_mfma_f32_16x16x32_bf16 v[26:29], v[150:153], v[210:213], v[26:29]
	v_mfma_f32_16x16x32_bf16 v[26:29], v[154:157], v[214:217], v[26:29]
	v_mfma_f32_16x16x32_bf16 v[22:25], v[190:193], v[214:217], v[22:25]
	v_mfma_f32_16x16x32_bf16 v[22:25], v[158:161], v[210:213], v[22:25]
	v_mfma_f32_16x16x32_bf16 v[4:7], v[158:161], v[218:221], v[6:9]
	v_mfma_f32_16x16x32_bf16 v[4:7], v[190:193], v[222:225], v[4:7]
	v_mfma_f32_16x16x32_bf16 v[10:13], v[154:157], v[222:225], v[10:13]
	v_mfma_f32_16x16x32_bf16 v[10:13], v[150:153], v[218:221], v[10:13]
	s_setprio 0
	s_barrier
	s_add_i32 s86, 0, 0x18000
	v_add_u32_e32 v3, s86, v186
	s_add_i32 s87, 0, 0x1c000
	ds_read_b128 v[134:137], v3
	ds_read_b128 v[138:141], v3 offset:1024
	ds_read_b128 v[142:145], v3 offset:2048
	ds_read_b128 v[146:149], v3 offset:3072
	v_add_u32_e32 v3, s87, v186
	ds_read_b128 v[150:153], v3
	ds_read_b128 v[154:157], v3 offset:1024
	ds_read_b128 v[158:161], v3 offset:2048
	ds_read_b128 v[190:193], v3 offset:3072
	s_add_u32 s40, s40, 0x100000
	s_addc_u32 s41, s41, 0
	s_mov_b32 m0, s44
	v_lshl_add_u64 v[8:9], s[40:41], 0, v[164:165]
	ds_read_b128 v[194:197], v188 offset:32768
	ds_read_b128 v[198:201], v188 offset:33792
	ds_read_b128 v[202:205], v188 offset:34816
	ds_read_b128 v[206:209], v188 offset:35840
	ds_read_b128 v[210:213], v188 offset:36864
	ds_read_b128 v[214:217], v188 offset:37888
	ds_read_b128 v[218:221], v188 offset:38912
	ds_read_b128 v[222:225], v188 offset:39936
	global_load_lds_dwordx4 v[8:9], off
	v_lshl_add_u64 v[8:9], s[40:41], 0, v[168:169]
	s_mov_b32 m0, s45
	s_nop 0
	global_load_lds_dwordx4 v[8:9], off
	s_waitcnt vmcnt(8)
	s_waitcnt lgkmcnt(0)
	s_barrier
	s_setprio 3
	s_waitcnt lgkmcnt(0)
	v_mfma_f32_16x16x32_bf16 v[130:133], v[134:137], v[194:197], v[130:133]
	v_mfma_f32_16x16x32_bf16 v[130:133], v[138:141], v[198:201], v[130:133]
	v_mfma_f32_16x16x32_bf16 v[126:129], v[146:149], v[198:201], v[126:129]
	v_mfma_f32_16x16x32_bf16 v[126:129], v[142:145], v[194:197], v[126:129]
	v_mfma_f32_16x16x32_bf16 v[110:113], v[142:145], v[202:205], v[110:113]
	v_mfma_f32_16x16x32_bf16 v[110:113], v[146:149], v[206:209], v[110:113]
	v_mfma_f32_16x16x32_bf16 v[114:117], v[138:141], v[206:209], v[114:117]
	v_mfma_f32_16x16x32_bf16 v[114:117], v[134:137], v[202:205], v[114:117]
	v_mfma_f32_16x16x32_bf16 v[98:101], v[134:137], v[210:213], v[98:101]
	v_mfma_f32_16x16x32_bf16 v[98:101], v[138:141], v[214:217], v[98:101]
	v_mfma_f32_16x16x32_bf16 v[94:97], v[146:149], v[214:217], v[94:97]
	v_mfma_f32_16x16x32_bf16 v[94:97], v[142:145], v[210:213], v[94:97]
	v_mfma_f32_16x16x32_bf16 v[78:81], v[142:145], v[218:221], v[78:81]
	v_mfma_f32_16x16x32_bf16 v[78:81], v[146:149], v[222:225], v[78:81]
	v_mfma_f32_16x16x32_bf16 v[82:85], v[138:141], v[222:225], v[82:85]
	v_mfma_f32_16x16x32_bf16 v[82:85], v[134:137], v[218:221], v[82:85]
	v_mfma_f32_16x16x32_bf16 v[122:125], v[150:153], v[194:197], v[122:125]
	v_mfma_f32_16x16x32_bf16 v[122:125], v[154:157], v[198:201], v[122:125]
	v_mfma_f32_16x16x32_bf16 v[118:121], v[190:193], v[198:201], v[118:121]
	v_mfma_f32_16x16x32_bf16 v[118:121], v[158:161], v[194:197], v[118:121]
	v_mfma_f32_16x16x32_bf16 v[102:105], v[158:161], v[202:205], v[102:105]
	v_mfma_f32_16x16x32_bf16 v[102:105], v[190:193], v[206:209], v[102:105]
	v_mfma_f32_16x16x32_bf16 v[106:109], v[154:157], v[206:209], v[106:109]
	v_mfma_f32_16x16x32_bf16 v[106:109], v[150:153], v[202:205], v[106:109]
	v_mfma_f32_16x16x32_bf16 v[90:93], v[150:153], v[210:213], v[90:93]
	v_mfma_f32_16x16x32_bf16 v[90:93], v[154:157], v[214:217], v[90:93]
	v_mfma_f32_16x16x32_bf16 v[86:89], v[190:193], v[214:217], v[86:89]
	v_mfma_f32_16x16x32_bf16 v[86:89], v[158:161], v[210:213], v[86:89]
	v_mfma_f32_16x16x32_bf16 v[70:73], v[158:161], v[218:221], v[70:73]
	v_mfma_f32_16x16x32_bf16 v[70:73], v[190:193], v[222:225], v[70:73]
	v_mfma_f32_16x16x32_bf16 v[74:77], v[154:157], v[222:225], v[74:77]
	v_mfma_f32_16x16x32_bf16 v[74:77], v[150:153], v[218:221], v[74:77]
	s_setprio 0
	s_barrier
; #define PG8_STAGE(bufoff, gbase, voff) do { _Pragma("unroll") for (int _i = 0; _i < 2; ++_i) \
;         __builtin_amdgcn_global_load_lds((const unsigned*)((const char*)(gbase) + (voff)[_i]), (PG8_LAS unsigned*)(lds + (bufoff) + ldsw + _i * 8192), 16, 0, 0); } while (0)
; #define PG8_LDA(dst, b, h) do { _Pragma("unroll") for (int m = 0; m < 4; ++m) _Pragma("unroll") for (int k = 0; k < 2; ++k) dst[m][k] = *(const PG8_LAS bf16x8*)(lds + PG8_SA(b, h) + aoff + m * 2048 + k * 1024); } while (0)
; #define PG8_MMA(ai, bj, At, Bt) do { __builtin_amdgcn_s_setprio(3); _Pragma("unroll") for (int m = 0; m < 4; ++m) _Pragma("unroll") for (int n = 0; n < 2; ++n) _Pragma("unroll") for (int k = 0; k < 2; ++k) \
;         acc[ai][bj][m][n] = __builtin_amdgcn_mfma_f32_16x16x32_bf16(Bt[n][k], At[m][k], acc[ai][bj][m][n], 0, 0, 0); __builtin_amdgcn_s_setprio(0); } while (0)
; #define PG8_WAIT_V(n) asm volatile("s_waitcnt vmcnt(" #n ")" ::: "memory")
; #define PG8_WAIT_L(n) asm volatile("s_waitcnt lgkmcnt(" #n ")" ::: "memory")
; #define PG8_BAR __builtin_amdgcn_s_barrier()
; #define PG8_SCHED __builtin_amdgcn_sched_barrier(0)
; template <class Epi, class Sched, bool ALIGN_EPI = false, bool SP2 = false>
; __device__ __forceinline__ void gemm_phase(PG8_LAS unsigned char* lds, const Gemm g, const Sched& S, const Epi& E) {
;     ...
;             PG8_LDA(At, 1, 1); PG8_STAGE(PG8_SB(1, 0), b3, voffB); PG8_STAGE(PG8_SB(1, 1), b3 + hstepB, voffB); PG8_STAGE(PG8_SA(1, 0), a3, voffA);
;             PG8_WAIT_V(8); PG8_WAIT_L(0); PG8_BAR; PG8_MMA(1, 0, At, B0); PG8_MMA(1, 1, At, B1); PG8_BAR; PG8_SCHED;
	s_add_i32 s40, s86, s33
	v_lshl_add_u64 v[8:9], v[226:227], 0, s[10:11]
	s_mov_b32 m0, s40
	ds_read_b128 v[194:197], v188 offset:49152
	ds_read_b128 v[198:201], v188 offset:50176
	ds_read_b128 v[202:205], v188 offset:51200
	ds_read_b128 v[206:209], v188 offset:52224
	ds_read_b128 v[210:213], v188 offset:53248
	ds_read_b128 v[214:217], v188 offset:54272
	ds_read_b128 v[218:221], v188 offset:55296
	ds_read_b128 v[222:225], v188 offset:56320
	global_load_lds_dwordx4 v[8:9], off
	s_add_i32 m0, s40, 0x2000
	s_add_u32 s36, s36, 0x100080
	v_lshl_add_u64 v[8:9], v[228:229], 0, s[10:11]
	s_addc_u32 s37, s37, 0
	s_add_i32 s40, s87, s33
	global_load_lds_dwordx4 v[8:9], off
	v_lshl_add_u64 v[8:9], s[36:37], 0, v[166:167]
	s_mov_b32 m0, s40
	s_nop 0
	global_load_lds_dwordx4 v[8:9], off
	v_lshl_add_u64 v[8:9], s[36:37], 0, v[170:171]
	s_add_i32 m0, s40, 0x2000
	s_nop 0
	global_load_lds_dwordx4 v[8:9], off
	v_lshl_add_u64 v[8:9], v[230:231], 0, s[10:11]
	s_mov_b32 m0, s60
	s_nop 0
	global_load_lds_dwordx4 v[8:9], off
	v_lshl_add_u64 v[8:9], v[232:233], 0, s[10:11]
	s_mov_b32 m0, s61
	s_nop 0
	global_load_lds_dwordx4 v[8:9], off
	s_waitcnt vmcnt(8)
	s_waitcnt lgkmcnt(0)
	s_barrier
	s_setprio 3
	s_waitcnt lgkmcnt(0)
	v_mfma_f32_16x16x32_bf16 v[66:69], v[134:137], v[194:197], v[66:69]
	v_mfma_f32_16x16x32_bf16 v[66:69], v[138:141], v[198:201], v[66:69]
	v_mfma_f32_16x16x32_bf16 v[62:65], v[146:149], v[198:201], v[62:65]
	v_mfma_f32_16x16x32_bf16 v[62:65], v[142:145], v[194:197], v[62:65]
	v_mfma_f32_16x16x32_bf16 v[46:49], v[142:145], v[202:205], v[46:49]
	v_mfma_f32_16x16x32_bf16 v[46:49], v[146:149], v[206:209], v[46:49]
	v_mfma_f32_16x16x32_bf16 v[50:53], v[138:141], v[206:209], v[50:53]
	v_mfma_f32_16x16x32_bf16 v[50:53], v[134:137], v[202:205], v[50:53]
	v_mfma_f32_16x16x32_bf16 v[34:37], v[134:137], v[210:213], v[34:37]
	v_mfma_f32_16x16x32_bf16 v[34:37], v[138:141], v[214:217], v[34:37]
	v_mfma_f32_16x16x32_bf16 v[30:33], v[146:149], v[214:217], v[30:33]
	v_mfma_f32_16x16x32_bf16 v[30:33], v[142:145], v[210:213], v[30:33]
	v_mfma_f32_16x16x32_bf16 v[14:17], v[142:145], v[218:221], v[14:17]
	v_mfma_f32_16x16x32_bf16 v[14:17], v[146:149], v[222:225], v[14:17]
	v_mfma_f32_16x16x32_bf16 v[18:21], v[138:141], v[222:225], v[18:21]
	v_mfma_f32_16x16x32_bf16 v[18:21], v[134:137], v[218:221], v[18:21]
	v_mfma_f32_16x16x32_bf16 v[58:61], v[150:153], v[194:197], v[58:61]
	v_mfma_f32_16x16x32_bf16 v[54:57], v[158:161], v[194:197], v[54:57]
	v_mfma_f32_16x16x32_bf16 v[42:45], v[150:153], v[202:205], v[42:45]
	v_mfma_f32_16x16x32_bf16 v[38:41], v[158:161], v[202:205], v[38:41]
	v_mfma_f32_16x16x32_bf16 v[26:29], v[150:153], v[210:213], v[26:29]
	v_mfma_f32_16x16x32_bf16 v[22:25], v[158:161], v[210:213], v[22:25]
	v_mfma_f32_16x16x32_bf16 v[8:11], v[150:153], v[218:221], v[10:13]
	v_mfma_f32_16x16x32_bf16 v[4:7], v[158:161], v[218:221], v[4:7]
	v_mfma_f32_16x16x32_bf16 v[58:61], v[154:157], v[198:201], v[58:61]
	v_mfma_f32_16x16x32_bf16 v[54:57], v[190:193], v[198:201], v[54:57]
	v_mfma_f32_16x16x32_bf16 v[42:45], v[154:157], v[206:209], v[42:45]
	v_mfma_f32_16x16x32_bf16 v[38:41], v[190:193], v[206:209], v[38:41]
	v_mfma_f32_16x16x32_bf16 v[26:29], v[154:157], v[214:217], v[26:29]
	v_mfma_f32_16x16x32_bf16 v[22:25], v[190:193], v[214:217], v[22:25]
	v_mfma_f32_16x16x32_bf16 v[10:13], v[154:157], v[222:225], v[8:11]
	v_mfma_f32_16x16x32_bf16 v[6:9], v[190:193], v[222:225], v[4:7]
	s_setprio 0
	s_barrier
	s_add_i32 s85, s85, 2
	s_add_u32 s30, s30, 0x100
	s_addc_u32 s31, s31, 0
	s_cmp_gt_u32 s85, 61
	s_cbranch_scc1 .LBB0_811

; #define PG8_STAGE(bufoff, gbase, voff) do { _Pragma("unroll") for (int _i = 0; _i < 2; ++_i) \
;         __builtin_amdgcn_global_load_lds((const unsigned*)((const char*)(gbase) + (voff)[_i]), (PG8_LAS unsigned*)(lds + (bufoff) + ldsw + _i * 8192), 16, 0, 0); } while (0)
; #define PG8_LDA(dst, b, h) do { _Pragma("unroll") for (int m = 0; m < 4; ++m) _Pragma("unroll") for (int k = 0; k < 2; ++k) dst[m][k] = *(const PG8_LAS bf16x8*)(lds + PG8_SA(b, h) + aoff + m * 2048 + k * 1024); } while (0)
; #define PG8_LDB(dst, b, h) do { _Pragma("unroll") for (int n = 0; n < 2; ++n) _Pragma("unroll") for (int k = 0; k < 2; ++k) dst[n][k] = *(const PG8_LAS bf16x8*)(lds + PG8_SB(b, h) + boff + n * 2048 + k * 1024); } while (0)
; #define PG8_MMA(ai, bj, At, Bt) do { __builtin_amdgcn_s_setprio(3); _Pragma("unroll") for (int m = 0; m < 4; ++m) _Pragma("unroll") for (int n = 0; n < 2; ++n) _Pragma("unroll") for (int k = 0; k < 2; ++k) \
;         acc[ai][bj][m][n] = __builtin_amdgcn_mfma_f32_16x16x32_bf16(Bt[n][k], At[m][k], acc[ai][bj][m][n], 0, 0, 0); __builtin_amdgcn_s_setprio(0); } while (0)
; #define PG8_WAIT_V(n) asm volatile("s_waitcnt vmcnt(" #n ")" ::: "memory")
; template <class Epi, class Sched, bool ALIGN_EPI = false, bool SP2 = false>
; __device__ __forceinline__ void gemm_phase(PG8_LAS unsigned char* lds, const Gemm g, const Sched& S, const Epi& E) {
;     ...
;             const bool last = (t == nt - 2);
;             const char* a1 = cA + (size_t)(t + 1) * kstep;
;             const char* a2 = last ? nA : cA + (size_t)(t + 2) * kstep; const char* b2 = last ? nB : cB + (size_t)(t + 2) * kstep;
;             const char* a3 = a2 + kstep; const char* b3 = b2 + kstep;
;             if (last && has_next) S.a_ready(nxt);
;             if constexpr (Epi::MIDK) { if (t == E.midk_step(nt)) E.midk(acc, cur, wr, wc, fr, fq); }
;             if constexpr (SP2) {
;             PG8_LDB(B0, 0, 0); PG8_LDB(B1, 0, 1); PG8_SCHED; PG8_LDA(At, 0, 0); PG8_STAGE(PG8_SA(1, 1), a1 + hstepA, voffA);
;             PG8_WAIT_V(8); PG8_WAIT_L(0); PG8_BAR; PG8_MMA(0, 0, At, B0); PG8_MMA(0, 1, At, B1); PG8_BAR; PG8_SCHED;
;             PG8_LDA(At, 0, 1); PG8_STAGE(PG8_SB(0, 0), b2, voffB); PG8_STAGE(PG8_SB(0, 1), b2 + hstepB, voffB); PG8_STAGE(PG8_SA(0, 0), a2, voffA);
;             PG8_WAIT_V(8); PG8_WAIT_L(0); PG8_BAR; PG8_MMA(1, 0, At, B0); PG8_MMA(1, 1, At, B1); PG8_BAR; PG8_SCHED;
.LBB0_908:
	ds_read_b128 v[158:161], v155
	ds_read_b128 v[164:167], v155 offset:1024
	ds_read_b128 v[168:171], v155 offset:2048
	ds_read_b128 v[172:175], v155 offset:3072
	ds_read_b128 v[176:179], v156
	ds_read_b128 v[180:183], v156 offset:1024
	ds_read_b128 v[184:187], v156 offset:2048
	ds_read_b128 v[188:191], v156 offset:3072
	s_add_u32 s26, s24, 0xfff00080
	s_addc_u32 s27, s25, -1
	s_cmp_eq_u32 s55, 60
	s_cselect_b32 s29, s17, s27
	s_cselect_b32 s28, s47, s26
	s_cselect_b32 s27, s15, s54
	s_cselect_b32 s26, s52, s53
	v_lshl_add_u64 v[146:147], s[24:25], 0, v[138:139]
	s_add_i32 m0, s23, 0xc000
	ds_read_b128 v[192:195], v157
	ds_read_b128 v[196:199], v157 offset:1024
	ds_read_b128 v[200:203], v157 offset:2048
	ds_read_b128 v[204:207], v157 offset:3072
	ds_read_b128 v[208:211], v157 offset:4096
	ds_read_b128 v[212:215], v157 offset:5120
	ds_read_b128 v[216:219], v157 offset:6144
	ds_read_b128 v[220:223], v157 offset:7168
	global_load_lds_dwordx4 v[146:147], off
	v_lshl_add_u64 v[146:147], s[24:25], 0, v[140:141]
	s_add_i32 m0, s23, 0xe000
	s_nop 0
	global_load_lds_dwordx4 v[146:147], off
	s_waitcnt vmcnt(8)
	s_waitcnt lgkmcnt(0)
	s_barrier
	s_setprio 3
	s_waitcnt lgkmcnt(0)
	v_mfma_f32_16x16x32_bf16 v[126:129], v[158:161], v[192:195], v[126:129]
	v_mfma_f32_16x16x32_bf16 v[126:129], v[164:167], v[196:199], v[126:129]
	v_mfma_f32_16x16x32_bf16 v[122:125], v[172:175], v[196:199], v[122:125]
	v_mfma_f32_16x16x32_bf16 v[122:125], v[168:171], v[192:195], v[122:125]
	v_mfma_f32_16x16x32_bf16 v[106:109], v[168:171], v[200:203], v[106:109]
	v_mfma_f32_16x16x32_bf16 v[106:109], v[172:175], v[204:207], v[106:109]
	v_mfma_f32_16x16x32_bf16 v[114:117], v[164:167], v[204:207], v[114:117]
	v_mfma_f32_16x16x32_bf16 v[114:117], v[158:161], v[200:203], v[114:117]
	v_mfma_f32_16x16x32_bf16 v[98:101], v[158:161], v[208:211], v[98:101]
	v_mfma_f32_16x16x32_bf16 v[98:101], v[164:167], v[212:215], v[98:101]
	v_mfma_f32_16x16x32_bf16 v[90:93], v[172:175], v[212:215], v[90:93]
	v_mfma_f32_16x16x32_bf16 v[90:93], v[168:171], v[208:211], v[90:93]
	v_mfma_f32_16x16x32_bf16 v[74:77], v[168:171], v[216:219], v[74:77]
	v_mfma_f32_16x16x32_bf16 v[74:77], v[172:175], v[220:223], v[74:77]
	v_mfma_f32_16x16x32_bf16 v[82:85], v[164:167], v[220:223], v[82:85]
	v_mfma_f32_16x16x32_bf16 v[82:85], v[158:161], v[216:219], v[82:85]
	v_mfma_f32_16x16x32_bf16 v[118:121], v[176:179], v[192:195], v[118:121]
	v_mfma_f32_16x16x32_bf16 v[118:121], v[180:183], v[196:199], v[118:121]
	v_mfma_f32_16x16x32_bf16 v[110:113], v[188:191], v[196:199], v[110:113]
	v_mfma_f32_16x16x32_bf16 v[110:113], v[184:187], v[192:195], v[110:113]
	v_mfma_f32_16x16x32_bf16 v[94:97], v[184:187], v[200:203], v[94:97]
	v_mfma_f32_16x16x32_bf16 v[94:97], v[188:191], v[204:207], v[94:97]
	v_mfma_f32_16x16x32_bf16 v[102:105], v[180:183], v[204:207], v[102:105]
	v_mfma_f32_16x16x32_bf16 v[102:105], v[176:179], v[200:203], v[102:105]
	v_mfma_f32_16x16x32_bf16 v[86:89], v[176:179], v[208:211], v[86:89]
	v_mfma_f32_16x16x32_bf16 v[86:89], v[180:183], v[212:215], v[86:89]
	v_mfma_f32_16x16x32_bf16 v[78:81], v[188:191], v[212:215], v[78:81]
	v_mfma_f32_16x16x32_bf16 v[78:81], v[184:187], v[208:211], v[78:81]
	v_mfma_f32_16x16x32_bf16 v[66:69], v[184:187], v[216:219], v[66:69]
	v_mfma_f32_16x16x32_bf16 v[66:69], v[188:191], v[220:223], v[66:69]
	v_mfma_f32_16x16x32_bf16 v[70:73], v[180:183], v[220:223], v[70:73]
	v_mfma_f32_16x16x32_bf16 v[70:73], v[176:179], v[216:219], v[70:73]
	s_setprio 0
	s_barrier
	s_add_i32 s56, s42, s30
	v_lshl_add_u64 v[146:147], s[26:27], 0, v[134:135]
	s_mov_b32 m0, s56
	ds_read_b128 v[192:195], v157 offset:16384
	ds_read_b128 v[196:199], v157 offset:17408
	ds_read_b128 v[200:203], v157 offset:18432
	ds_read_b128 v[204:207], v157 offset:19456
	ds_read_b128 v[208:211], v157 offset:20480
	ds_read_b128 v[212:215], v157 offset:21504
	ds_read_b128 v[216:219], v157 offset:22528
	ds_read_b128 v[220:223], v157 offset:23552
	global_load_lds_dwordx4 v[146:147], off
	s_add_i32 m0, s56, 0x2000
	s_add_u32 s56, s26, 0x100000
	v_lshl_add_u64 v[224:225], s[26:27], 0, v[130:131]
	s_addc_u32 s57, s27, 0
	s_add_i32 s58, s43, s30
	global_load_lds_dwordx4 v[224:225], off
	v_lshl_add_u64 v[226:227], s[56:57], 0, v[134:135]
	s_mov_b32 m0, s58
	v_lshl_add_u64 v[228:229], s[28:29], 0, v[132:133]
	global_load_lds_dwordx4 v[226:227], off
	v_lshl_add_u64 v[226:227], s[56:57], 0, v[130:131]
	s_add_i32 m0, s58, 0x2000
	s_nop 0
	global_load_lds_dwordx4 v[226:227], off
	v_lshl_add_u64 v[226:227], s[28:29], 0, v[136:137]
	s_mov_b32 m0, s23
	s_nop 0
	global_load_lds_dwordx4 v[226:227], off
	s_mov_b32 m0, s33
	s_nop 0
	global_load_lds_dwordx4 v[228:229], off
	s_waitcnt vmcnt(8)
	s_waitcnt lgkmcnt(0)
	s_barrier
; #define PG8_STAGE(bufoff, gbase, voff) do { _Pragma("unroll") for (int _i = 0; _i < 2; ++_i) \
;         __builtin_amdgcn_global_load_lds((const unsigned*)((const char*)(gbase) + (voff)[_i]), (PG8_LAS unsigned*)(lds + (bufoff) + ldsw + _i * 8192), 16, 0, 0); } while (0)
; #define PG8_LDA(dst, b, h) do { _Pragma("unroll") for (int m = 0; m < 4; ++m) _Pragma("unroll") for (int k = 0; k < 2; ++k) dst[m][k] = *(const PG8_LAS bf16x8*)(lds + PG8_SA(b, h) + aoff + m * 2048 + k * 1024); } while (0)
; #define PG8_LDB(dst, b, h) do { _Pragma("unroll") for (int n = 0; n < 2; ++n) _Pragma("unroll") for (int k = 0; k < 2; ++k) dst[n][k] = *(const PG8_LAS bf16x8*)(lds + PG8_SB(b, h) + boff + n * 2048 + k * 1024); } while (0)
; #define PG8_MMA(ai, bj, At, Bt) do { __builtin_amdgcn_s_setprio(3); _Pragma("unroll") for (int m = 0; m < 4; ++m) _Pragma("unroll") for (int n = 0; n < 2; ++n) _Pragma("unroll") for (int k = 0; k < 2; ++k) \
;         acc[ai][bj][m][n] = __builtin_amdgcn_mfma_f32_16x16x32_bf16(Bt[n][k], At[m][k], acc[ai][bj][m][n], 0, 0, 0); __builtin_amdgcn_s_setprio(0); } while (0)
; #define PG8_WAIT_V(n) asm volatile("s_waitcnt vmcnt(" #n ")" ::: "memory")
; #define PG8_WAIT_L(n) asm volatile("s_waitcnt lgkmcnt(" #n ")" ::: "memory")
; #define PG8_BAR __builtin_amdgcn_s_barrier()
; #define PG8_SCHED __builtin_amdgcn_sched_barrier(0)
; template <class Epi, class Sched, bool ALIGN_EPI = false, bool SP2 = false>
; __device__ __forceinline__ void gemm_phase(PG8_LAS unsigned char* lds, const Gemm g, const Sched& S, const Epi& E) {
;     ...
;             PG8_WAIT_V(8); PG8_WAIT_L(0); PG8_BAR; PG8_MMA(1, 0, At, B0); PG8_MMA(1, 1, At, B1); PG8_BAR; PG8_SCHED;
;             PG8_LDB(B0, 1, 0); PG8_LDB(B1, 1, 1); PG8_SCHED; PG8_LDA(At, 1, 0); PG8_STAGE(PG8_SA(0, 1), a2 + hstepA, voffA);
;             PG8_WAIT_V(8); PG8_WAIT_L(0); PG8_BAR; PG8_MMA(0, 0, At, B0); PG8_MMA(0, 1, At, B1); PG8_BAR; PG8_SCHED;
	s_setprio 3
	s_waitcnt lgkmcnt(0)
	v_mfma_f32_16x16x32_bf16 v[62:65], v[158:161], v[192:195], v[62:65]
	v_mfma_f32_16x16x32_bf16 v[62:65], v[164:167], v[196:199], v[62:65]
	v_mfma_f32_16x16x32_bf16 v[58:61], v[172:175], v[196:199], v[58:61]
	v_mfma_f32_16x16x32_bf16 v[58:61], v[168:171], v[192:195], v[58:61]
	v_mfma_f32_16x16x32_bf16 v[42:45], v[168:171], v[200:203], v[42:45]
	v_mfma_f32_16x16x32_bf16 v[42:45], v[172:175], v[204:207], v[42:45]
	v_mfma_f32_16x16x32_bf16 v[50:53], v[164:167], v[204:207], v[50:53]
	v_mfma_f32_16x16x32_bf16 v[50:53], v[158:161], v[200:203], v[50:53]
	v_mfma_f32_16x16x32_bf16 v[34:37], v[158:161], v[208:211], v[34:37]
	v_mfma_f32_16x16x32_bf16 v[34:37], v[164:167], v[212:215], v[34:37]
	v_mfma_f32_16x16x32_bf16 v[26:29], v[172:175], v[212:215], v[26:29]
	v_mfma_f32_16x16x32_bf16 v[26:29], v[168:171], v[208:211], v[26:29]
	v_mfma_f32_16x16x32_bf16 v[10:13], v[168:171], v[216:219], v[10:13]
	v_mfma_f32_16x16x32_bf16 v[10:13], v[172:175], v[220:223], v[10:13]
	v_mfma_f32_16x16x32_bf16 v[14:17], v[164:167], v[220:223], v[14:17]
	v_mfma_f32_16x16x32_bf16 v[14:17], v[158:161], v[216:219], v[14:17]
	v_mfma_f32_16x16x32_bf16 v[54:57], v[176:179], v[192:195], v[54:57]
	v_mfma_f32_16x16x32_bf16 v[54:57], v[180:183], v[196:199], v[54:57]
	v_mfma_f32_16x16x32_bf16 v[46:49], v[188:191], v[196:199], v[46:49]
	v_mfma_f32_16x16x32_bf16 v[46:49], v[184:187], v[192:195], v[46:49]
	v_mfma_f32_16x16x32_bf16 v[30:33], v[184:187], v[200:203], v[30:33]
	v_mfma_f32_16x16x32_bf16 v[30:33], v[188:191], v[204:207], v[30:33]
	v_mfma_f32_16x16x32_bf16 v[38:41], v[180:183], v[204:207], v[38:41]
	v_mfma_f32_16x16x32_bf16 v[38:41], v[176:179], v[200:203], v[38:41]
	v_mfma_f32_16x16x32_bf16 v[22:25], v[176:179], v[208:211], v[22:25]
	v_mfma_f32_16x16x32_bf16 v[22:25], v[180:183], v[212:215], v[22:25]
	v_mfma_f32_16x16x32_bf16 v[18:21], v[188:191], v[212:215], v[18:21]
	v_mfma_f32_16x16x32_bf16 v[18:21], v[184:187], v[208:211], v[18:21]
	v_mfma_f32_16x16x32_bf16 v[2:5], v[184:187], v[216:219], v[2:5]
	v_mfma_f32_16x16x32_bf16 v[2:5], v[188:191], v[220:223], v[2:5]
	v_mfma_f32_16x16x32_bf16 v[6:9], v[180:183], v[220:223], v[6:9]
	v_mfma_f32_16x16x32_bf16 v[6:9], v[176:179], v[216:219], v[6:9]
	s_setprio 0
	s_barrier
	s_add_i32 s56, 0, 0x18000
	v_add_u32_e32 v148, s56, v151
	s_add_i32 s57, 0, 0x1c000
	ds_read_b128 v[158:161], v148
	ds_read_b128 v[164:167], v148 offset:1024
	ds_read_b128 v[168:171], v148 offset:2048
	ds_read_b128 v[172:175], v148 offset:3072
	v_add_u32_e32 v148, s57, v151
	ds_read_b128 v[176:179], v148
	ds_read_b128 v[180:183], v148 offset:1024
	ds_read_b128 v[184:187], v148 offset:2048
	ds_read_b128 v[188:191], v148 offset:3072
	s_add_u32 s28, s28, 0x100000
	s_addc_u32 s29, s29, 0
	s_mov_b32 m0, s36
	v_lshl_add_u64 v[230:231], s[28:29], 0, v[136:137]
	ds_read_b128 v[192:195], v157 offset:32768
	ds_read_b128 v[196:199], v157 offset:33792
	ds_read_b128 v[200:203], v157 offset:34816
	ds_read_b128 v[204:207], v157 offset:35840
	ds_read_b128 v[208:211], v157 offset:36864
	ds_read_b128 v[212:215], v157 offset:37888
	ds_read_b128 v[216:219], v157 offset:38912
	ds_read_b128 v[220:223], v157 offset:39936
	global_load_lds_dwordx4 v[230:231], off
	v_lshl_add_u64 v[230:231], s[28:29], 0, v[132:133]
	s_mov_b32 m0, s37
	s_nop 0
	global_load_lds_dwordx4 v[230:231], off
	s_waitcnt vmcnt(8)
	s_waitcnt lgkmcnt(0)
	s_barrier
	s_setprio 3
	s_waitcnt lgkmcnt(0)
	v_mfma_f32_16x16x32_bf16 v[126:129], v[158:161], v[192:195], v[126:129]
	v_mfma_f32_16x16x32_bf16 v[126:129], v[164:167], v[196:199], v[126:129]
	v_mfma_f32_16x16x32_bf16 v[122:125], v[172:175], v[196:199], v[122:125]
	v_mfma_f32_16x16x32_bf16 v[122:125], v[168:171], v[192:195], v[122:125]
	v_mfma_f32_16x16x32_bf16 v[106:109], v[168:171], v[200:203], v[106:109]
	v_mfma_f32_16x16x32_bf16 v[106:109], v[172:175], v[204:207], v[106:109]
	v_mfma_f32_16x16x32_bf16 v[114:117], v[164:167], v[204:207], v[114:117]
	v_mfma_f32_16x16x32_bf16 v[114:117], v[158:161], v[200:203], v[114:117]
	v_mfma_f32_16x16x32_bf16 v[98:101], v[158:161], v[208:211], v[98:101]
	v_mfma_f32_16x16x32_bf16 v[98:101], v[164:167], v[212:215], v[98:101]
	v_mfma_f32_16x16x32_bf16 v[90:93], v[172:175], v[212:215], v[90:93]
	v_mfma_f32_16x16x32_bf16 v[90:93], v[168:171], v[208:211], v[90:93]
	v_mfma_f32_16x16x32_bf16 v[74:77], v[168:171], v[216:219], v[74:77]
	v_mfma_f32_16x16x32_bf16 v[74:77], v[172:175], v[220:223], v[74:77]
	v_mfma_f32_16x16x32_bf16 v[82:85], v[164:167], v[220:223], v[82:85]
	v_mfma_f32_16x16x32_bf16 v[82:85], v[158:161], v[216:219], v[82:85]
	v_mfma_f32_16x16x32_bf16 v[118:121], v[176:179], v[192:195], v[118:121]
	v_mfma_f32_16x16x32_bf16 v[118:121], v[180:183], v[196:199], v[118:121]
	v_mfma_f32_16x16x32_bf16 v[110:113], v[188:191], v[196:199], v[110:113]
	v_mfma_f32_16x16x32_bf16 v[110:113], v[184:187], v[192:195], v[110:113]
	v_mfma_f32_16x16x32_bf16 v[94:97], v[184:187], v[200:203], v[94:97]
	v_mfma_f32_16x16x32_bf16 v[94:97], v[188:191], v[204:207], v[94:97]
	v_mfma_f32_16x16x32_bf16 v[102:105], v[180:183], v[204:207], v[102:105]
	v_mfma_f32_16x16x32_bf16 v[102:105], v[176:179], v[200:203], v[102:105]
	v_mfma_f32_16x16x32_bf16 v[86:89], v[176:179], v[208:211], v[86:89]
	v_mfma_f32_16x16x32_bf16 v[86:89], v[180:183], v[212:215], v[86:89]
	v_mfma_f32_16x16x32_bf16 v[78:81], v[188:191], v[212:215], v[78:81]
	v_mfma_f32_16x16x32_bf16 v[78:81], v[184:187], v[208:211], v[78:81]
	v_mfma_f32_16x16x32_bf16 v[66:69], v[184:187], v[216:219], v[66:69]
	v_mfma_f32_16x16x32_bf16 v[66:69], v[188:191], v[220:223], v[66:69]
	v_mfma_f32_16x16x32_bf16 v[70:73], v[180:183], v[220:223], v[70:73]
	v_mfma_f32_16x16x32_bf16 v[70:73], v[176:179], v[216:219], v[70:73]
	s_setprio 0
	s_barrier
; #define PG8_STAGE(bufoff, gbase, voff) do { _Pragma("unroll") for (int _i = 0; _i < 2; ++_i) \
;         __builtin_amdgcn_global_load_lds((const unsigned*)((const char*)(gbase) + (voff)[_i]), (PG8_LAS unsigned*)(lds + (bufoff) + ldsw + _i * 8192), 16, 0, 0); } while (0)
; #define PG8_LDA(dst, b, h) do { _Pragma("unroll") for (int m = 0; m < 4; ++m) _Pragma("unroll") for (int k = 0; k < 2; ++k) dst[m][k] = *(const PG8_LAS bf16x8*)(lds + PG8_SA(b, h) + aoff + m * 2048 + k * 1024); } while (0)
; #define PG8_MMA(ai, bj, At, Bt) do { __builtin_amdgcn_s_setprio(3); _Pragma("unroll") for (int m = 0; m < 4; ++m) _Pragma("unroll") for (int n = 0; n < 2; ++n) _Pragma("unroll") for (int k = 0; k < 2; ++k) \
;         acc[ai][bj][m][n] = __builtin_amdgcn_mfma_f32_16x16x32_bf16(Bt[n][k], At[m][k], acc[ai][bj][m][n], 0, 0, 0); __builtin_amdgcn_s_setprio(0); } while (0)
; #define PG8_WAIT_V(n) asm volatile("s_waitcnt vmcnt(" #n ")" ::: "memory")
; #define PG8_WAIT_L(n) asm volatile("s_waitcnt lgkmcnt(" #n ")" ::: "memory")
; #define PG8_BAR __builtin_amdgcn_s_barrier()
; #define PG8_SCHED __builtin_amdgcn_sched_barrier(0)
; template <class Epi, class Sched, bool ALIGN_EPI = false, bool SP2 = false>
; __device__ __forceinline__ void gemm_phase(PG8_LAS unsigned char* lds, const Gemm g, const Sched& S, const Epi& E) {
;     ...
;             PG8_LDA(At, 1, 1); PG8_STAGE(PG8_SB(1, 0), b3, voffB); PG8_STAGE(PG8_SB(1, 1), b3 + hstepB, voffB); PG8_STAGE(PG8_SA(1, 0), a3, voffA);
;             PG8_WAIT_V(8); PG8_WAIT_L(0); PG8_BAR; PG8_MMA(1, 0, At, B0); PG8_MMA(1, 1, At, B1); PG8_BAR; PG8_SCHED;
	s_add_i32 s28, s56, s30
	v_lshl_add_u64 v[146:147], v[146:147], 0, s[12:13]
	s_mov_b32 m0, s28
	ds_read_b128 v[192:195], v157 offset:49152
	ds_read_b128 v[196:199], v157 offset:50176
	ds_read_b128 v[200:203], v157 offset:51200
	ds_read_b128 v[204:207], v157 offset:52224
	ds_read_b128 v[208:211], v157 offset:53248
	ds_read_b128 v[212:215], v157 offset:54272
	ds_read_b128 v[216:219], v157 offset:55296
	ds_read_b128 v[220:223], v157 offset:56320
	global_load_lds_dwordx4 v[146:147], off
	s_add_i32 m0, s28, 0x2000
	s_add_u32 s26, s26, 0x100080
	v_lshl_add_u64 v[146:147], v[224:225], 0, s[12:13]
	s_addc_u32 s27, s27, 0
	s_add_i32 s28, s57, s30
	global_load_lds_dwordx4 v[146:147], off
	v_lshl_add_u64 v[146:147], s[26:27], 0, v[134:135]
	s_mov_b32 m0, s28
	s_nop 0
	global_load_lds_dwordx4 v[146:147], off
	v_lshl_add_u64 v[146:147], s[26:27], 0, v[130:131]
	s_add_i32 m0, s28, 0x2000
	s_nop 0
	global_load_lds_dwordx4 v[146:147], off
	v_lshl_add_u64 v[146:147], v[226:227], 0, s[12:13]
	s_mov_b32 m0, s39
	s_nop 0
	global_load_lds_dwordx4 v[146:147], off
	v_lshl_add_u64 v[146:147], v[228:229], 0, s[12:13]
	s_mov_b32 m0, s40
	s_nop 0
	global_load_lds_dwordx4 v[146:147], off
	s_waitcnt vmcnt(8)
	s_waitcnt lgkmcnt(0)
	s_barrier
	s_setprio 3
	s_waitcnt lgkmcnt(0)
	v_mfma_f32_16x16x32_bf16 v[62:65], v[158:161], v[192:195], v[62:65]
	v_mfma_f32_16x16x32_bf16 v[62:65], v[164:167], v[196:199], v[62:65]
	v_mfma_f32_16x16x32_bf16 v[58:61], v[172:175], v[196:199], v[58:61]
	v_mfma_f32_16x16x32_bf16 v[58:61], v[168:171], v[192:195], v[58:61]
	v_mfma_f32_16x16x32_bf16 v[42:45], v[168:171], v[200:203], v[42:45]
	v_mfma_f32_16x16x32_bf16 v[42:45], v[172:175], v[204:207], v[42:45]
	v_mfma_f32_16x16x32_bf16 v[50:53], v[164:167], v[204:207], v[50:53]
	v_mfma_f32_16x16x32_bf16 v[50:53], v[158:161], v[200:203], v[50:53]
	v_mfma_f32_16x16x32_bf16 v[34:37], v[158:161], v[208:211], v[34:37]
	v_mfma_f32_16x16x32_bf16 v[34:37], v[164:167], v[212:215], v[34:37]
	v_mfma_f32_16x16x32_bf16 v[26:29], v[172:175], v[212:215], v[26:29]
	v_mfma_f32_16x16x32_bf16 v[26:29], v[168:171], v[208:211], v[26:29]
	v_mfma_f32_16x16x32_bf16 v[10:13], v[168:171], v[216:219], v[10:13]
	v_mfma_f32_16x16x32_bf16 v[10:13], v[172:175], v[220:223], v[10:13]
	v_mfma_f32_16x16x32_bf16 v[14:17], v[164:167], v[220:223], v[14:17]
	v_mfma_f32_16x16x32_bf16 v[14:17], v[158:161], v[216:219], v[14:17]
	v_mfma_f32_16x16x32_bf16 v[54:57], v[176:179], v[192:195], v[54:57]
	v_mfma_f32_16x16x32_bf16 v[54:57], v[180:183], v[196:199], v[54:57]
	v_mfma_f32_16x16x32_bf16 v[46:49], v[188:191], v[196:199], v[46:49]
	v_mfma_f32_16x16x32_bf16 v[46:49], v[184:187], v[192:195], v[46:49]
	v_mfma_f32_16x16x32_bf16 v[30:33], v[184:187], v[200:203], v[30:33]
	v_mfma_f32_16x16x32_bf16 v[30:33], v[188:191], v[204:207], v[30:33]
	v_mfma_f32_16x16x32_bf16 v[38:41], v[180:183], v[204:207], v[38:41]
	v_mfma_f32_16x16x32_bf16 v[38:41], v[176:179], v[200:203], v[38:41]
	v_mfma_f32_16x16x32_bf16 v[22:25], v[176:179], v[208:211], v[22:25]
	v_mfma_f32_16x16x32_bf16 v[22:25], v[180:183], v[212:215], v[22:25]
	v_mfma_f32_16x16x32_bf16 v[18:21], v[188:191], v[212:215], v[18:21]
	v_mfma_f32_16x16x32_bf16 v[18:21], v[184:187], v[208:211], v[18:21]
	v_mfma_f32_16x16x32_bf16 v[2:5], v[184:187], v[216:219], v[2:5]
	v_mfma_f32_16x16x32_bf16 v[2:5], v[188:191], v[220:223], v[2:5]
	v_mfma_f32_16x16x32_bf16 v[6:9], v[180:183], v[220:223], v[6:9]
	v_mfma_f32_16x16x32_bf16 v[6:9], v[176:179], v[216:219], v[6:9]
	s_setprio 0
	s_barrier
	s_add_i32 s55, s55, 2
	s_add_u32 s24, s24, 0x100
	s_addc_u32 s25, s25, 0
	s_add_u32 s53, s53, 0x100
	s_addc_u32 s54, s54, 0
	s_cmp_gt_u32 s55, 61
	s_cbranch_scc0 .LBB0_908
	s_and_b64 vcc, exec, s[0:1]
	s_cbranch_vccz .LBB0_911
	s_barrier

; #define PG8_STAGE(bufoff, gbase, voff) do { _Pragma("unroll") for (int _i = 0; _i < 2; ++_i) \
;         __builtin_amdgcn_global_load_lds((const unsigned*)((const char*)(gbase) + (voff)[_i]), (PG8_LAS unsigned*)(lds + (bufoff) + ldsw + _i * 8192), 16, 0, 0); } while (0)
; #define PG8_LDA(dst, b, h) do { _Pragma("unroll") for (int m = 0; m < 4; ++m) _Pragma("unroll") for (int k = 0; k < 2; ++k) dst[m][k] = *(const PG8_LAS bf16x8*)(lds + PG8_SA(b, h) + aoff + m * 2048 + k * 1024); } while (0)
; #define PG8_LDB(dst, b, h) do { _Pragma("unroll") for (int n = 0; n < 2; ++n) _Pragma("unroll") for (int k = 0; k < 2; ++k) dst[n][k] = *(const PG8_LAS bf16x8*)(lds + PG8_SB(b, h) + boff + n * 2048 + k * 1024); } while (0)
; #define PG8_MMA(ai, bj, At, Bt) do { __builtin_amdgcn_s_setprio(3); _Pragma("unroll") for (int m = 0; m < 4; ++m) _Pragma("unroll") for (int n = 0; n < 2; ++n) _Pragma("unroll") for (int k = 0; k < 2; ++k) \
;         acc[ai][bj][m][n] = __builtin_amdgcn_mfma_f32_16x16x32_bf16(Bt[n][k], At[m][k], acc[ai][bj][m][n], 0, 0, 0); __builtin_amdgcn_s_setprio(0); } while (0)
; #define PG8_WAIT_V(n) asm volatile("s_waitcnt vmcnt(" #n ")" ::: "memory")
; template <class Epi, class Sched, bool ALIGN_EPI = false, bool SP2 = false>
; __device__ __forceinline__ void gemm_phase(PG8_LAS unsigned char* lds, const Gemm g, const Sched& S, const Epi& E) {
;     ...
;             const bool last = (t == nt - 2);
;             const char* a1 = cA + (size_t)(t + 1) * kstep;
;             const char* a2 = last ? nA : cA + (size_t)(t + 2) * kstep; const char* b2 = last ? nB : cB + (size_t)(t + 2) * kstep;
;             const char* a3 = a2 + kstep; const char* b3 = b2 + kstep;
;             if (last && has_next) S.a_ready(nxt);
;             if constexpr (Epi::MIDK) { if (t == E.midk_step(nt)) E.midk(acc, cur, wr, wc, fr, fq); }
;             if constexpr (SP2) {
;             PG8_LDB(B0, 0, 0); PG8_LDB(B1, 0, 1); PG8_SCHED; PG8_LDA(At, 0, 0); PG8_STAGE(PG8_SA(1, 1), a1 + hstepA, voffA);
;             PG8_WAIT_V(8); PG8_WAIT_L(0); PG8_BAR; PG8_MMA(0, 0, At, B0); PG8_MMA(0, 1, At, B1); PG8_BAR; PG8_SCHED;
;             PG8_LDA(At, 0, 1); PG8_STAGE(PG8_SB(0, 0), b2, voffB); PG8_STAGE(PG8_SB(0, 1), b2 + hstepB, voffB); PG8_STAGE(PG8_SA(0, 0), a2, voffA);
;             PG8_WAIT_V(8); PG8_WAIT_L(0); PG8_BAR; PG8_MMA(1, 0, At, B0); PG8_MMA(1, 1, At, B1); PG8_BAR; PG8_SCHED;
.LBB0_975:
	v_add_u32_e32 v144, s46, v206
	v_add_u32_e32 v160, s47, v206
	s_add_u32 s28, s2, s12
	ds_read_b128 v[132:135], v144
	ds_read_b128 v[136:139], v144 offset:1024
	ds_read_b128 v[140:143], v144 offset:2048
	ds_read_b128 v[144:147], v144 offset:3072
	ds_read_b128 v[148:151], v160
	ds_read_b128 v[152:155], v160 offset:1024
	ds_read_b128 v[156:159], v160 offset:2048
	ds_read_b128 v[160:163], v160 offset:3072
	s_addc_u32 s29, s3, s13
	s_add_u32 s28, s28, 0x21500100
	s_addc_u32 s29, s29, 0
	s_add_u32 s81, s44, s12
	s_addc_u32 s82, s45, s13
	s_cmpk_eq_i32 s12, 0x5500
	s_cselect_b32 s31, s1, s29
	s_cselect_b32 s30, s0, s28
	s_cselect_b32 s29, s11, s82
	s_cselect_b32 s28, s10, s81
	s_mov_b32 m0, s71
	v_lshl_add_u64 v[234:235], v[2:3], 0, s[12:13]
	ds_read_b128 v[164:167], v207
	ds_read_b128 v[168:171], v207 offset:1024
	ds_read_b128 v[210:213], v207 offset:2048
	ds_read_b128 v[214:217], v207 offset:3072
	ds_read_b128 v[218:221], v207 offset:4096
	ds_read_b128 v[222:225], v207 offset:5120
	ds_read_b128 v[226:229], v207 offset:6144
	ds_read_b128 v[230:233], v207 offset:7168
	global_load_lds_dwordx4 v[234:235], off
	v_lshl_add_u64 v[234:235], v[200:201], 0, s[12:13]
	s_mov_b32 m0, s72
	s_nop 0
	global_load_lds_dwordx4 v[234:235], off
	s_waitcnt vmcnt(8)
	s_waitcnt lgkmcnt(0)
	s_barrier
	s_setprio 3
	s_waitcnt lgkmcnt(0)
	v_mfma_f32_16x16x32_bf16 v[128:131], v[132:135], v[164:167], v[128:131]
	v_mfma_f32_16x16x32_bf16 v[128:131], v[136:139], v[168:171], v[128:131]
	v_mfma_f32_16x16x32_bf16 v[124:127], v[144:147], v[168:171], v[124:127]
	v_mfma_f32_16x16x32_bf16 v[124:127], v[140:143], v[164:167], v[124:127]
	v_mfma_f32_16x16x32_bf16 v[96:99], v[140:143], v[210:213], v[96:99]
	v_mfma_f32_16x16x32_bf16 v[96:99], v[144:147], v[214:217], v[96:99]
	v_mfma_f32_16x16x32_bf16 v[100:103], v[136:139], v[214:217], v[100:103]
	v_mfma_f32_16x16x32_bf16 v[100:103], v[132:135], v[210:213], v[100:103]
	v_mfma_f32_16x16x32_bf16 v[112:115], v[132:135], v[218:221], v[112:115]
	v_mfma_f32_16x16x32_bf16 v[112:115], v[136:139], v[222:225], v[112:115]
	v_mfma_f32_16x16x32_bf16 v[108:111], v[144:147], v[222:225], v[108:111]
	v_mfma_f32_16x16x32_bf16 v[108:111], v[140:143], v[218:221], v[108:111]
	v_mfma_f32_16x16x32_bf16 v[76:79], v[140:143], v[226:229], v[76:79]
	v_mfma_f32_16x16x32_bf16 v[76:79], v[144:147], v[230:233], v[76:79]
	v_mfma_f32_16x16x32_bf16 v[80:83], v[136:139], v[230:233], v[80:83]
	v_mfma_f32_16x16x32_bf16 v[80:83], v[132:135], v[226:229], v[80:83]
	v_mfma_f32_16x16x32_bf16 v[120:123], v[148:151], v[164:167], v[120:123]
	v_mfma_f32_16x16x32_bf16 v[120:123], v[152:155], v[168:171], v[120:123]
	v_mfma_f32_16x16x32_bf16 v[116:119], v[160:163], v[168:171], v[116:119]
	v_mfma_f32_16x16x32_bf16 v[116:119], v[156:159], v[164:167], v[116:119]
	v_mfma_f32_16x16x32_bf16 v[88:91], v[156:159], v[210:213], v[88:91]
	v_mfma_f32_16x16x32_bf16 v[88:91], v[160:163], v[214:217], v[88:91]
	v_mfma_f32_16x16x32_bf16 v[92:95], v[152:155], v[214:217], v[92:95]
	v_mfma_f32_16x16x32_bf16 v[92:95], v[148:151], v[210:213], v[92:95]
	v_mfma_f32_16x16x32_bf16 v[104:107], v[148:151], v[218:221], v[104:107]
	v_mfma_f32_16x16x32_bf16 v[104:107], v[152:155], v[222:225], v[104:107]
	v_mfma_f32_16x16x32_bf16 v[84:87], v[160:163], v[222:225], v[84:87]
	v_mfma_f32_16x16x32_bf16 v[84:87], v[156:159], v[218:221], v[84:87]
	v_mfma_f32_16x16x32_bf16 v[68:71], v[156:159], v[226:229], v[68:71]
	v_mfma_f32_16x16x32_bf16 v[68:71], v[160:163], v[230:233], v[68:71]
	v_mfma_f32_16x16x32_bf16 v[72:75], v[152:155], v[230:233], v[72:75]
	v_mfma_f32_16x16x32_bf16 v[72:75], v[148:151], v[226:229], v[72:75]
	s_setprio 0
	s_barrier
	s_mov_b32 m0, s73
	v_lshl_add_u64 v[234:235], s[28:29], 0, v[174:175]
	s_add_u32 s82, s28, 0x2b0000
	ds_read_b128 v[164:167], v207 offset:16384
	ds_read_b128 v[168:171], v207 offset:17408
	ds_read_b128 v[210:213], v207 offset:18432
	ds_read_b128 v[214:217], v207 offset:19456
	ds_read_b128 v[218:221], v207 offset:20480
	ds_read_b128 v[222:225], v207 offset:21504
	ds_read_b128 v[226:229], v207 offset:22528
	ds_read_b128 v[230:233], v207 offset:23552
	global_load_lds_dwordx4 v[234:235], off
	v_lshl_add_u64 v[236:237], s[28:29], 0, v[178:179]
	s_mov_b32 m0, s74
	s_addc_u32 s83, s29, 0
	global_load_lds_dwordx4 v[236:237], off
	v_lshl_add_u64 v[238:239], s[82:83], 0, v[174:175]
	s_mov_b32 m0, s75
	v_lshl_add_u64 v[240:241], s[30:31], 0, v[176:177]
	global_load_lds_dwordx4 v[238:239], off
	v_lshl_add_u64 v[238:239], s[82:83], 0, v[178:179]
	s_mov_b32 m0, s76
	s_nop 0
	global_load_lds_dwordx4 v[238:239], off
	v_lshl_add_u64 v[238:239], s[30:31], 0, v[172:173]
	s_mov_b32 m0, s42
	s_nop 0
	global_load_lds_dwordx4 v[238:239], off
	s_mov_b32 m0, s54
	s_nop 0
	global_load_lds_dwordx4 v[240:241], off
	s_waitcnt vmcnt(8)
	s_waitcnt lgkmcnt(0)
	s_barrier
; #define PG8_STAGE(bufoff, gbase, voff) do { _Pragma("unroll") for (int _i = 0; _i < 2; ++_i) \
;         __builtin_amdgcn_global_load_lds((const unsigned*)((const char*)(gbase) + (voff)[_i]), (PG8_LAS unsigned*)(lds + (bufoff) + ldsw + _i * 8192), 16, 0, 0); } while (0)
; #define PG8_LDA(dst, b, h) do { _Pragma("unroll") for (int m = 0; m < 4; ++m) _Pragma("unroll") for (int k = 0; k < 2; ++k) dst[m][k] = *(const PG8_LAS bf16x8*)(lds + PG8_SA(b, h) + aoff + m * 2048 + k * 1024); } while (0)
; #define PG8_LDB(dst, b, h) do { _Pragma("unroll") for (int n = 0; n < 2; ++n) _Pragma("unroll") for (int k = 0; k < 2; ++k) dst[n][k] = *(const PG8_LAS bf16x8*)(lds + PG8_SB(b, h) + boff + n * 2048 + k * 1024); } while (0)
; #define PG8_MMA(ai, bj, At, Bt) do { __builtin_amdgcn_s_setprio(3); _Pragma("unroll") for (int m = 0; m < 4; ++m) _Pragma("unroll") for (int n = 0; n < 2; ++n) _Pragma("unroll") for (int k = 0; k < 2; ++k) \
;         acc[ai][bj][m][n] = __builtin_amdgcn_mfma_f32_16x16x32_bf16(Bt[n][k], At[m][k], acc[ai][bj][m][n], 0, 0, 0); __builtin_amdgcn_s_setprio(0); } while (0)
; #define PG8_WAIT_V(n) asm volatile("s_waitcnt vmcnt(" #n ")" ::: "memory")
; #define PG8_WAIT_L(n) asm volatile("s_waitcnt lgkmcnt(" #n ")" ::: "memory")
; #define PG8_BAR __builtin_amdgcn_s_barrier()
; #define PG8_SCHED __builtin_amdgcn_sched_barrier(0)
; template <class Epi, class Sched, bool ALIGN_EPI = false, bool SP2 = false>
; __device__ __forceinline__ void gemm_phase(PG8_LAS unsigned char* lds, const Gemm g, const Sched& S, const Epi& E) {
;     ...
;             PG8_WAIT_V(8); PG8_WAIT_L(0); PG8_BAR; PG8_MMA(1, 0, At, B0); PG8_MMA(1, 1, At, B1); PG8_BAR; PG8_SCHED;
;             PG8_LDB(B0, 1, 0); PG8_LDB(B1, 1, 1); PG8_SCHED; PG8_LDA(At, 1, 0); PG8_STAGE(PG8_SA(0, 1), a2 + hstepA, voffA);
;             PG8_WAIT_V(8); PG8_WAIT_L(0); PG8_BAR; PG8_MMA(0, 0, At, B0); PG8_MMA(0, 1, At, B1); PG8_BAR; PG8_SCHED;
	s_setprio 3
	s_waitcnt lgkmcnt(0)
	v_mfma_f32_16x16x32_bf16 v[64:67], v[132:135], v[164:167], v[64:67]
	v_mfma_f32_16x16x32_bf16 v[64:67], v[136:139], v[168:171], v[64:67]
	v_mfma_f32_16x16x32_bf16 v[60:63], v[144:147], v[168:171], v[60:63]
	v_mfma_f32_16x16x32_bf16 v[60:63], v[140:143], v[164:167], v[60:63]
	v_mfma_f32_16x16x32_bf16 v[44:47], v[140:143], v[210:213], v[44:47]
	v_mfma_f32_16x16x32_bf16 v[44:47], v[144:147], v[214:217], v[44:47]
	v_mfma_f32_16x16x32_bf16 v[48:51], v[136:139], v[214:217], v[48:51]
	v_mfma_f32_16x16x32_bf16 v[48:51], v[132:135], v[210:213], v[48:51]
	v_mfma_f32_16x16x32_bf16 v[32:35], v[132:135], v[218:221], v[32:35]
	v_mfma_f32_16x16x32_bf16 v[32:35], v[136:139], v[222:225], v[32:35]
	v_mfma_f32_16x16x32_bf16 v[28:31], v[144:147], v[222:225], v[28:31]
	v_mfma_f32_16x16x32_bf16 v[28:31], v[140:143], v[218:221], v[28:31]
	v_mfma_f32_16x16x32_bf16 v[12:15], v[140:143], v[226:229], v[12:15]
	v_mfma_f32_16x16x32_bf16 v[12:15], v[144:147], v[230:233], v[12:15]
	v_mfma_f32_16x16x32_bf16 v[16:19], v[136:139], v[230:233], v[16:19]
	v_mfma_f32_16x16x32_bf16 v[16:19], v[132:135], v[226:229], v[16:19]
	v_mfma_f32_16x16x32_bf16 v[56:59], v[148:151], v[164:167], v[56:59]
	v_mfma_f32_16x16x32_bf16 v[56:59], v[152:155], v[168:171], v[56:59]
	v_mfma_f32_16x16x32_bf16 v[52:55], v[160:163], v[168:171], v[52:55]
	v_mfma_f32_16x16x32_bf16 v[52:55], v[156:159], v[164:167], v[52:55]
	v_mfma_f32_16x16x32_bf16 v[36:39], v[156:159], v[210:213], v[36:39]
	v_mfma_f32_16x16x32_bf16 v[36:39], v[160:163], v[214:217], v[36:39]
	v_mfma_f32_16x16x32_bf16 v[40:43], v[152:155], v[214:217], v[40:43]
	v_mfma_f32_16x16x32_bf16 v[40:43], v[148:151], v[210:213], v[40:43]
	v_mfma_f32_16x16x32_bf16 v[24:27], v[148:151], v[218:221], v[24:27]
	v_mfma_f32_16x16x32_bf16 v[24:27], v[152:155], v[222:225], v[24:27]
	v_mfma_f32_16x16x32_bf16 v[20:23], v[160:163], v[222:225], v[20:23]
	v_mfma_f32_16x16x32_bf16 v[20:23], v[156:159], v[218:221], v[20:23]
	v_mfma_f32_16x16x32_bf16 v[4:7], v[156:159], v[226:229], v[4:7]
	v_mfma_f32_16x16x32_bf16 v[4:7], v[160:163], v[230:233], v[4:7]
	v_mfma_f32_16x16x32_bf16 v[8:11], v[152:155], v[230:233], v[8:11]
	v_mfma_f32_16x16x32_bf16 v[8:11], v[148:151], v[226:229], v[8:11]
	s_setprio 0
	s_barrier
	v_add_u32_e32 v144, s52, v206
	v_add_u32_e32 v160, s53, v206
	ds_read_b128 v[132:135], v144
	ds_read_b128 v[136:139], v144 offset:1024
	ds_read_b128 v[140:143], v144 offset:2048
	ds_read_b128 v[144:147], v144 offset:3072
	ds_read_b128 v[148:151], v160
	ds_read_b128 v[152:155], v160 offset:1024
	ds_read_b128 v[156:159], v160 offset:2048
	ds_read_b128 v[160:163], v160 offset:3072
	s_add_u32 s30, s30, 0x2b0000
	s_addc_u32 s31, s31, 0
	s_mov_b32 m0, s55
	v_lshl_add_u64 v[242:243], s[30:31], 0, v[172:173]
	ds_read_b128 v[164:167], v207 offset:32768
	ds_read_b128 v[168:171], v207 offset:33792
	ds_read_b128 v[210:213], v207 offset:34816
	ds_read_b128 v[214:217], v207 offset:35840
	ds_read_b128 v[218:221], v207 offset:36864
	ds_read_b128 v[222:225], v207 offset:37888
	ds_read_b128 v[226:229], v207 offset:38912
	ds_read_b128 v[230:233], v207 offset:39936
	global_load_lds_dwordx4 v[242:243], off
	v_lshl_add_u64 v[242:243], s[30:31], 0, v[176:177]
	s_mov_b32 m0, s56
	s_nop 0
	global_load_lds_dwordx4 v[242:243], off
	s_waitcnt vmcnt(8)
	s_waitcnt lgkmcnt(0)
	s_barrier
	s_setprio 3
	s_waitcnt lgkmcnt(0)
	v_mfma_f32_16x16x32_bf16 v[128:131], v[132:135], v[164:167], v[128:131]
	v_mfma_f32_16x16x32_bf16 v[128:131], v[136:139], v[168:171], v[128:131]
	v_mfma_f32_16x16x32_bf16 v[124:127], v[144:147], v[168:171], v[124:127]
	v_mfma_f32_16x16x32_bf16 v[124:127], v[140:143], v[164:167], v[124:127]
	v_mfma_f32_16x16x32_bf16 v[96:99], v[140:143], v[210:213], v[96:99]
	v_mfma_f32_16x16x32_bf16 v[96:99], v[144:147], v[214:217], v[96:99]
	v_mfma_f32_16x16x32_bf16 v[100:103], v[136:139], v[214:217], v[100:103]
	v_mfma_f32_16x16x32_bf16 v[100:103], v[132:135], v[210:213], v[100:103]
	v_mfma_f32_16x16x32_bf16 v[112:115], v[132:135], v[218:221], v[112:115]
	v_mfma_f32_16x16x32_bf16 v[112:115], v[136:139], v[222:225], v[112:115]
	v_mfma_f32_16x16x32_bf16 v[108:111], v[144:147], v[222:225], v[108:111]
	v_mfma_f32_16x16x32_bf16 v[108:111], v[140:143], v[218:221], v[108:111]
	v_mfma_f32_16x16x32_bf16 v[76:79], v[140:143], v[226:229], v[76:79]
	v_mfma_f32_16x16x32_bf16 v[76:79], v[144:147], v[230:233], v[76:79]
	v_mfma_f32_16x16x32_bf16 v[80:83], v[136:139], v[230:233], v[80:83]
	v_mfma_f32_16x16x32_bf16 v[80:83], v[132:135], v[226:229], v[80:83]
	v_mfma_f32_16x16x32_bf16 v[120:123], v[148:151], v[164:167], v[120:123]
	v_mfma_f32_16x16x32_bf16 v[120:123], v[152:155], v[168:171], v[120:123]
	v_mfma_f32_16x16x32_bf16 v[116:119], v[160:163], v[168:171], v[116:119]
	v_mfma_f32_16x16x32_bf16 v[116:119], v[156:159], v[164:167], v[116:119]
	v_mfma_f32_16x16x32_bf16 v[88:91], v[156:159], v[210:213], v[88:91]
	v_mfma_f32_16x16x32_bf16 v[88:91], v[160:163], v[214:217], v[88:91]
	v_mfma_f32_16x16x32_bf16 v[92:95], v[152:155], v[214:217], v[92:95]
	v_mfma_f32_16x16x32_bf16 v[92:95], v[148:151], v[210:213], v[92:95]
	v_mfma_f32_16x16x32_bf16 v[104:107], v[148:151], v[218:221], v[104:107]
	v_mfma_f32_16x16x32_bf16 v[104:107], v[152:155], v[222:225], v[104:107]
	v_mfma_f32_16x16x32_bf16 v[84:87], v[160:163], v[222:225], v[84:87]
	v_mfma_f32_16x16x32_bf16 v[84:87], v[156:159], v[218:221], v[84:87]
	v_mfma_f32_16x16x32_bf16 v[68:71], v[156:159], v[226:229], v[68:71]
	v_mfma_f32_16x16x32_bf16 v[68:71], v[160:163], v[230:233], v[68:71]
	v_mfma_f32_16x16x32_bf16 v[72:75], v[152:155], v[230:233], v[72:75]
	v_mfma_f32_16x16x32_bf16 v[72:75], v[148:151], v[226:229], v[72:75]
	s_setprio 0
	s_barrier
; #define PG8_STAGE(bufoff, gbase, voff) do { _Pragma("unroll") for (int _i = 0; _i < 2; ++_i) \
;         __builtin_amdgcn_global_load_lds((const unsigned*)((const char*)(gbase) + (voff)[_i]), (PG8_LAS unsigned*)(lds + (bufoff) + ldsw + _i * 8192), 16, 0, 0); } while (0)
; #define PG8_LDA(dst, b, h) do { _Pragma("unroll") for (int m = 0; m < 4; ++m) _Pragma("unroll") for (int k = 0; k < 2; ++k) dst[m][k] = *(const PG8_LAS bf16x8*)(lds + PG8_SA(b, h) + aoff + m * 2048 + k * 1024); } while (0)
; #define PG8_MMA(ai, bj, At, Bt) do { __builtin_amdgcn_s_setprio(3); _Pragma("unroll") for (int m = 0; m < 4; ++m) _Pragma("unroll") for (int n = 0; n < 2; ++n) _Pragma("unroll") for (int k = 0; k < 2; ++k) \
;         acc[ai][bj][m][n] = __builtin_amdgcn_mfma_f32_16x16x32_bf16(Bt[n][k], At[m][k], acc[ai][bj][m][n], 0, 0, 0); __builtin_amdgcn_s_setprio(0); } while (0)
; #define PG8_WAIT_V(n) asm volatile("s_waitcnt vmcnt(" #n ")" ::: "memory")
; #define PG8_WAIT_L(n) asm volatile("s_waitcnt lgkmcnt(" #n ")" ::: "memory")
; #define PG8_BAR __builtin_amdgcn_s_barrier()
; #define PG8_SCHED __builtin_amdgcn_sched_barrier(0)
; template <class Epi, class Sched, bool ALIGN_EPI = false, bool SP2 = false>
; __device__ __forceinline__ void gemm_phase(PG8_LAS unsigned char* lds, const Gemm g, const Sched& S, const Epi& E) {
;     ...
;             PG8_LDA(At, 1, 1); PG8_STAGE(PG8_SB(1, 0), b3, voffB); PG8_STAGE(PG8_SB(1, 1), b3 + hstepB, voffB); PG8_STAGE(PG8_SA(1, 0), a3, voffA);
;             PG8_WAIT_V(8); PG8_WAIT_L(0); PG8_BAR; PG8_MMA(1, 0, At, B0); PG8_MMA(1, 1, At, B1); PG8_BAR; PG8_SCHED;
	s_mov_b32 m0, s77
	v_lshl_add_u64 v[234:235], v[234:235], 0, s[4:5]
	s_add_u32 s28, s28, 0x2b0080
	ds_read_b128 v[164:167], v207 offset:49152
	ds_read_b128 v[168:171], v207 offset:50176
	ds_read_b128 v[210:213], v207 offset:51200
	ds_read_b128 v[214:217], v207 offset:52224
	ds_read_b128 v[218:221], v207 offset:53248
	ds_read_b128 v[222:225], v207 offset:54272
	ds_read_b128 v[226:229], v207 offset:55296
	ds_read_b128 v[230:233], v207 offset:56320
	global_load_lds_dwordx4 v[234:235], off
	v_lshl_add_u64 v[234:235], v[236:237], 0, s[4:5]
	s_mov_b32 m0, s78
	s_addc_u32 s29, s29, 0
	global_load_lds_dwordx4 v[234:235], off
	v_lshl_add_u64 v[234:235], s[28:29], 0, v[174:175]
	s_mov_b32 m0, s79
	s_nop 0
	global_load_lds_dwordx4 v[234:235], off
	v_lshl_add_u64 v[234:235], s[28:29], 0, v[178:179]
	s_mov_b32 m0, s80
	s_nop 0
	global_load_lds_dwordx4 v[234:235], off
	v_lshl_add_u64 v[234:235], v[238:239], 0, s[4:5]
	s_mov_b32 m0, s57
	s_nop 0
	global_load_lds_dwordx4 v[234:235], off
	v_lshl_add_u64 v[234:235], v[240:241], 0, s[4:5]
	s_mov_b32 m0, s58
	s_nop 0
	global_load_lds_dwordx4 v[234:235], off
	s_waitcnt vmcnt(8)
	s_waitcnt lgkmcnt(0)
	s_barrier
	s_setprio 3
	s_waitcnt lgkmcnt(0)
	v_mfma_f32_16x16x32_bf16 v[64:67], v[132:135], v[164:167], v[64:67]
	v_mfma_f32_16x16x32_bf16 v[64:67], v[136:139], v[168:171], v[64:67]
	v_mfma_f32_16x16x32_bf16 v[60:63], v[144:147], v[168:171], v[60:63]
	v_mfma_f32_16x16x32_bf16 v[60:63], v[140:143], v[164:167], v[60:63]
	v_mfma_f32_16x16x32_bf16 v[44:47], v[140:143], v[210:213], v[44:47]
	v_mfma_f32_16x16x32_bf16 v[44:47], v[144:147], v[214:217], v[44:47]
	v_mfma_f32_16x16x32_bf16 v[48:51], v[136:139], v[214:217], v[48:51]
	v_mfma_f32_16x16x32_bf16 v[48:51], v[132:135], v[210:213], v[48:51]
	v_mfma_f32_16x16x32_bf16 v[32:35], v[132:135], v[218:221], v[32:35]
	v_mfma_f32_16x16x32_bf16 v[32:35], v[136:139], v[222:225], v[32:35]
	v_mfma_f32_16x16x32_bf16 v[28:31], v[144:147], v[222:225], v[28:31]
	v_mfma_f32_16x16x32_bf16 v[28:31], v[140:143], v[218:221], v[28:31]
	v_mfma_f32_16x16x32_bf16 v[12:15], v[140:143], v[226:229], v[12:15]
	v_mfma_f32_16x16x32_bf16 v[12:15], v[144:147], v[230:233], v[12:15]
	v_mfma_f32_16x16x32_bf16 v[16:19], v[136:139], v[230:233], v[16:19]
	v_mfma_f32_16x16x32_bf16 v[16:19], v[132:135], v[226:229], v[16:19]
	v_mfma_f32_16x16x32_bf16 v[56:59], v[148:151], v[164:167], v[56:59]
	v_mfma_f32_16x16x32_bf16 v[56:59], v[152:155], v[168:171], v[56:59]
	v_mfma_f32_16x16x32_bf16 v[52:55], v[160:163], v[168:171], v[52:55]
	v_mfma_f32_16x16x32_bf16 v[52:55], v[156:159], v[164:167], v[52:55]
	v_mfma_f32_16x16x32_bf16 v[36:39], v[156:159], v[210:213], v[36:39]
	v_mfma_f32_16x16x32_bf16 v[36:39], v[160:163], v[214:217], v[36:39]
	v_mfma_f32_16x16x32_bf16 v[40:43], v[152:155], v[214:217], v[40:43]
	v_mfma_f32_16x16x32_bf16 v[40:43], v[148:151], v[210:213], v[40:43]
	v_mfma_f32_16x16x32_bf16 v[24:27], v[148:151], v[218:221], v[24:27]
	v_mfma_f32_16x16x32_bf16 v[24:27], v[152:155], v[222:225], v[24:27]
	v_mfma_f32_16x16x32_bf16 v[20:23], v[160:163], v[222:225], v[20:23]
	v_mfma_f32_16x16x32_bf16 v[20:23], v[156:159], v[218:221], v[20:23]
	v_mfma_f32_16x16x32_bf16 v[4:7], v[156:159], v[226:229], v[4:7]
	v_mfma_f32_16x16x32_bf16 v[4:7], v[160:163], v[230:233], v[4:7]
	v_mfma_f32_16x16x32_bf16 v[8:11], v[152:155], v[230:233], v[8:11]
	v_mfma_f32_16x16x32_bf16 v[8:11], v[148:151], v[226:229], v[8:11]
	s_setprio 0
	s_barrier
	s_add_i32 s61, s61, 2
	s_add_u32 s12, s12, 0x100
	s_addc_u32 s13, s13, 0
	s_cmpk_gt_u32 s61, 0xa9
	s_cbranch_scc1 .LBB0_978

; #define PG8_STAGE(bufoff, gbase, voff) do { _Pragma("unroll") for (int _i = 0; _i < 2; ++_i) \
;         __builtin_amdgcn_global_load_lds((const unsigned*)((const char*)(gbase) + (voff)[_i]), (PG8_LAS unsigned*)(lds + (bufoff) + ldsw + _i * 8192), 16, 0, 0); } while (0)
; #define PG8_LDA(dst, b, h) do { _Pragma("unroll") for (int m = 0; m < 4; ++m) _Pragma("unroll") for (int k = 0; k < 2; ++k) dst[m][k] = *(const PG8_LAS bf16x8*)(lds + PG8_SA(b, h) + aoff + m * 2048 + k * 1024); } while (0)
; #define PG8_LDB(dst, b, h) do { _Pragma("unroll") for (int n = 0; n < 2; ++n) _Pragma("unroll") for (int k = 0; k < 2; ++k) dst[n][k] = *(const PG8_LAS bf16x8*)(lds + PG8_SB(b, h) + boff + n * 2048 + k * 1024); } while (0)
; #define PG8_MMA(ai, bj, At, Bt) do { __builtin_amdgcn_s_setprio(3); _Pragma("unroll") for (int m = 0; m < 4; ++m) _Pragma("unroll") for (int n = 0; n < 2; ++n) _Pragma("unroll") for (int k = 0; k < 2; ++k) \
;         acc[ai][bj][m][n] = __builtin_amdgcn_mfma_f32_16x16x32_bf16(Bt[n][k], At[m][k], acc[ai][bj][m][n], 0, 0, 0); __builtin_amdgcn_s_setprio(0); } while (0)
; #define PG8_WAIT_V(n) asm volatile("s_waitcnt vmcnt(" #n ")" ::: "memory")
; template <class Epi, class Sched, bool ALIGN_EPI = false, bool SP2 = false>
; __device__ __forceinline__ void gemm_phase(PG8_LAS unsigned char* lds, const Gemm g, const Sched& S, const Epi& E) {
;     ...
;             const bool last = (t == nt - 2);
;             const char* a1 = cA + (size_t)(t + 1) * kstep;
;             const char* a2 = last ? nA : cA + (size_t)(t + 2) * kstep; const char* b2 = last ? nB : cB + (size_t)(t + 2) * kstep;
;             const char* a3 = a2 + kstep; const char* b3 = b2 + kstep;
;             if (last && has_next) S.a_ready(nxt);
;             if constexpr (Epi::MIDK) { if (t == E.midk_step(nt)) E.midk(acc, cur, wr, wc, fr, fq); }
;             if constexpr (SP2) {
;             PG8_LDB(B0, 0, 0); PG8_LDB(B1, 0, 1); PG8_SCHED; PG8_LDA(At, 0, 0); PG8_STAGE(PG8_SA(1, 1), a1 + hstepA, voffA);
;             PG8_WAIT_V(8); PG8_WAIT_L(0); PG8_BAR; PG8_MMA(0, 0, At, B0); PG8_MMA(0, 1, At, B1); PG8_BAR; PG8_SCHED;
;             PG8_LDA(At, 0, 1); PG8_STAGE(PG8_SB(0, 0), b2, voffB); PG8_STAGE(PG8_SB(0, 1), b2 + hstepB, voffB); PG8_STAGE(PG8_SA(0, 0), a2, voffA);
;             PG8_WAIT_V(8); PG8_WAIT_L(0); PG8_BAR; PG8_MMA(1, 0, At, B0); PG8_MMA(1, 1, At, B1); PG8_BAR; PG8_SCHED;
.LBB0_1018:
	v_add_u32_e32 v142, s46, v189
	v_add_u32_e32 v158, s47, v189
	s_add_u32 s40, s20, s22
	ds_read_b128 v[130:133], v142
	ds_read_b128 v[134:137], v142 offset:1024
	ds_read_b128 v[138:141], v142 offset:2048
	ds_read_b128 v[142:145], v142 offset:3072
	ds_read_b128 v[146:149], v158
	ds_read_b128 v[150:153], v158 offset:1024
	ds_read_b128 v[154:157], v158 offset:2048
	ds_read_b128 v[158:161], v158 offset:3072
	s_addc_u32 s41, s21, s23
	s_add_u32 s40, s40, 0x21500100
	s_addc_u32 s41, s41, 0
	s_add_u32 s87, s44, s22
	s_addc_u32 s88, s45, s23
	s_cmpk_eq_i32 s22, 0x5500
	s_cselect_b32 s43, s17, s41
	s_cselect_b32 s42, s16, s40
	s_cselect_b32 s41, s11, s88
	s_cselect_b32 s40, s10, s87
	s_mov_b32 m0, s77
	v_lshl_add_u64 v[186:187], v[0:1], 0, s[22:23]
	ds_read_b128 v[162:165], v180
	ds_read_b128 v[166:169], v180 offset:1024
	ds_read_b128 v[182:185], v180 offset:2048
	ds_read_b128 v[190:193], v180 offset:3072
	ds_read_b128 v[194:197], v180 offset:4096
	ds_read_b128 v[208:211], v180 offset:5120
	ds_read_b128 v[212:215], v180 offset:6144
	ds_read_b128 v[216:219], v180 offset:7168
	global_load_lds_dwordx4 v[186:187], off
	v_lshl_add_u64 v[186:187], v[170:171], 0, s[22:23]
	s_mov_b32 m0, s78
	s_nop 0
	global_load_lds_dwordx4 v[186:187], off
	s_waitcnt vmcnt(8)
	s_waitcnt lgkmcnt(0)
	s_barrier
	s_setprio 3
	s_waitcnt lgkmcnt(0)
	v_mfma_f32_16x16x32_bf16 v[126:129], v[130:133], v[162:165], v[126:129]
	v_mfma_f32_16x16x32_bf16 v[126:129], v[134:137], v[166:169], v[126:129]
	v_mfma_f32_16x16x32_bf16 v[122:125], v[142:145], v[166:169], v[122:125]
	v_mfma_f32_16x16x32_bf16 v[122:125], v[138:141], v[162:165], v[122:125]
	v_mfma_f32_16x16x32_bf16 v[94:97], v[138:141], v[182:185], v[94:97]
	v_mfma_f32_16x16x32_bf16 v[94:97], v[142:145], v[190:193], v[94:97]
	v_mfma_f32_16x16x32_bf16 v[98:101], v[134:137], v[190:193], v[98:101]
	v_mfma_f32_16x16x32_bf16 v[98:101], v[130:133], v[182:185], v[98:101]
	v_mfma_f32_16x16x32_bf16 v[110:113], v[130:133], v[194:197], v[110:113]
	v_mfma_f32_16x16x32_bf16 v[110:113], v[134:137], v[208:211], v[110:113]
	v_mfma_f32_16x16x32_bf16 v[106:109], v[142:145], v[208:211], v[106:109]
	v_mfma_f32_16x16x32_bf16 v[106:109], v[138:141], v[194:197], v[106:109]
	v_mfma_f32_16x16x32_bf16 v[74:77], v[138:141], v[212:215], v[74:77]
	v_mfma_f32_16x16x32_bf16 v[74:77], v[142:145], v[216:219], v[74:77]
	v_mfma_f32_16x16x32_bf16 v[78:81], v[134:137], v[216:219], v[78:81]
	v_mfma_f32_16x16x32_bf16 v[78:81], v[130:133], v[212:215], v[78:81]
	v_mfma_f32_16x16x32_bf16 v[118:121], v[146:149], v[162:165], v[118:121]
	v_mfma_f32_16x16x32_bf16 v[118:121], v[150:153], v[166:169], v[118:121]
	v_mfma_f32_16x16x32_bf16 v[114:117], v[158:161], v[166:169], v[114:117]
	v_mfma_f32_16x16x32_bf16 v[114:117], v[154:157], v[162:165], v[114:117]
	v_mfma_f32_16x16x32_bf16 v[86:89], v[154:157], v[182:185], v[86:89]
	v_mfma_f32_16x16x32_bf16 v[86:89], v[158:161], v[190:193], v[86:89]
	v_mfma_f32_16x16x32_bf16 v[90:93], v[150:153], v[190:193], v[90:93]
	v_mfma_f32_16x16x32_bf16 v[90:93], v[146:149], v[182:185], v[90:93]
	v_mfma_f32_16x16x32_bf16 v[102:105], v[146:149], v[194:197], v[102:105]
	v_mfma_f32_16x16x32_bf16 v[102:105], v[150:153], v[208:211], v[102:105]
	v_mfma_f32_16x16x32_bf16 v[82:85], v[158:161], v[208:211], v[82:85]
	v_mfma_f32_16x16x32_bf16 v[82:85], v[154:157], v[194:197], v[82:85]
	v_mfma_f32_16x16x32_bf16 v[66:69], v[154:157], v[212:215], v[66:69]
	v_mfma_f32_16x16x32_bf16 v[66:69], v[158:161], v[216:219], v[66:69]
	v_mfma_f32_16x16x32_bf16 v[70:73], v[150:153], v[216:219], v[70:73]
	v_mfma_f32_16x16x32_bf16 v[70:73], v[146:149], v[212:215], v[70:73]
	s_setprio 0
	s_barrier
	s_mov_b32 m0, s79
	v_lshl_add_u64 v[186:187], s[40:41], 0, v[174:175]
	s_add_u32 s88, s40, 0x2b0000
	ds_read_b128 v[162:165], v180 offset:16384
	ds_read_b128 v[166:169], v180 offset:17408
	ds_read_b128 v[182:185], v180 offset:18432
	ds_read_b128 v[190:193], v180 offset:19456
	ds_read_b128 v[194:197], v180 offset:20480
	ds_read_b128 v[208:211], v180 offset:21504
	ds_read_b128 v[212:215], v180 offset:22528
	ds_read_b128 v[216:219], v180 offset:23552
	global_load_lds_dwordx4 v[186:187], off
	v_lshl_add_u64 v[198:199], s[40:41], 0, v[178:179]
	s_mov_b32 m0, s80
	s_addc_u32 s89, s41, 0
	global_load_lds_dwordx4 v[198:199], off
	v_lshl_add_u64 v[204:205], s[88:89], 0, v[174:175]
	s_mov_b32 m0, s81
	v_lshl_add_u64 v[220:221], s[42:43], 0, v[176:177]
	global_load_lds_dwordx4 v[204:205], off
	v_lshl_add_u64 v[204:205], s[88:89], 0, v[178:179]
	s_mov_b32 m0, s82
	s_nop 0
	global_load_lds_dwordx4 v[204:205], off
	v_lshl_add_u64 v[204:205], s[42:43], 0, v[172:173]
	s_mov_b32 m0, s58
	s_nop 0
	global_load_lds_dwordx4 v[204:205], off
	s_mov_b32 m0, s60
	s_nop 0
	global_load_lds_dwordx4 v[220:221], off
	s_waitcnt vmcnt(8)
	s_waitcnt lgkmcnt(0)
	s_barrier
; #define PG8_STAGE(bufoff, gbase, voff) do { _Pragma("unroll") for (int _i = 0; _i < 2; ++_i) \
;         __builtin_amdgcn_global_load_lds((const unsigned*)((const char*)(gbase) + (voff)[_i]), (PG8_LAS unsigned*)(lds + (bufoff) + ldsw + _i * 8192), 16, 0, 0); } while (0)
; #define PG8_LDA(dst, b, h) do { _Pragma("unroll") for (int m = 0; m < 4; ++m) _Pragma("unroll") for (int k = 0; k < 2; ++k) dst[m][k] = *(const PG8_LAS bf16x8*)(lds + PG8_SA(b, h) + aoff + m * 2048 + k * 1024); } while (0)
; #define PG8_LDB(dst, b, h) do { _Pragma("unroll") for (int n = 0; n < 2; ++n) _Pragma("unroll") for (int k = 0; k < 2; ++k) dst[n][k] = *(const PG8_LAS bf16x8*)(lds + PG8_SB(b, h) + boff + n * 2048 + k * 1024); } while (0)
; #define PG8_MMA(ai, bj, At, Bt) do { __builtin_amdgcn_s_setprio(3); _Pragma("unroll") for (int m = 0; m < 4; ++m) _Pragma("unroll") for (int n = 0; n < 2; ++n) _Pragma("unroll") for (int k = 0; k < 2; ++k) \
;         acc[ai][bj][m][n] = __builtin_amdgcn_mfma_f32_16x16x32_bf16(Bt[n][k], At[m][k], acc[ai][bj][m][n], 0, 0, 0); __builtin_amdgcn_s_setprio(0); } while (0)
; #define PG8_WAIT_V(n) asm volatile("s_waitcnt vmcnt(" #n ")" ::: "memory")
; #define PG8_WAIT_L(n) asm volatile("s_waitcnt lgkmcnt(" #n ")" ::: "memory")
; #define PG8_BAR __builtin_amdgcn_s_barrier()
; #define PG8_SCHED __builtin_amdgcn_sched_barrier(0)
; template <class Epi, class Sched, bool ALIGN_EPI = false, bool SP2 = false>
; __device__ __forceinline__ void gemm_phase(PG8_LAS unsigned char* lds, const Gemm g, const Sched& S, const Epi& E) {
;     ...
;             PG8_WAIT_V(8); PG8_WAIT_L(0); PG8_BAR; PG8_MMA(1, 0, At, B0); PG8_MMA(1, 1, At, B1); PG8_BAR; PG8_SCHED;
;             PG8_LDB(B0, 1, 0); PG8_LDB(B1, 1, 1); PG8_SCHED; PG8_LDA(At, 1, 0); PG8_STAGE(PG8_SA(0, 1), a2 + hstepA, voffA);
;             PG8_WAIT_V(8); PG8_WAIT_L(0); PG8_BAR; PG8_MMA(0, 0, At, B0); PG8_MMA(0, 1, At, B1); PG8_BAR; PG8_SCHED;
	s_setprio 3
	s_waitcnt lgkmcnt(0)
	v_mfma_f32_16x16x32_bf16 v[62:65], v[130:133], v[162:165], v[62:65]
	v_mfma_f32_16x16x32_bf16 v[62:65], v[134:137], v[166:169], v[62:65]
	v_mfma_f32_16x16x32_bf16 v[58:61], v[142:145], v[166:169], v[58:61]
	v_mfma_f32_16x16x32_bf16 v[58:61], v[138:141], v[162:165], v[58:61]
	v_mfma_f32_16x16x32_bf16 v[42:45], v[138:141], v[182:185], v[42:45]
	v_mfma_f32_16x16x32_bf16 v[42:45], v[142:145], v[190:193], v[42:45]
	v_mfma_f32_16x16x32_bf16 v[46:49], v[134:137], v[190:193], v[46:49]
	v_mfma_f32_16x16x32_bf16 v[46:49], v[130:133], v[182:185], v[46:49]
	v_mfma_f32_16x16x32_bf16 v[30:33], v[130:133], v[194:197], v[30:33]
	v_mfma_f32_16x16x32_bf16 v[30:33], v[134:137], v[208:211], v[30:33]
	v_mfma_f32_16x16x32_bf16 v[26:29], v[142:145], v[208:211], v[26:29]
	v_mfma_f32_16x16x32_bf16 v[26:29], v[138:141], v[194:197], v[26:29]
	v_mfma_f32_16x16x32_bf16 v[10:13], v[138:141], v[212:215], v[10:13]
	v_mfma_f32_16x16x32_bf16 v[10:13], v[142:145], v[216:219], v[10:13]
	v_mfma_f32_16x16x32_bf16 v[14:17], v[134:137], v[216:219], v[14:17]
	v_mfma_f32_16x16x32_bf16 v[14:17], v[130:133], v[212:215], v[14:17]
	v_mfma_f32_16x16x32_bf16 v[54:57], v[146:149], v[162:165], v[54:57]
	v_mfma_f32_16x16x32_bf16 v[54:57], v[150:153], v[166:169], v[54:57]
	v_mfma_f32_16x16x32_bf16 v[50:53], v[158:161], v[166:169], v[50:53]
	v_mfma_f32_16x16x32_bf16 v[50:53], v[154:157], v[162:165], v[50:53]
	v_mfma_f32_16x16x32_bf16 v[34:37], v[154:157], v[182:185], v[34:37]
	v_mfma_f32_16x16x32_bf16 v[34:37], v[158:161], v[190:193], v[34:37]
	v_mfma_f32_16x16x32_bf16 v[38:41], v[150:153], v[190:193], v[38:41]
	v_mfma_f32_16x16x32_bf16 v[38:41], v[146:149], v[182:185], v[38:41]
	v_mfma_f32_16x16x32_bf16 v[22:25], v[146:149], v[194:197], v[22:25]
	v_mfma_f32_16x16x32_bf16 v[22:25], v[150:153], v[208:211], v[22:25]
	v_mfma_f32_16x16x32_bf16 v[18:21], v[158:161], v[208:211], v[18:21]
	v_mfma_f32_16x16x32_bf16 v[18:21], v[154:157], v[194:197], v[18:21]
	v_mfma_f32_16x16x32_bf16 v[2:5], v[154:157], v[212:215], v[2:5]
	v_mfma_f32_16x16x32_bf16 v[2:5], v[158:161], v[216:219], v[2:5]
	v_mfma_f32_16x16x32_bf16 v[6:9], v[150:153], v[216:219], v[6:9]
	v_mfma_f32_16x16x32_bf16 v[6:9], v[146:149], v[212:215], v[6:9]
	s_setprio 0
	s_barrier
	v_add_u32_e32 v142, s52, v189
	v_add_u32_e32 v158, s53, v189
	ds_read_b128 v[130:133], v142
	ds_read_b128 v[134:137], v142 offset:1024
	ds_read_b128 v[138:141], v142 offset:2048
	ds_read_b128 v[142:145], v142 offset:3072
	ds_read_b128 v[146:149], v158
	ds_read_b128 v[150:153], v158 offset:1024
	ds_read_b128 v[154:157], v158 offset:2048
	ds_read_b128 v[158:161], v158 offset:3072
	s_add_u32 s42, s42, 0x2b0000
	s_addc_u32 s43, s43, 0
	s_mov_b32 m0, s61
	v_lshl_add_u64 v[222:223], s[42:43], 0, v[172:173]
	ds_read_b128 v[162:165], v180 offset:32768
	ds_read_b128 v[166:169], v180 offset:33792
	ds_read_b128 v[182:185], v180 offset:34816
	ds_read_b128 v[190:193], v180 offset:35840
	ds_read_b128 v[194:197], v180 offset:36864
	ds_read_b128 v[208:211], v180 offset:37888
	ds_read_b128 v[212:215], v180 offset:38912
	ds_read_b128 v[216:219], v180 offset:39936
	global_load_lds_dwordx4 v[222:223], off
	v_lshl_add_u64 v[222:223], s[42:43], 0, v[176:177]
	s_mov_b32 m0, s62
	s_nop 0
	global_load_lds_dwordx4 v[222:223], off
	s_waitcnt vmcnt(8)
	s_waitcnt lgkmcnt(0)
	s_barrier
	s_setprio 3
	s_waitcnt lgkmcnt(0)
	v_mfma_f32_16x16x32_bf16 v[126:129], v[130:133], v[162:165], v[126:129]
	v_mfma_f32_16x16x32_bf16 v[126:129], v[134:137], v[166:169], v[126:129]
	v_mfma_f32_16x16x32_bf16 v[122:125], v[142:145], v[166:169], v[122:125]
	v_mfma_f32_16x16x32_bf16 v[122:125], v[138:141], v[162:165], v[122:125]
	v_mfma_f32_16x16x32_bf16 v[94:97], v[138:141], v[182:185], v[94:97]
	v_mfma_f32_16x16x32_bf16 v[94:97], v[142:145], v[190:193], v[94:97]
	v_mfma_f32_16x16x32_bf16 v[98:101], v[134:137], v[190:193], v[98:101]
	v_mfma_f32_16x16x32_bf16 v[98:101], v[130:133], v[182:185], v[98:101]
	v_mfma_f32_16x16x32_bf16 v[110:113], v[130:133], v[194:197], v[110:113]
	v_mfma_f32_16x16x32_bf16 v[110:113], v[134:137], v[208:211], v[110:113]
	v_mfma_f32_16x16x32_bf16 v[106:109], v[142:145], v[208:211], v[106:109]
	v_mfma_f32_16x16x32_bf16 v[106:109], v[138:141], v[194:197], v[106:109]
	v_mfma_f32_16x16x32_bf16 v[74:77], v[138:141], v[212:215], v[74:77]
	v_mfma_f32_16x16x32_bf16 v[74:77], v[142:145], v[216:219], v[74:77]
	v_mfma_f32_16x16x32_bf16 v[78:81], v[134:137], v[216:219], v[78:81]
	v_mfma_f32_16x16x32_bf16 v[78:81], v[130:133], v[212:215], v[78:81]
	v_mfma_f32_16x16x32_bf16 v[118:121], v[146:149], v[162:165], v[118:121]
	v_mfma_f32_16x16x32_bf16 v[118:121], v[150:153], v[166:169], v[118:121]
	v_mfma_f32_16x16x32_bf16 v[114:117], v[158:161], v[166:169], v[114:117]
	v_mfma_f32_16x16x32_bf16 v[114:117], v[154:157], v[162:165], v[114:117]
	v_mfma_f32_16x16x32_bf16 v[86:89], v[154:157], v[182:185], v[86:89]
	v_mfma_f32_16x16x32_bf16 v[86:89], v[158:161], v[190:193], v[86:89]
	v_mfma_f32_16x16x32_bf16 v[90:93], v[150:153], v[190:193], v[90:93]
	v_mfma_f32_16x16x32_bf16 v[90:93], v[146:149], v[182:185], v[90:93]
	v_mfma_f32_16x16x32_bf16 v[102:105], v[146:149], v[194:197], v[102:105]
	v_mfma_f32_16x16x32_bf16 v[102:105], v[150:153], v[208:211], v[102:105]
	v_mfma_f32_16x16x32_bf16 v[82:85], v[158:161], v[208:211], v[82:85]
	v_mfma_f32_16x16x32_bf16 v[82:85], v[154:157], v[194:197], v[82:85]
	v_mfma_f32_16x16x32_bf16 v[66:69], v[154:157], v[212:215], v[66:69]
	v_mfma_f32_16x16x32_bf16 v[66:69], v[158:161], v[216:219], v[66:69]
	v_mfma_f32_16x16x32_bf16 v[70:73], v[150:153], v[216:219], v[70:73]
	v_mfma_f32_16x16x32_bf16 v[70:73], v[146:149], v[212:215], v[70:73]
	s_setprio 0
	s_barrier
; #define PG8_STAGE(bufoff, gbase, voff) do { _Pragma("unroll") for (int _i = 0; _i < 2; ++_i) \
;         __builtin_amdgcn_global_load_lds((const unsigned*)((const char*)(gbase) + (voff)[_i]), (PG8_LAS unsigned*)(lds + (bufoff) + ldsw + _i * 8192), 16, 0, 0); } while (0)
; #define PG8_LDA(dst, b, h) do { _Pragma("unroll") for (int m = 0; m < 4; ++m) _Pragma("unroll") for (int k = 0; k < 2; ++k) dst[m][k] = *(const PG8_LAS bf16x8*)(lds + PG8_SA(b, h) + aoff + m * 2048 + k * 1024); } while (0)
; #define PG8_MMA(ai, bj, At, Bt) do { __builtin_amdgcn_s_setprio(3); _Pragma("unroll") for (int m = 0; m < 4; ++m) _Pragma("unroll") for (int n = 0; n < 2; ++n) _Pragma("unroll") for (int k = 0; k < 2; ++k) \
;         acc[ai][bj][m][n] = __builtin_amdgcn_mfma_f32_16x16x32_bf16(Bt[n][k], At[m][k], acc[ai][bj][m][n], 0, 0, 0); __builtin_amdgcn_s_setprio(0); } while (0)
; #define PG8_WAIT_V(n) asm volatile("s_waitcnt vmcnt(" #n ")" ::: "memory")
; #define PG8_WAIT_L(n) asm volatile("s_waitcnt lgkmcnt(" #n ")" ::: "memory")
; #define PG8_BAR __builtin_amdgcn_s_barrier()
; #define PG8_SCHED __builtin_amdgcn_sched_barrier(0)
; template <class Epi, class Sched, bool ALIGN_EPI = false, bool SP2 = false>
; __device__ __forceinline__ void gemm_phase(PG8_LAS unsigned char* lds, const Gemm g, const Sched& S, const Epi& E) {
;     ...
;             PG8_LDA(At, 1, 1); PG8_STAGE(PG8_SB(1, 0), b3, voffB); PG8_STAGE(PG8_SB(1, 1), b3 + hstepB, voffB); PG8_STAGE(PG8_SA(1, 0), a3, voffA);
;             PG8_WAIT_V(8); PG8_WAIT_L(0); PG8_BAR; PG8_MMA(1, 0, At, B0); PG8_MMA(1, 1, At, B1); PG8_BAR; PG8_SCHED;
	s_mov_b32 m0, s83
	v_lshl_add_u64 v[186:187], v[186:187], 0, s[18:19]
	s_add_u32 s40, s40, 0x2b0080
	ds_read_b128 v[162:165], v180 offset:49152
	ds_read_b128 v[166:169], v180 offset:50176
	ds_read_b128 v[182:185], v180 offset:51200
	ds_read_b128 v[190:193], v180 offset:52224
	ds_read_b128 v[194:197], v180 offset:53248
	ds_read_b128 v[208:211], v180 offset:54272
	ds_read_b128 v[212:215], v180 offset:55296
	ds_read_b128 v[216:219], v180 offset:56320
	global_load_lds_dwordx4 v[186:187], off
	v_lshl_add_u64 v[186:187], v[198:199], 0, s[18:19]
	s_mov_b32 m0, s84
	s_addc_u32 s41, s41, 0
	global_load_lds_dwordx4 v[186:187], off
	v_lshl_add_u64 v[186:187], s[40:41], 0, v[174:175]
	s_mov_b32 m0, s85
	s_nop 0
	global_load_lds_dwordx4 v[186:187], off
	v_lshl_add_u64 v[186:187], s[40:41], 0, v[178:179]
	s_mov_b32 m0, s86
	s_nop 0
	global_load_lds_dwordx4 v[186:187], off
	v_lshl_add_u64 v[186:187], v[204:205], 0, s[18:19]
	s_mov_b32 m0, s63
	s_nop 0
	global_load_lds_dwordx4 v[186:187], off
	v_lshl_add_u64 v[186:187], v[220:221], 0, s[18:19]
	s_mov_b32 m0, s64
	s_nop 0
	global_load_lds_dwordx4 v[186:187], off
	s_waitcnt vmcnt(8)
	s_waitcnt lgkmcnt(0)
	s_barrier
	s_setprio 3
	s_waitcnt lgkmcnt(0)
	v_mfma_f32_16x16x32_bf16 v[62:65], v[130:133], v[162:165], v[62:65]
	v_mfma_f32_16x16x32_bf16 v[62:65], v[134:137], v[166:169], v[62:65]
	v_mfma_f32_16x16x32_bf16 v[58:61], v[142:145], v[166:169], v[58:61]
	v_mfma_f32_16x16x32_bf16 v[58:61], v[138:141], v[162:165], v[58:61]
	v_mfma_f32_16x16x32_bf16 v[42:45], v[138:141], v[182:185], v[42:45]
	v_mfma_f32_16x16x32_bf16 v[42:45], v[142:145], v[190:193], v[42:45]
	v_mfma_f32_16x16x32_bf16 v[46:49], v[134:137], v[190:193], v[46:49]
	v_mfma_f32_16x16x32_bf16 v[46:49], v[130:133], v[182:185], v[46:49]
	v_mfma_f32_16x16x32_bf16 v[30:33], v[130:133], v[194:197], v[30:33]
	v_mfma_f32_16x16x32_bf16 v[30:33], v[134:137], v[208:211], v[30:33]
	v_mfma_f32_16x16x32_bf16 v[26:29], v[142:145], v[208:211], v[26:29]
	v_mfma_f32_16x16x32_bf16 v[26:29], v[138:141], v[194:197], v[26:29]
	v_mfma_f32_16x16x32_bf16 v[10:13], v[138:141], v[212:215], v[10:13]
	v_mfma_f32_16x16x32_bf16 v[10:13], v[142:145], v[216:219], v[10:13]
	v_mfma_f32_16x16x32_bf16 v[14:17], v[134:137], v[216:219], v[14:17]
	v_mfma_f32_16x16x32_bf16 v[14:17], v[130:133], v[212:215], v[14:17]
	v_mfma_f32_16x16x32_bf16 v[54:57], v[146:149], v[162:165], v[54:57]
	v_mfma_f32_16x16x32_bf16 v[54:57], v[150:153], v[166:169], v[54:57]
	v_mfma_f32_16x16x32_bf16 v[50:53], v[158:161], v[166:169], v[50:53]
	v_mfma_f32_16x16x32_bf16 v[50:53], v[154:157], v[162:165], v[50:53]
	v_mfma_f32_16x16x32_bf16 v[34:37], v[154:157], v[182:185], v[34:37]
	v_mfma_f32_16x16x32_bf16 v[34:37], v[158:161], v[190:193], v[34:37]
	v_mfma_f32_16x16x32_bf16 v[38:41], v[150:153], v[190:193], v[38:41]
	v_mfma_f32_16x16x32_bf16 v[38:41], v[146:149], v[182:185], v[38:41]
	v_mfma_f32_16x16x32_bf16 v[22:25], v[146:149], v[194:197], v[22:25]
	v_mfma_f32_16x16x32_bf16 v[22:25], v[150:153], v[208:211], v[22:25]
	v_mfma_f32_16x16x32_bf16 v[18:21], v[158:161], v[208:211], v[18:21]
	v_mfma_f32_16x16x32_bf16 v[18:21], v[154:157], v[194:197], v[18:21]
	v_mfma_f32_16x16x32_bf16 v[2:5], v[154:157], v[212:215], v[2:5]
	v_mfma_f32_16x16x32_bf16 v[2:5], v[158:161], v[216:219], v[2:5]
	v_mfma_f32_16x16x32_bf16 v[6:9], v[150:153], v[216:219], v[6:9]
	v_mfma_f32_16x16x32_bf16 v[6:9], v[146:149], v[212:215], v[6:9]
	s_setprio 0
	s_barrier
	s_add_i32 s67, s67, 2
	s_add_u32 s22, s22, 0x100
	s_addc_u32 s23, s23, 0
	s_cmpk_gt_u32 s67, 0xa9
	s_cbranch_scc1 .LBB0_1021
